# GEMM epilogues: hoist per-row-group ss loads (P1,P5,P8) and prefetch residual loads 4-8 row groups ahead with counted vmcnt (P4,P7,P9)
# speedup vs baseline: 1.0119x; 1.0119x over previous
.LBB0_298:
	v_lshl_add_u32 v150, s0, 8, v152
	v_ashrrev_i32_e32 v151, 31, v150
	v_lshl_add_u64 v[146:147], v[150:151], 2, s[12:13]
	global_load_dword v159, v[146:147], off
	global_load_dword v200, v[146:147], off offset:64
	global_load_dword v201, v[146:147], off offset:128
	global_load_dword v202, v[146:147], off offset:192
	global_load_dword v203, v[146:147], off offset:512
	global_load_dword v204, v[146:147], off offset:576
	global_load_dword v205, v[146:147], off offset:640
	global_load_dword v206, v[146:147], off offset:704
	v_lshl_or_b32 v148, s1, 8, v154
	v_ashrrev_i32_e32 v149, 31, v148
	v_lshlrev_b64 v[164:165], 1, v[148:149]
	v_lshlrev_b64 v[162:163], 13, v[150:151]
	v_or_b32_e32 v160, 16, v150
	v_ashrrev_i32_e32 v161, 31, v160
	s_mov_b64 s[0:1], 0x100000
	s_mov_b32 s19, 0x100000
	s_waitcnt vmcnt(0)
	v_fmamk_f32 v148, v159, 0x3a800000, v158
	v_mul_f32_e32 v149, 0x4b800000, v148
	v_cmp_gt_f32_e32 vcc, s87, v148
	s_nop 1
	v_cndmask_b32_e32 v148, v148, v149, vcc
	v_rsq_f32_e32 v151, v148
	v_lshl_add_u64 v[148:149], s[8:9], 0, v[162:163]
	v_lshl_add_u64 v[148:149], v[148:149], 0, v[164:165]
	v_lshl_add_u64 v[162:163], v[160:161], 2, s[12:13]
	v_mul_f32_e32 v159, 0x45800000, v151
	v_cndmask_b32_e32 v166, v151, v159, vcc
	v_pk_mul_f32 v[126:127], v[126:127], v[166:167] op_sel_hi:[1,0]
	v_pk_mul_f32 v[124:125], v[124:125], v[166:167] op_sel_hi:[1,0]
	v_pk_mul_f32 v[122:123], v[122:123], v[166:167] op_sel_hi:[1,0]
	v_pk_mul_f32 v[120:121], v[120:121], v[166:167] op_sel_hi:[1,0]
	v_pk_mul_f32 v[118:119], v[118:119], v[166:167] op_sel_hi:[1,0]
	v_pk_mul_f32 v[116:117], v[116:117], v[166:167] op_sel_hi:[1,0]
	v_pk_mul_f32 v[168:169], v[114:115], v[166:167] op_sel_hi:[1,0]
	v_pk_mul_f32 v[166:167], v[112:113], v[166:167] op_sel_hi:[1,0]
	v_cvt_pk_bf16_f32 v112, v124, v125
	v_cvt_pk_bf16_f32 v113, v126, v127
	v_cvt_pk_bf16_f32 v114, v120, v121
	v_cvt_pk_bf16_f32 v115, v122, v123
	global_store_dwordx4 v[148:149], v[112:115], off
	s_nop 1
	v_cvt_pk_bf16_f32 v112, v116, v117
	v_cvt_pk_bf16_f32 v113, v118, v119
	v_cvt_pk_bf16_f32 v114, v166, v167
	v_cvt_pk_bf16_f32 v115, v168, v169
	global_store_dwordx4 v[148:149], v[112:115], off offset:256
	s_nop 0
	s_nop 0
	v_fmamk_f32 v116, v200, 0x3a800000, v158
	v_mul_f32_e32 v117, 0x4b800000, v116
	v_cmp_gt_f32_e32 vcc, s87, v116
	v_lshlrev_b64 v[114:115], 13, v[160:161]
	v_or_b32_e32 v112, 32, v150
	v_cndmask_b32_e32 v116, v116, v117, vcc
	v_rsq_f32_e32 v118, v116
	v_lshl_add_u64 v[114:115], s[8:9], 0, v[114:115]
	v_ashrrev_i32_e32 v113, 31, v112
	v_lshl_add_u64 v[114:115], v[114:115], 0, v[164:165]
	v_mul_f32_e32 v119, 0x45800000, v118
	v_cndmask_b32_e32 v118, v118, v119, vcc
	v_pk_mul_f32 v[110:111], v[110:111], v[118:119] op_sel_hi:[1,0]
	v_pk_mul_f32 v[108:109], v[108:109], v[118:119] op_sel_hi:[1,0]
	v_pk_mul_f32 v[106:107], v[106:107], v[118:119] op_sel_hi:[1,0]
	v_pk_mul_f32 v[104:105], v[104:105], v[118:119] op_sel_hi:[1,0]
	v_pk_mul_f32 v[102:103], v[102:103], v[118:119] op_sel_hi:[1,0]
	v_pk_mul_f32 v[100:101], v[100:101], v[118:119] op_sel_hi:[1,0]
	v_pk_mul_f32 v[120:121], v[98:99], v[118:119] op_sel_hi:[1,0]
	v_pk_mul_f32 v[118:119], v[96:97], v[118:119] op_sel_hi:[1,0]
	v_cvt_pk_bf16_f32 v96, v108, v109
	v_cvt_pk_bf16_f32 v97, v110, v111
	v_cvt_pk_bf16_f32 v98, v104, v105
	v_cvt_pk_bf16_f32 v99, v106, v107
	v_lshl_add_u64 v[116:117], v[112:113], 2, s[12:13]
	global_store_dwordx4 v[114:115], v[96:99], off
	s_nop 1
	v_cvt_pk_bf16_f32 v96, v100, v101
	v_cvt_pk_bf16_f32 v97, v102, v103
	v_cvt_pk_bf16_f32 v98, v118, v119
	v_cvt_pk_bf16_f32 v99, v120, v121
	global_store_dwordx4 v[114:115], v[96:99], off offset:256
	s_nop 0
	s_nop 0
	v_fmamk_f32 v100, v201, 0x3a800000, v158
	v_mul_f32_e32 v101, 0x4b800000, v100
	v_cmp_gt_f32_e32 vcc, s87, v100
	v_lshlrev_b64 v[98:99], 13, v[112:113]
	v_or_b32_e32 v96, 48, v150
	v_cndmask_b32_e32 v100, v100, v101, vcc
	v_rsq_f32_e32 v102, v100
	v_lshl_add_u64 v[98:99], s[8:9], 0, v[98:99]
	v_ashrrev_i32_e32 v97, 31, v96
	v_lshl_add_u64 v[98:99], v[98:99], 0, v[164:165]
	v_mul_f32_e32 v103, 0x45800000, v102
	v_cndmask_b32_e32 v102, v102, v103, vcc
	v_pk_mul_f32 v[94:95], v[94:95], v[102:103] op_sel_hi:[1,0]
	v_pk_mul_f32 v[92:93], v[92:93], v[102:103] op_sel_hi:[1,0]
	v_pk_mul_f32 v[90:91], v[90:91], v[102:103] op_sel_hi:[1,0]
	v_pk_mul_f32 v[88:89], v[88:89], v[102:103] op_sel_hi:[1,0]
	v_pk_mul_f32 v[86:87], v[86:87], v[102:103] op_sel_hi:[1,0]
	v_pk_mul_f32 v[84:85], v[84:85], v[102:103] op_sel_hi:[1,0]
	v_pk_mul_f32 v[104:105], v[82:83], v[102:103] op_sel_hi:[1,0]
	v_pk_mul_f32 v[102:103], v[80:81], v[102:103] op_sel_hi:[1,0]
	v_cvt_pk_bf16_f32 v80, v92, v93
	v_cvt_pk_bf16_f32 v81, v94, v95
	v_cvt_pk_bf16_f32 v82, v88, v89
	v_cvt_pk_bf16_f32 v83, v90, v91
	v_lshl_add_u64 v[100:101], v[96:97], 2, s[12:13]
	global_store_dwordx4 v[98:99], v[80:83], off
	s_nop 1
	v_cvt_pk_bf16_f32 v80, v84, v85
	v_cvt_pk_bf16_f32 v81, v86, v87
	v_cvt_pk_bf16_f32 v82, v102, v103
	v_cvt_pk_bf16_f32 v83, v104, v105
	global_store_dwordx4 v[98:99], v[80:83], off offset:256
	s_nop 0
	s_nop 0
	v_fmamk_f32 v80, v202, 0x3a800000, v158
	v_mul_f32_e32 v81, 0x4b800000, v80
	v_cmp_gt_f32_e32 vcc, s87, v80
	s_nop 1
	v_cndmask_b32_e32 v80, v80, v81, vcc
	v_rsq_f32_e32 v82, v80
	v_lshlrev_b64 v[80:81], 13, v[96:97]
	v_lshl_add_u64 v[80:81], s[8:9], 0, v[80:81]
	v_lshl_add_u64 v[80:81], v[80:81], 0, v[164:165]
	v_mul_f32_e32 v83, 0x45800000, v82
	v_cndmask_b32_e32 v82, v82, v83, vcc
	v_pk_mul_f32 v[78:79], v[78:79], v[82:83] op_sel_hi:[1,0]
	v_pk_mul_f32 v[76:77], v[76:77], v[82:83] op_sel_hi:[1,0]
	v_pk_mul_f32 v[74:75], v[74:75], v[82:83] op_sel_hi:[1,0]
	v_pk_mul_f32 v[72:73], v[72:73], v[82:83] op_sel_hi:[1,0]
	v_pk_mul_f32 v[70:71], v[70:71], v[82:83] op_sel_hi:[1,0]
	v_pk_mul_f32 v[68:69], v[68:69], v[82:83] op_sel_hi:[1,0]
	v_pk_mul_f32 v[84:85], v[66:67], v[82:83] op_sel_hi:[1,0]
	v_pk_mul_f32 v[82:83], v[64:65], v[82:83] op_sel_hi:[1,0]
	v_cvt_pk_bf16_f32 v64, v76, v77
	v_cvt_pk_bf16_f32 v65, v78, v79
	v_cvt_pk_bf16_f32 v66, v72, v73
	v_cvt_pk_bf16_f32 v67, v74, v75
	global_store_dwordx4 v[80:81], v[64:67], off
	s_nop 1
	v_cvt_pk_bf16_f32 v64, v68, v69
	v_cvt_pk_bf16_f32 v65, v70, v71
	v_cvt_pk_bf16_f32 v66, v82, v83
	v_cvt_pk_bf16_f32 v67, v84, v85
	global_store_dwordx4 v[80:81], v[64:67], off offset:256
	s_nop 0
	s_nop 0
	v_lshl_add_u64 v[64:65], v[148:149], 0, s[0:1]
	s_nop 0
	v_fmamk_f32 v66, v203, 0x3a800000, v158
	v_mul_f32_e32 v67, 0x4b800000, v66
	v_cmp_gt_f32_e32 vcc, s87, v66
	s_nop 1
	v_cndmask_b32_e32 v66, v66, v67, vcc
	v_rsq_f32_e32 v68, v66
	v_add_co_u32_e64 v66, s[0:1], s19, v148
	s_mov_b32 s19, 0x120000
	v_mul_f32_e32 v69, 0x45800000, v68
	v_cndmask_b32_e32 v68, v68, v69, vcc
	v_addc_co_u32_e64 v67, s[0:1], 0, v149, s[0:1]
	v_pk_mul_f32 v[62:63], v[62:63], v[68:69] op_sel_hi:[1,0]
	v_pk_mul_f32 v[60:61], v[60:61], v[68:69] op_sel_hi:[1,0]
	v_pk_mul_f32 v[58:59], v[58:59], v[68:69] op_sel_hi:[1,0]
	v_pk_mul_f32 v[56:57], v[56:57], v[68:69] op_sel_hi:[1,0]
	v_pk_mul_f32 v[54:55], v[54:55], v[68:69] op_sel_hi:[1,0]
	v_pk_mul_f32 v[52:53], v[52:53], v[68:69] op_sel_hi:[1,0]
	v_pk_mul_f32 v[70:71], v[50:51], v[68:69] op_sel_hi:[1,0]
	v_pk_mul_f32 v[68:69], v[48:49], v[68:69] op_sel_hi:[1,0]
	v_cvt_pk_bf16_f32 v48, v60, v61
	v_cvt_pk_bf16_f32 v49, v62, v63
	v_cvt_pk_bf16_f32 v50, v56, v57
	v_cvt_pk_bf16_f32 v51, v58, v59
	global_store_dwordx4 v[66:67], v[48:51], off
	s_mov_b64 s[0:1], 0x120000
	s_nop 0
	v_cvt_pk_bf16_f32 v48, v52, v53
	v_cvt_pk_bf16_f32 v49, v54, v55
	v_cvt_pk_bf16_f32 v50, v68, v69
	v_cvt_pk_bf16_f32 v51, v70, v71
	global_store_dwordx4 v[64:65], v[48:51], off offset:256
	s_nop 0
	s_nop 0
	v_lshl_add_u64 v[48:49], v[148:149], 0, s[0:1]
	s_nop 0
	v_fmamk_f32 v50, v204, 0x3a800000, v158
	v_mul_f32_e32 v51, 0x4b800000, v50
	v_cmp_gt_f32_e32 vcc, s87, v50
	s_nop 1
	v_cndmask_b32_e32 v50, v50, v51, vcc
	v_rsq_f32_e32 v52, v50
	v_add_co_u32_e64 v50, s[0:1], s19, v148
	v_mul_f32_e32 v53, 0x45800000, v52
	v_cndmask_b32_e32 v52, v52, v53, vcc
	v_addc_co_u32_e64 v51, s[0:1], 0, v149, s[0:1]
	v_pk_mul_f32 v[46:47], v[46:47], v[52:53] op_sel_hi:[1,0]
	v_pk_mul_f32 v[44:45], v[44:45], v[52:53] op_sel_hi:[1,0]
	v_pk_mul_f32 v[42:43], v[42:43], v[52:53] op_sel_hi:[1,0]
	v_pk_mul_f32 v[40:41], v[40:41], v[52:53] op_sel_hi:[1,0]
	v_pk_mul_f32 v[38:39], v[38:39], v[52:53] op_sel_hi:[1,0]
	v_pk_mul_f32 v[36:37], v[36:37], v[52:53] op_sel_hi:[1,0]
	v_pk_mul_f32 v[54:55], v[34:35], v[52:53] op_sel_hi:[1,0]
	v_pk_mul_f32 v[52:53], v[32:33], v[52:53] op_sel_hi:[1,0]
	v_cvt_pk_bf16_f32 v32, v44, v45
	v_cvt_pk_bf16_f32 v33, v46, v47
	v_cvt_pk_bf16_f32 v34, v40, v41
	v_cvt_pk_bf16_f32 v35, v42, v43
	global_store_dwordx4 v[50:51], v[32:35], off
	s_mov_b64 s[0:1], 0x140000
	s_nop 0
	v_cvt_pk_bf16_f32 v32, v36, v37
	v_cvt_pk_bf16_f32 v33, v38, v39
	v_cvt_pk_bf16_f32 v34, v52, v53
	v_cvt_pk_bf16_f32 v35, v54, v55
	global_store_dwordx4 v[48:49], v[32:35], off offset:256
	s_nop 0
	s_nop 0
	v_lshl_add_u64 v[32:33], v[148:149], 0, s[0:1]
	s_nop 0
	v_fmamk_f32 v34, v205, 0x3a800000, v158
	v_mul_f32_e32 v35, 0x4b800000, v34
	v_cmp_gt_f32_e32 vcc, s87, v34
	s_nop 1
	v_cndmask_b32_e32 v34, v34, v35, vcc
	v_rsq_f32_e32 v36, v34
	v_add_co_u32_e64 v34, s[0:1], s88, v148
	v_mul_f32_e32 v37, 0x45800000, v36
	v_cndmask_b32_e32 v36, v36, v37, vcc
	v_addc_co_u32_e64 v35, s[0:1], 0, v149, s[0:1]
	v_pk_mul_f32 v[30:31], v[30:31], v[36:37] op_sel_hi:[1,0]
	v_pk_mul_f32 v[28:29], v[28:29], v[36:37] op_sel_hi:[1,0]
	v_pk_mul_f32 v[26:27], v[26:27], v[36:37] op_sel_hi:[1,0]
	v_pk_mul_f32 v[24:25], v[24:25], v[36:37] op_sel_hi:[1,0]
	v_pk_mul_f32 v[22:23], v[22:23], v[36:37] op_sel_hi:[1,0]
	v_pk_mul_f32 v[20:21], v[20:21], v[36:37] op_sel_hi:[1,0]
	v_pk_mul_f32 v[38:39], v[18:19], v[36:37] op_sel_hi:[1,0]
	v_pk_mul_f32 v[36:37], v[16:17], v[36:37] op_sel_hi:[1,0]
	v_cvt_pk_bf16_f32 v16, v28, v29
	v_cvt_pk_bf16_f32 v17, v30, v31
	v_cvt_pk_bf16_f32 v18, v24, v25
	v_cvt_pk_bf16_f32 v19, v26, v27
	global_store_dwordx4 v[34:35], v[16:19], off
	s_andn2_b64 vcc, exec, s[2:3]
	s_nop 0
	v_cvt_pk_bf16_f32 v16, v20, v21
	v_cvt_pk_bf16_f32 v17, v22, v23
	v_cvt_pk_bf16_f32 v18, v36, v37
	v_cvt_pk_bf16_f32 v19, v38, v39
	global_store_dwordx4 v[32:33], v[16:19], off offset:256
	s_nop 0
	s_nop 0
	v_lshl_add_u64 v[16:17], v[148:149], 0, s[16:17]
	s_nop 0
	v_fmamk_f32 v18, v206, 0x3a800000, v158
	v_mul_f32_e32 v19, 0x4b800000, v18
	v_cmp_gt_f32_e64 s[0:1], s87, v18
	s_nop 1
	v_cndmask_b32_e64 v18, v18, v19, s[0:1]
	v_rsq_f32_e32 v20, v18
	v_add_co_u32_e64 v18, s[2:3], s89, v148
	v_mul_f32_e32 v21, 0x45800000, v20
	v_cndmask_b32_e64 v20, v20, v21, s[0:1]
	v_addc_co_u32_e64 v19, s[2:3], 0, v149, s[2:3]
	v_pk_mul_f32 v[14:15], v[14:15], v[20:21] op_sel_hi:[1,0]
	v_pk_mul_f32 v[12:13], v[12:13], v[20:21] op_sel_hi:[1,0]
	v_pk_mul_f32 v[10:11], v[10:11], v[20:21] op_sel_hi:[1,0]
	v_pk_mul_f32 v[8:9], v[8:9], v[20:21] op_sel_hi:[1,0]
	v_pk_mul_f32 v[6:7], v[6:7], v[20:21] op_sel_hi:[1,0]
	v_pk_mul_f32 v[4:5], v[4:5], v[20:21] op_sel_hi:[1,0]
	v_pk_mul_f32 v[22:23], v[2:3], v[20:21] op_sel_hi:[1,0]
	v_pk_mul_f32 v[20:21], v[0:1], v[20:21] op_sel_hi:[1,0]
	v_cvt_pk_bf16_f32 v0, v12, v13
	v_cvt_pk_bf16_f32 v1, v14, v15
	v_cvt_pk_bf16_f32 v2, v8, v9
	v_cvt_pk_bf16_f32 v3, v10, v11
	s_mov_b64 s[0:1], -1
	global_store_dwordx4 v[18:19], v[0:3], off
	s_nop 1
	v_cvt_pk_bf16_f32 v0, v4, v5
	v_cvt_pk_bf16_f32 v1, v6, v7
	v_cvt_pk_bf16_f32 v2, v20, v21
	v_cvt_pk_bf16_f32 v3, v22, v23
	global_store_dwordx4 v[16:17], v[0:3], off offset:256
	s_cbranch_vccnz .LBB0_287
	s_andn2_b64 vcc, exec, s[6:7]
	s_cbranch_vccnz .LBB0_286
	s_barrier
	s_branch .LBB0_286

.LBB0_993:
	v_lshl_add_u32 v148, s52, 8, v152
	v_lshl_or_b32 v146, s50, 8, v154
	v_ashrrev_i32_e32 v149, 31, v148
	v_ashrrev_i32_e32 v147, 31, v146
	v_lshlrev_b64 v[160:161], 10, v[148:149]
	v_readlane_b32 s76, v255, 1
	v_lshl_add_u64 v[168:169], v[160:161], 0, v[146:147]
	v_readlane_b32 s77, v255, 2
	v_xor_b32_e32 v159, 32, v158
	v_readlane_b32 s78, v255, 3
	v_lshl_add_u64 v[170:171], v[168:169], 2, s[76:77]
	v_mov_b32_e32 v240, v170
	v_mov_b32_e32 v241, v171
	global_load_dwordx4 v[176:179], v[170:171], off
	global_load_dwordx4 v[180:183], v[170:171], off offset:16
	global_load_dwordx4 v[184:187], v[170:171], off offset:512
	global_load_dwordx4 v[188:191], v[170:171], off offset:528
	s_mov_b64 s[98:99], 0x10000
	v_lshl_add_u64 v[242:243], v[240:241], 0, s[98:99]
	global_load_dwordx4 v[192:195], v[242:243], off
	global_load_dwordx4 v[196:199], v[242:243], off offset:16
	global_load_dwordx4 v[200:203], v[242:243], off offset:512
	global_load_dwordx4 v[204:207], v[242:243], off offset:528
	s_mov_b64 s[98:99], 0x20000
	v_lshl_add_u64 v[242:243], v[240:241], 0, s[98:99]
	global_load_dwordx4 v[208:211], v[242:243], off
	global_load_dwordx4 v[212:215], v[242:243], off offset:16
	global_load_dwordx4 v[216:219], v[242:243], off offset:512
	global_load_dwordx4 v[220:223], v[242:243], off offset:528
	s_mov_b64 s[98:99], 0x30000
	v_lshl_add_u64 v[242:243], v[240:241], 0, s[98:99]
	global_load_dwordx4 v[224:227], v[242:243], off
	global_load_dwordx4 v[228:231], v[242:243], off offset:16
	global_load_dwordx4 v[232:235], v[242:243], off offset:512
	global_load_dwordx4 v[236:239], v[242:243], off offset:528
	s_nop 0
	s_nop 0
	v_lshlrev_b64 v[168:169], 1, v[168:169]
	v_lshl_add_u64 v[172:173], s[10:11], 0, v[168:169]
	v_or_b32_e32 v168, 0x100, v168
	v_readlane_b32 s79, v255, 4
	v_readlane_b32 s80, v255, 5
	v_readlane_b32 s81, v255, 6
	v_readlane_b32 s82, v255, 7
	v_readlane_b32 s83, v255, 8
	v_readlane_b32 s84, v255, 9
	v_readlane_b32 s85, v255, 10
	v_readlane_b32 s86, v255, 11
	v_readlane_b32 s87, v255, 12
	v_readlane_b32 s88, v255, 13
	v_readlane_b32 s89, v255, 14
	v_readlane_b32 s90, v255, 15
	v_readlane_b32 s91, v255, 16
	s_waitcnt vmcnt(12)
	v_pk_add_f32 v[126:127], v[126:127], v[178:179]
	v_pk_add_f32 v[174:175], v[124:125], v[176:177]
	v_pk_add_f32 v[166:167], v[122:123], v[182:183]
	v_pk_add_f32 v[164:165], v[120:121], v[180:181]
	v_cvt_pk_bf16_f32 v120, v174, v175
	v_cvt_pk_bf16_f32 v121, v126, v127
	v_mul_f32_e32 v127, v127, v127
	v_cvt_pk_bf16_f32 v122, v164, v165
	v_cvt_pk_bf16_f32 v123, v166, v167
	global_store_dwordx4 v[172:173], v[120:123], off
	s_nop 0
	s_nop 0
	s_nop 0
	v_and_b32_e32 v121, 64, v158
	v_mul_f32_e32 v170, v175, v175
	v_mul_f32_e32 v165, v165, v165
	v_mul_f32_e32 v167, v167, v167
	v_xor_b32_e32 v120, 16, v158
	v_add_u32_e32 v121, 64, v121
	v_fmac_f32_e32 v170, v174, v174
	v_fmac_f32_e32 v127, v126, v126
	v_fmac_f32_e32 v165, v164, v164
	v_fmac_f32_e32 v167, v166, v166
	v_cmp_lt_i32_e32 vcc, v120, v121
	v_add_f32_e32 v126, v170, v127
	v_add_f32_e32 v127, v165, v167
	v_cndmask_b32_e32 v120, v158, v120, vcc
	v_add_f32_e32 v126, v126, v127
	v_lshlrev_b32_e32 v120, 2, v120
	v_cmp_lt_i32_e32 vcc, v159, v121
	s_nop 0
	v_pk_add_f32 v[118:119], v[118:119], v[186:187]
	v_pk_add_f32 v[116:117], v[116:117], v[184:185]
	s_nop 0
	v_pk_add_f32 v[122:123], v[114:115], v[190:191]
	v_pk_add_f32 v[112:113], v[112:113], v[188:189]
	v_mul_f32_e32 v114, v117, v117
	v_mul_f32_e32 v115, v119, v119
	v_mul_f32_e32 v124, v113, v113
	v_mul_f32_e32 v125, v123, v123
	v_fmac_f32_e32 v114, v116, v116
	v_fmac_f32_e32 v115, v118, v118
	v_fmac_f32_e32 v124, v112, v112
	v_fmac_f32_e32 v125, v122, v122
	v_add_f32_e32 v114, v114, v115
	v_add_f32_e32 v115, v124, v125
	v_add_f32_e32 v114, v114, v115
	v_add_f32_e32 v114, v126, v114
	ds_bpermute_b32 v115, v120, v114
	v_cndmask_b32_e32 v121, v158, v159, vcc
	v_cvt_pk_bf16_f32 v116, v116, v117
	v_cvt_pk_bf16_f32 v117, v118, v119
	v_cvt_pk_bf16_f32 v118, v112, v113
	s_waitcnt lgkmcnt(0)
	v_add_f32_e32 v112, v114, v115
	v_lshlrev_b32_e32 v114, 2, v121
	ds_bpermute_b32 v113, v114, v112
	v_cvt_pk_bf16_f32 v119, v122, v123
	v_lshl_add_u64 v[122:123], s[10:11], 0, v[168:169]
	global_store_dwordx4 v[122:123], v[116:119], off
	s_and_saveexec_b64 s[20:21], s[2:3]
	s_cbranch_execz .LBB0_995
	v_lshl_add_u64 v[116:117], v[148:149], 2, s[12:13]
	s_waitcnt lgkmcnt(0)
	v_add_f32_e32 v112, v112, v113
	global_atomic_add_f32 v[116:117], v112, off
.LBB0_995:
	s_or_b64 exec, exec, s[20:21]
	v_or_b32_e32 v112, 16, v148
	s_waitcnt lgkmcnt(0)
	v_ashrrev_i32_e32 v113, 31, v112
	v_lshlrev_b64 v[116:117], 10, v[112:113]
	v_readlane_b32 s76, v255, 1
	v_lshl_add_u64 v[126:127], v[116:117], 0, v[146:147]
	v_readlane_b32 s77, v255, 2
	v_readlane_b32 s78, v255, 3
	v_readlane_b32 s79, v255, 4
	v_lshl_add_u64 v[160:161], v[126:127], 2, s[76:77]
	s_mov_b64 s[98:99], 0x80000
	v_lshl_add_u64 v[242:243], v[240:241], 0, s[98:99]
	global_load_dwordx4 v[176:179], v[242:243], off
	global_load_dwordx4 v[180:183], v[242:243], off offset:16
	global_load_dwordx4 v[184:187], v[242:243], off offset:512
	global_load_dwordx4 v[188:191], v[242:243], off offset:528
	s_nop 0
	s_nop 0
	v_lshlrev_b64 v[126:127], 1, v[126:127]
	v_lshl_add_u64 v[162:163], s[10:11], 0, v[126:127]
	v_or_b32_e32 v126, 0x100, v126
	v_readlane_b32 s80, v255, 5
	v_readlane_b32 s81, v255, 6
	v_readlane_b32 s82, v255, 7
	v_readlane_b32 s83, v255, 8
	v_readlane_b32 s84, v255, 9
	v_readlane_b32 s85, v255, 10
	v_readlane_b32 s86, v255, 11
	v_readlane_b32 s87, v255, 12
	v_readlane_b32 s88, v255, 13
	v_readlane_b32 s89, v255, 14
	v_readlane_b32 s90, v255, 15
	v_readlane_b32 s91, v255, 16
	s_waitcnt vmcnt(14)
	v_pk_add_f32 v[118:119], v[110:111], v[194:195]
	v_pk_add_f32 v[116:117], v[108:109], v[192:193]
	s_nop 0
	v_pk_add_f32 v[124:125], v[106:107], v[198:199]
	v_pk_add_f32 v[122:123], v[104:105], v[196:197]
	v_cvt_pk_bf16_f32 v104, v116, v117
	v_cvt_pk_bf16_f32 v105, v118, v119
	v_mul_f32_e32 v115, v117, v117
	v_cvt_pk_bf16_f32 v106, v122, v123
	v_cvt_pk_bf16_f32 v107, v124, v125
	global_store_dwordx4 v[162:163], v[104:107], off
	s_nop 0
	s_nop 0
	s_nop 0
	v_mul_f32_e32 v117, v119, v119
	v_mul_f32_e32 v119, v123, v123
	v_mul_f32_e32 v121, v125, v125
	v_fmac_f32_e32 v115, v116, v116
	v_fmac_f32_e32 v117, v118, v118
	v_fmac_f32_e32 v119, v122, v122
	v_fmac_f32_e32 v121, v124, v124
	v_add_f32_e32 v115, v115, v117
	v_add_f32_e32 v116, v119, v121
	v_add_f32_e32 v115, v115, v116
	s_nop 0
	v_pk_add_f32 v[102:103], v[102:103], v[202:203]
	v_pk_add_f32 v[100:101], v[100:101], v[200:201]
	s_nop 0
	v_pk_add_f32 v[104:105], v[98:99], v[206:207]
	v_pk_add_f32 v[96:97], v[96:97], v[204:205]
	v_mul_f32_e32 v98, v101, v101
	v_mul_f32_e32 v99, v103, v103
	v_mul_f32_e32 v106, v97, v97
	v_mul_f32_e32 v107, v105, v105
	v_fmac_f32_e32 v98, v100, v100
	v_fmac_f32_e32 v99, v102, v102
	v_fmac_f32_e32 v106, v96, v96
	v_fmac_f32_e32 v107, v104, v104
	v_add_f32_e32 v98, v98, v99
	v_add_f32_e32 v99, v106, v107
	v_add_f32_e32 v98, v98, v99
	v_add_f32_e32 v106, v115, v98
	ds_bpermute_b32 v107, v120, v106
	v_cvt_pk_bf16_f32 v98, v100, v101
	v_cvt_pk_bf16_f32 v99, v102, v103
	v_cvt_pk_bf16_f32 v100, v96, v97
	v_lshl_add_u64 v[102:103], s[10:11], 0, v[126:127]
	s_waitcnt lgkmcnt(0)
	v_add_f32_e32 v96, v106, v107
	ds_bpermute_b32 v97, v114, v96
	v_cvt_pk_bf16_f32 v101, v104, v105
	global_store_dwordx4 v[102:103], v[98:101], off
	s_and_saveexec_b64 s[20:21], s[2:3]
	s_cbranch_execz .LBB0_997
	v_lshl_add_u64 v[98:99], v[112:113], 2, s[12:13]
	s_waitcnt lgkmcnt(0)
	v_add_f32_e32 v96, v96, v97
	global_atomic_add_f32 v[98:99], v96, off
.LBB0_997:
	s_or_b64 exec, exec, s[20:21]
	v_or_b32_e32 v96, 32, v148
	s_waitcnt lgkmcnt(0)
	v_ashrrev_i32_e32 v97, 31, v96
	v_lshlrev_b64 v[98:99], 10, v[96:97]
	v_readlane_b32 s76, v255, 1
	v_lshl_add_u64 v[106:107], v[98:99], 0, v[146:147]
	v_readlane_b32 s77, v255, 2
	v_readlane_b32 s78, v255, 3
	v_readlane_b32 s79, v255, 4
	v_lshl_add_u64 v[108:109], v[106:107], 2, s[76:77]
	s_mov_b64 s[98:99], 0x90000
	v_lshl_add_u64 v[242:243], v[240:241], 0, s[98:99]
	global_load_dwordx4 v[192:195], v[242:243], off
	global_load_dwordx4 v[196:199], v[242:243], off offset:16
	global_load_dwordx4 v[200:203], v[242:243], off offset:512
	global_load_dwordx4 v[204:207], v[242:243], off offset:528
	s_nop 0
	s_nop 0
	v_lshlrev_b64 v[106:107], 1, v[106:107]
	v_lshl_add_u64 v[110:111], s[10:11], 0, v[106:107]
	v_or_b32_e32 v106, 0x100, v106
	v_readlane_b32 s80, v255, 5
	v_readlane_b32 s81, v255, 6
	v_readlane_b32 s82, v255, 7
	v_readlane_b32 s83, v255, 8
	v_readlane_b32 s84, v255, 9
	v_readlane_b32 s85, v255, 10
	v_readlane_b32 s86, v255, 11
	v_readlane_b32 s87, v255, 12
	v_readlane_b32 s88, v255, 13
	v_readlane_b32 s89, v255, 14
	v_readlane_b32 s90, v255, 15
	v_readlane_b32 s91, v255, 16
	s_waitcnt vmcnt(16)
	v_pk_add_f32 v[100:101], v[94:95], v[210:211]
	v_pk_add_f32 v[98:99], v[92:93], v[208:209]
	s_nop 0
	v_pk_add_f32 v[104:105], v[90:91], v[214:215]
	v_pk_add_f32 v[102:103], v[88:89], v[212:213]
	v_cvt_pk_bf16_f32 v88, v98, v99
	v_cvt_pk_bf16_f32 v89, v100, v101
	v_mul_f32_e32 v99, v99, v99
	v_cvt_pk_bf16_f32 v90, v102, v103
	v_cvt_pk_bf16_f32 v91, v104, v105
	global_store_dwordx4 v[110:111], v[88:91], off
	s_nop 0
	s_nop 0
	s_nop 0
	v_mul_f32_e32 v101, v101, v101
	v_mul_f32_e32 v103, v103, v103
	v_mul_f32_e32 v105, v105, v105
	v_fmac_f32_e32 v99, v98, v98
	v_fmac_f32_e32 v101, v100, v100
	v_fmac_f32_e32 v103, v102, v102
	v_fmac_f32_e32 v105, v104, v104
	v_add_f32_e32 v98, v99, v101
	v_add_f32_e32 v99, v103, v105
	v_add_f32_e32 v98, v98, v99
	s_nop 0
	v_pk_add_f32 v[86:87], v[86:87], v[218:219]
	v_pk_add_f32 v[84:85], v[84:85], v[216:217]
	s_nop 0
	v_pk_add_f32 v[88:89], v[82:83], v[222:223]
	v_pk_add_f32 v[80:81], v[80:81], v[220:221]
	v_mul_f32_e32 v82, v85, v85
	v_mul_f32_e32 v83, v87, v87
	v_mul_f32_e32 v90, v81, v81
	v_mul_f32_e32 v91, v89, v89
	v_fmac_f32_e32 v82, v84, v84
	v_fmac_f32_e32 v83, v86, v86
	v_fmac_f32_e32 v90, v80, v80
	v_fmac_f32_e32 v91, v88, v88
	v_add_f32_e32 v82, v82, v83
	v_add_f32_e32 v83, v90, v91
	v_add_f32_e32 v82, v82, v83
	v_add_f32_e32 v90, v98, v82
	ds_bpermute_b32 v91, v120, v90
	v_cvt_pk_bf16_f32 v82, v84, v85
	v_cvt_pk_bf16_f32 v83, v86, v87
	v_cvt_pk_bf16_f32 v84, v80, v81
	v_lshl_add_u64 v[86:87], s[10:11], 0, v[106:107]
	s_waitcnt lgkmcnt(0)
	v_add_f32_e32 v80, v90, v91
	ds_bpermute_b32 v81, v114, v80
	v_cvt_pk_bf16_f32 v85, v88, v89
	global_store_dwordx4 v[86:87], v[82:85], off
	s_and_saveexec_b64 s[20:21], s[2:3]
	s_cbranch_execz .LBB0_999
	v_lshl_add_u64 v[82:83], v[96:97], 2, s[12:13]
	s_waitcnt lgkmcnt(0)
	v_add_f32_e32 v80, v80, v81
	global_atomic_add_f32 v[82:83], v80, off
.LBB0_999:
	s_or_b64 exec, exec, s[20:21]
	v_or_b32_e32 v80, 48, v148
	s_waitcnt lgkmcnt(0)
	v_ashrrev_i32_e32 v81, 31, v80
	v_lshlrev_b64 v[82:83], 10, v[80:81]
	v_readlane_b32 s76, v255, 1
	v_lshl_add_u64 v[90:91], v[82:83], 0, v[146:147]
	v_readlane_b32 s77, v255, 2
	v_readlane_b32 s78, v255, 3
	v_readlane_b32 s79, v255, 4
	v_lshl_add_u64 v[92:93], v[90:91], 2, s[76:77]
	s_mov_b64 s[98:99], 0xa0000
	v_lshl_add_u64 v[242:243], v[240:241], 0, s[98:99]
	global_load_dwordx4 v[208:211], v[242:243], off
	global_load_dwordx4 v[212:215], v[242:243], off offset:16
	global_load_dwordx4 v[216:219], v[242:243], off offset:512
	global_load_dwordx4 v[220:223], v[242:243], off offset:528
	s_nop 0
	s_nop 0
	v_lshlrev_b64 v[90:91], 1, v[90:91]
	v_lshl_add_u64 v[94:95], s[10:11], 0, v[90:91]
	v_or_b32_e32 v90, 0x100, v90
	v_readlane_b32 s80, v255, 5
	v_readlane_b32 s81, v255, 6
	v_readlane_b32 s82, v255, 7
	v_readlane_b32 s83, v255, 8
	v_readlane_b32 s84, v255, 9
	v_readlane_b32 s85, v255, 10
	v_readlane_b32 s86, v255, 11
	v_readlane_b32 s87, v255, 12
	v_readlane_b32 s88, v255, 13
	v_readlane_b32 s89, v255, 14
	v_readlane_b32 s90, v255, 15
	v_readlane_b32 s91, v255, 16
	s_waitcnt vmcnt(18)
	v_pk_add_f32 v[84:85], v[78:79], v[226:227]
	v_pk_add_f32 v[82:83], v[76:77], v[224:225]
	s_nop 0
	v_pk_add_f32 v[88:89], v[74:75], v[230:231]
	v_pk_add_f32 v[86:87], v[72:73], v[228:229]
	v_cvt_pk_bf16_f32 v72, v82, v83
	v_cvt_pk_bf16_f32 v73, v84, v85
	v_mul_f32_e32 v83, v83, v83
	v_cvt_pk_bf16_f32 v74, v86, v87
	v_cvt_pk_bf16_f32 v75, v88, v89
	global_store_dwordx4 v[94:95], v[72:75], off
	s_nop 0
	s_nop 0
	s_nop 0
	v_mul_f32_e32 v85, v85, v85
	v_mul_f32_e32 v87, v87, v87
	v_mul_f32_e32 v89, v89, v89
	v_fmac_f32_e32 v83, v82, v82
	v_fmac_f32_e32 v85, v84, v84
	v_fmac_f32_e32 v87, v86, v86
	v_fmac_f32_e32 v89, v88, v88
	v_add_f32_e32 v82, v83, v85
	v_add_f32_e32 v83, v87, v89
	v_add_f32_e32 v82, v82, v83
	s_nop 0
	v_pk_add_f32 v[70:71], v[70:71], v[234:235]
	v_pk_add_f32 v[68:69], v[68:69], v[232:233]
	s_nop 0
	v_pk_add_f32 v[72:73], v[66:67], v[238:239]
	v_pk_add_f32 v[64:65], v[64:65], v[236:237]
	v_mul_f32_e32 v66, v69, v69
	v_mul_f32_e32 v67, v71, v71
	v_mul_f32_e32 v74, v65, v65
	v_mul_f32_e32 v75, v73, v73
	v_fmac_f32_e32 v66, v68, v68
	v_fmac_f32_e32 v67, v70, v70
	v_fmac_f32_e32 v74, v64, v64
	v_fmac_f32_e32 v75, v72, v72
	v_add_f32_e32 v66, v66, v67
	v_add_f32_e32 v67, v74, v75
	v_add_f32_e32 v66, v66, v67
	v_add_f32_e32 v74, v82, v66
	ds_bpermute_b32 v75, v120, v74
	v_cvt_pk_bf16_f32 v66, v68, v69
	v_cvt_pk_bf16_f32 v67, v70, v71
	v_cvt_pk_bf16_f32 v68, v64, v65
	v_lshl_add_u64 v[70:71], s[10:11], 0, v[90:91]
	s_waitcnt lgkmcnt(0)
	v_add_f32_e32 v64, v74, v75
	ds_bpermute_b32 v65, v114, v64
	v_cvt_pk_bf16_f32 v69, v72, v73
	global_store_dwordx4 v[70:71], v[66:69], off
	s_and_saveexec_b64 s[20:21], s[2:3]
	s_cbranch_execz .LBB0_1001
	v_lshl_add_u64 v[66:67], v[80:81], 2, s[12:13]
	s_waitcnt lgkmcnt(0)
	v_add_f32_e32 v64, v64, v65
	global_atomic_add_f32 v[66:67], v64, off
.LBB0_1001:
	s_or_b64 exec, exec, s[20:21]
	v_add_u32_e32 v64, 0x80, v148
	s_waitcnt lgkmcnt(0)
	v_ashrrev_i32_e32 v65, 31, v64
	v_lshlrev_b64 v[66:67], 10, v[64:65]
	v_readlane_b32 s76, v255, 1
	v_lshl_add_u64 v[74:75], v[66:67], 0, v[146:147]
	v_readlane_b32 s77, v255, 2
	v_readlane_b32 s78, v255, 3
	v_readlane_b32 s79, v255, 4
	v_lshl_add_u64 v[76:77], v[74:75], 2, s[76:77]
	s_mov_b64 s[98:99], 0xb0000
	v_lshl_add_u64 v[242:243], v[240:241], 0, s[98:99]
	global_load_dwordx4 v[224:227], v[242:243], off
	global_load_dwordx4 v[228:231], v[242:243], off offset:16
	global_load_dwordx4 v[232:235], v[242:243], off offset:512
	global_load_dwordx4 v[236:239], v[242:243], off offset:528
	s_nop 0
	s_nop 0
	v_lshlrev_b64 v[74:75], 1, v[74:75]
	v_lshl_add_u64 v[78:79], s[10:11], 0, v[74:75]
	v_or_b32_e32 v74, 0x100, v74
	v_readlane_b32 s80, v255, 5
	v_readlane_b32 s81, v255, 6
	v_readlane_b32 s82, v255, 7
	v_readlane_b32 s83, v255, 8
	v_readlane_b32 s84, v255, 9
	v_readlane_b32 s85, v255, 10
	v_readlane_b32 s86, v255, 11
	v_readlane_b32 s87, v255, 12
	v_readlane_b32 s88, v255, 13
	v_readlane_b32 s89, v255, 14
	v_readlane_b32 s90, v255, 15
	v_readlane_b32 s91, v255, 16
	s_waitcnt vmcnt(18)
	v_pk_add_f32 v[68:69], v[62:63], v[178:179]
	v_pk_add_f32 v[66:67], v[60:61], v[176:177]
	s_nop 0
	v_pk_add_f32 v[72:73], v[58:59], v[182:183]
	v_pk_add_f32 v[70:71], v[56:57], v[180:181]
	v_cvt_pk_bf16_f32 v56, v66, v67
	v_cvt_pk_bf16_f32 v57, v68, v69
	v_mul_f32_e32 v67, v67, v67
	v_cvt_pk_bf16_f32 v58, v70, v71
	v_cvt_pk_bf16_f32 v59, v72, v73
	global_store_dwordx4 v[78:79], v[56:59], off
	s_nop 0
	s_nop 0
	s_nop 0
	v_mul_f32_e32 v69, v69, v69
	v_mul_f32_e32 v71, v71, v71
	v_mul_f32_e32 v73, v73, v73
	v_fmac_f32_e32 v67, v66, v66
	v_fmac_f32_e32 v69, v68, v68
	v_fmac_f32_e32 v71, v70, v70
	v_fmac_f32_e32 v73, v72, v72
	v_add_f32_e32 v66, v67, v69
	v_add_f32_e32 v67, v71, v73
	v_add_f32_e32 v66, v66, v67
	s_nop 0
	v_pk_add_f32 v[54:55], v[54:55], v[186:187]
	v_pk_add_f32 v[52:53], v[52:53], v[184:185]
	s_nop 0
	v_pk_add_f32 v[56:57], v[50:51], v[190:191]
	v_pk_add_f32 v[48:49], v[48:49], v[188:189]
	v_mul_f32_e32 v50, v53, v53
	v_mul_f32_e32 v51, v55, v55
	v_mul_f32_e32 v58, v49, v49
	v_mul_f32_e32 v59, v57, v57
	v_fmac_f32_e32 v50, v52, v52
	v_fmac_f32_e32 v51, v54, v54
	v_fmac_f32_e32 v58, v48, v48
	v_fmac_f32_e32 v59, v56, v56
	v_add_f32_e32 v50, v50, v51
	v_add_f32_e32 v51, v58, v59
	v_add_f32_e32 v50, v50, v51
	v_add_f32_e32 v58, v66, v50
	ds_bpermute_b32 v59, v120, v58
	v_cvt_pk_bf16_f32 v50, v52, v53
	v_cvt_pk_bf16_f32 v51, v54, v55
	v_cvt_pk_bf16_f32 v52, v48, v49
	v_lshl_add_u64 v[54:55], s[10:11], 0, v[74:75]
	s_waitcnt lgkmcnt(0)
	v_add_f32_e32 v48, v58, v59
	ds_bpermute_b32 v49, v114, v48
	v_cvt_pk_bf16_f32 v53, v56, v57
	global_store_dwordx4 v[54:55], v[50:53], off
	s_and_saveexec_b64 s[20:21], s[2:3]
	s_cbranch_execz .LBB0_1003
	v_lshl_add_u64 v[50:51], v[64:65], 2, s[12:13]
	s_waitcnt lgkmcnt(0)
	v_add_f32_e32 v48, v48, v49
	global_atomic_add_f32 v[50:51], v48, off
.LBB0_1003:
	s_or_b64 exec, exec, s[20:21]
	v_add_u32_e32 v48, 0x90, v148
	s_waitcnt lgkmcnt(0)
	v_ashrrev_i32_e32 v49, 31, v48
	v_lshlrev_b64 v[50:51], 10, v[48:49]
	v_readlane_b32 s76, v255, 1
	v_lshl_add_u64 v[58:59], v[50:51], 0, v[146:147]
	v_readlane_b32 s77, v255, 2
	v_readlane_b32 s78, v255, 3
	v_readlane_b32 s79, v255, 4
	v_lshl_add_u64 v[60:61], v[58:59], 2, s[76:77]
	s_nop 0
	s_nop 0
	v_lshlrev_b64 v[58:59], 1, v[58:59]
	v_lshl_add_u64 v[62:63], s[10:11], 0, v[58:59]
	v_or_b32_e32 v58, 0x100, v58
	v_readlane_b32 s80, v255, 5
	v_readlane_b32 s81, v255, 6
	v_readlane_b32 s82, v255, 7
	v_readlane_b32 s83, v255, 8
	v_readlane_b32 s84, v255, 9
	v_readlane_b32 s85, v255, 10
	v_readlane_b32 s86, v255, 11
	v_readlane_b32 s87, v255, 12
	v_readlane_b32 s88, v255, 13
	v_readlane_b32 s89, v255, 14
	v_readlane_b32 s90, v255, 15
	v_readlane_b32 s91, v255, 16
	s_waitcnt vmcnt(14)
	v_pk_add_f32 v[52:53], v[46:47], v[194:195]
	v_pk_add_f32 v[50:51], v[44:45], v[192:193]
	s_nop 0
	v_pk_add_f32 v[56:57], v[42:43], v[198:199]
	v_pk_add_f32 v[54:55], v[40:41], v[196:197]
	v_cvt_pk_bf16_f32 v40, v50, v51
	v_cvt_pk_bf16_f32 v41, v52, v53
	v_mul_f32_e32 v51, v51, v51
	v_cvt_pk_bf16_f32 v42, v54, v55
	v_cvt_pk_bf16_f32 v43, v56, v57
	global_store_dwordx4 v[62:63], v[40:43], off
	s_nop 0
	s_nop 0
	s_nop 0
	v_mul_f32_e32 v53, v53, v53
	v_mul_f32_e32 v55, v55, v55
	v_mul_f32_e32 v57, v57, v57
	v_fmac_f32_e32 v51, v50, v50
	v_fmac_f32_e32 v53, v52, v52
	v_fmac_f32_e32 v55, v54, v54
	v_fmac_f32_e32 v57, v56, v56
	v_add_f32_e32 v50, v51, v53
	v_add_f32_e32 v51, v55, v57
	v_add_f32_e32 v50, v50, v51
	s_nop 0
	v_pk_add_f32 v[38:39], v[38:39], v[202:203]
	v_pk_add_f32 v[36:37], v[36:37], v[200:201]
	s_nop 0
	v_pk_add_f32 v[40:41], v[34:35], v[206:207]
	v_pk_add_f32 v[32:33], v[32:33], v[204:205]
	v_mul_f32_e32 v34, v37, v37
	v_mul_f32_e32 v35, v39, v39
	v_mul_f32_e32 v42, v33, v33
	v_mul_f32_e32 v43, v41, v41
	v_fmac_f32_e32 v34, v36, v36
	v_fmac_f32_e32 v35, v38, v38
	v_fmac_f32_e32 v42, v32, v32
	v_fmac_f32_e32 v43, v40, v40
	v_add_f32_e32 v34, v34, v35
	v_add_f32_e32 v35, v42, v43
	v_add_f32_e32 v34, v34, v35
	v_add_f32_e32 v42, v50, v34
	ds_bpermute_b32 v43, v120, v42
	v_cvt_pk_bf16_f32 v34, v36, v37
	v_cvt_pk_bf16_f32 v35, v38, v39
	v_cvt_pk_bf16_f32 v36, v32, v33
	v_lshl_add_u64 v[38:39], s[10:11], 0, v[58:59]
	s_waitcnt lgkmcnt(0)
	v_add_f32_e32 v32, v42, v43
	ds_bpermute_b32 v33, v114, v32
	v_cvt_pk_bf16_f32 v37, v40, v41
	global_store_dwordx4 v[38:39], v[34:37], off
	s_and_saveexec_b64 s[20:21], s[2:3]
	s_cbranch_execz .LBB0_1005
	v_lshl_add_u64 v[34:35], v[48:49], 2, s[12:13]
	s_waitcnt lgkmcnt(0)
	v_add_f32_e32 v32, v32, v33
	global_atomic_add_f32 v[34:35], v32, off
.LBB0_1005:
	s_or_b64 exec, exec, s[20:21]
	v_add_u32_e32 v32, 0xa0, v148
	s_waitcnt lgkmcnt(0)
	v_ashrrev_i32_e32 v33, 31, v32
	v_lshlrev_b64 v[34:35], 10, v[32:33]
	v_readlane_b32 s76, v255, 1
	v_lshl_add_u64 v[42:43], v[34:35], 0, v[146:147]
	v_readlane_b32 s77, v255, 2
	v_readlane_b32 s78, v255, 3
	v_readlane_b32 s79, v255, 4
	v_lshl_add_u64 v[44:45], v[42:43], 2, s[76:77]
	s_nop 0
	s_nop 0
	v_lshlrev_b64 v[42:43], 1, v[42:43]
	v_lshl_add_u64 v[46:47], s[10:11], 0, v[42:43]
	v_or_b32_e32 v42, 0x100, v42
	v_readlane_b32 s80, v255, 5
	v_readlane_b32 s81, v255, 6
	v_readlane_b32 s82, v255, 7
	v_readlane_b32 s83, v255, 8
	v_readlane_b32 s84, v255, 9
	v_readlane_b32 s85, v255, 10
	v_readlane_b32 s86, v255, 11
	v_readlane_b32 s87, v255, 12
	v_readlane_b32 s88, v255, 13
	v_readlane_b32 s89, v255, 14
	v_readlane_b32 s90, v255, 15
	v_readlane_b32 s91, v255, 16
	s_waitcnt vmcnt(10)
	v_pk_add_f32 v[36:37], v[30:31], v[210:211]
	v_pk_add_f32 v[34:35], v[28:29], v[208:209]
	s_nop 0
	v_pk_add_f32 v[40:41], v[26:27], v[214:215]
	v_pk_add_f32 v[38:39], v[24:25], v[212:213]
	v_cvt_pk_bf16_f32 v24, v34, v35
	v_cvt_pk_bf16_f32 v25, v36, v37
	v_mul_f32_e32 v35, v35, v35
	v_cvt_pk_bf16_f32 v26, v38, v39
	v_cvt_pk_bf16_f32 v27, v40, v41
	global_store_dwordx4 v[46:47], v[24:27], off
	s_nop 0
	s_nop 0
	s_nop 0
	v_mul_f32_e32 v37, v37, v37
	v_mul_f32_e32 v39, v39, v39
	v_mul_f32_e32 v41, v41, v41
	v_fmac_f32_e32 v35, v34, v34
	v_fmac_f32_e32 v37, v36, v36
	v_fmac_f32_e32 v39, v38, v38
	v_fmac_f32_e32 v41, v40, v40
	v_add_f32_e32 v34, v35, v37
	v_add_f32_e32 v35, v39, v41
	v_add_f32_e32 v34, v34, v35
	s_nop 0
	v_pk_add_f32 v[22:23], v[22:23], v[218:219]
	v_pk_add_f32 v[20:21], v[20:21], v[216:217]
	s_nop 0
	v_pk_add_f32 v[24:25], v[18:19], v[222:223]
	v_pk_add_f32 v[16:17], v[16:17], v[220:221]
	v_mul_f32_e32 v18, v21, v21
	v_mul_f32_e32 v19, v23, v23
	v_mul_f32_e32 v26, v17, v17
	v_mul_f32_e32 v27, v25, v25
	v_fmac_f32_e32 v18, v20, v20
	v_fmac_f32_e32 v19, v22, v22
	v_fmac_f32_e32 v26, v16, v16
	v_fmac_f32_e32 v27, v24, v24
	v_add_f32_e32 v18, v18, v19
	v_add_f32_e32 v19, v26, v27
	v_add_f32_e32 v18, v18, v19
	v_add_f32_e32 v26, v34, v18
	ds_bpermute_b32 v27, v120, v26
	v_cvt_pk_bf16_f32 v18, v20, v21
	v_cvt_pk_bf16_f32 v19, v22, v23
	v_cvt_pk_bf16_f32 v20, v16, v17
	v_lshl_add_u64 v[22:23], s[10:11], 0, v[42:43]
	s_waitcnt lgkmcnt(0)
	v_add_f32_e32 v16, v26, v27
	ds_bpermute_b32 v17, v114, v16
	v_cvt_pk_bf16_f32 v21, v24, v25
	global_store_dwordx4 v[22:23], v[18:21], off
	s_and_saveexec_b64 s[20:21], s[2:3]
	s_cbranch_execz .LBB0_1007
	v_lshl_add_u64 v[18:19], v[32:33], 2, s[12:13]
	s_waitcnt lgkmcnt(0)
	v_add_f32_e32 v16, v16, v17
	global_atomic_add_f32 v[18:19], v16, off
.LBB0_1007:
	s_or_b64 exec, exec, s[20:21]
	v_add_u32_e32 v16, 0xb0, v148
	s_waitcnt lgkmcnt(0)
	v_ashrrev_i32_e32 v17, 31, v16
	v_lshlrev_b64 v[18:19], 10, v[16:17]
	v_readlane_b32 s76, v255, 1
	v_lshl_add_u64 v[26:27], v[18:19], 0, v[146:147]
	v_readlane_b32 s77, v255, 2
	v_readlane_b32 s78, v255, 3
	v_readlane_b32 s79, v255, 4
	v_lshl_add_u64 v[28:29], v[26:27], 2, s[76:77]
	s_nop 0
	s_nop 0
	v_lshlrev_b64 v[26:27], 1, v[26:27]
	v_lshl_add_u64 v[30:31], s[10:11], 0, v[26:27]
	v_or_b32_e32 v26, 0x100, v26
	v_readlane_b32 s80, v255, 5
	v_readlane_b32 s81, v255, 6
	v_readlane_b32 s82, v255, 7
	v_readlane_b32 s83, v255, 8
	v_readlane_b32 s84, v255, 9
	v_readlane_b32 s85, v255, 10
	v_readlane_b32 s86, v255, 11
	v_readlane_b32 s87, v255, 12
	v_readlane_b32 s88, v255, 13
	v_readlane_b32 s89, v255, 14
	v_readlane_b32 s90, v255, 15
	v_readlane_b32 s91, v255, 16
	s_waitcnt vmcnt(6)
	v_pk_add_f32 v[20:21], v[14:15], v[226:227]
	v_pk_add_f32 v[18:19], v[12:13], v[224:225]
	s_nop 0
	v_pk_add_f32 v[24:25], v[10:11], v[230:231]
	v_pk_add_f32 v[22:23], v[8:9], v[228:229]
	v_cvt_pk_bf16_f32 v8, v18, v19
	v_cvt_pk_bf16_f32 v9, v20, v21
	v_mul_f32_e32 v19, v19, v19
	v_cvt_pk_bf16_f32 v10, v22, v23
	v_cvt_pk_bf16_f32 v11, v24, v25
	global_store_dwordx4 v[30:31], v[8:11], off
	s_nop 0
	s_nop 0
	s_nop 0
	v_mul_f32_e32 v21, v21, v21
	v_mul_f32_e32 v23, v23, v23
	v_mul_f32_e32 v25, v25, v25
	v_fmac_f32_e32 v19, v18, v18
	v_fmac_f32_e32 v21, v20, v20
	v_fmac_f32_e32 v23, v22, v22
	v_fmac_f32_e32 v25, v24, v24
	v_add_f32_e32 v18, v19, v21
	v_add_f32_e32 v19, v23, v25
	v_add_f32_e32 v18, v18, v19
	s_nop 0
	v_pk_add_f32 v[6:7], v[6:7], v[234:235]
	v_pk_add_f32 v[4:5], v[4:5], v[232:233]
	s_nop 0
	v_pk_add_f32 v[8:9], v[2:3], v[238:239]
	v_pk_add_f32 v[0:1], v[0:1], v[236:237]
	v_mul_f32_e32 v2, v5, v5
	v_mul_f32_e32 v3, v7, v7
	v_mul_f32_e32 v10, v1, v1
	v_mul_f32_e32 v11, v9, v9
	v_fmac_f32_e32 v2, v4, v4
	v_fmac_f32_e32 v3, v6, v6
	v_fmac_f32_e32 v10, v0, v0
	v_fmac_f32_e32 v11, v8, v8
	v_add_f32_e32 v2, v2, v3
	v_add_f32_e32 v3, v10, v11
	v_add_f32_e32 v2, v2, v3
	v_add_f32_e32 v10, v18, v2
	ds_bpermute_b32 v11, v120, v10
	v_cvt_pk_bf16_f32 v2, v4, v5
	v_cvt_pk_bf16_f32 v3, v6, v7
	v_cvt_pk_bf16_f32 v4, v0, v1
	v_lshl_add_u64 v[6:7], s[10:11], 0, v[26:27]
	s_waitcnt lgkmcnt(0)
	v_add_f32_e32 v0, v10, v11
	ds_bpermute_b32 v1, v114, v0
	v_cvt_pk_bf16_f32 v5, v8, v9
	global_store_dwordx4 v[6:7], v[2:5], off
	s_and_saveexec_b64 s[20:21], s[2:3]
	s_cbranch_execz .LBB0_1009
	v_lshl_add_u64 v[2:3], v[16:17], 2, s[12:13]
	s_waitcnt lgkmcnt(0)
	v_add_f32_e32 v0, v0, v1
	global_atomic_add_f32 v[2:3], v0, off

.LBB0_1089:
	v_lshl_add_u32 v150, s0, 8, v152
	v_ashrrev_i32_e32 v151, 31, v150
	v_lshl_add_u64 v[146:147], v[150:151], 2, s[14:15]
	global_load_dword v159, v[146:147], off
	global_load_dword v200, v[146:147], off offset:64
	global_load_dword v201, v[146:147], off offset:128
	global_load_dword v202, v[146:147], off offset:192
	global_load_dword v203, v[146:147], off offset:512
	global_load_dword v204, v[146:147], off offset:576
	global_load_dword v205, v[146:147], off offset:640
	global_load_dword v206, v[146:147], off offset:704
	v_lshl_or_b32 v148, s1, 8, v154
	v_ashrrev_i32_e32 v149, 31, v148
	v_lshlrev_b64 v[164:165], 1, v[148:149]
	v_lshlrev_b64 v[162:163], 11, v[150:151]
	v_or_b32_e32 v160, 16, v150
	v_ashrrev_i32_e32 v161, 31, v160
	s_waitcnt vmcnt(0)
	v_fmamk_f32 v148, v159, 0x3a800000, v158
	v_mul_f32_e32 v149, 0x4b800000, v148
	v_cmp_gt_f32_e32 vcc, s75, v148
	s_nop 1
	v_cndmask_b32_e32 v148, v148, v149, vcc
	v_rsq_f32_e32 v151, v148
	v_lshl_add_u64 v[148:149], s[12:13], 0, v[162:163]
	v_lshl_add_u64 v[148:149], v[148:149], 0, v[164:165]
	v_lshl_add_u64 v[162:163], v[160:161], 2, s[14:15]
	v_mul_f32_e32 v159, 0x45800000, v151
	v_cndmask_b32_e32 v151, v151, v159, vcc
	v_mul_f32_e32 v166, 0x3d800000, v151
	v_pk_mul_f32 v[126:127], v[126:127], v[166:167] op_sel_hi:[1,0]
	v_pk_mul_f32 v[124:125], v[124:125], v[166:167] op_sel_hi:[1,0]
	v_pk_mul_f32 v[122:123], v[122:123], v[166:167] op_sel_hi:[1,0]
	v_pk_mul_f32 v[120:121], v[120:121], v[166:167] op_sel_hi:[1,0]
	v_pk_mul_f32 v[118:119], v[118:119], v[166:167] op_sel_hi:[1,0]
	v_pk_mul_f32 v[116:117], v[116:117], v[166:167] op_sel_hi:[1,0]
	v_pk_mul_f32 v[168:169], v[114:115], v[166:167] op_sel_hi:[1,0]
	v_pk_mul_f32 v[166:167], v[112:113], v[166:167] op_sel_hi:[1,0]
	v_cvt_pk_bf16_f32 v112, v124, v125
	v_cvt_pk_bf16_f32 v113, v126, v127
	v_cvt_pk_bf16_f32 v114, v120, v121
	v_cvt_pk_bf16_f32 v115, v122, v123
	global_store_dwordx4 v[148:149], v[112:115], off
	s_nop 1
	v_cvt_pk_bf16_f32 v112, v116, v117
	v_cvt_pk_bf16_f32 v113, v118, v119
	v_cvt_pk_bf16_f32 v114, v166, v167
	v_cvt_pk_bf16_f32 v115, v168, v169
	global_store_dwordx4 v[148:149], v[112:115], off offset:256
	s_nop 0
	s_nop 0
	v_fmamk_f32 v116, v200, 0x3a800000, v158
	v_mul_f32_e32 v117, 0x4b800000, v116
	v_cmp_gt_f32_e32 vcc, s75, v116
	v_lshlrev_b64 v[114:115], 11, v[160:161]
	v_or_b32_e32 v112, 32, v150
	v_cndmask_b32_e32 v116, v116, v117, vcc
	v_rsq_f32_e32 v118, v116
	v_lshl_add_u64 v[114:115], s[12:13], 0, v[114:115]
	v_ashrrev_i32_e32 v113, 31, v112
	v_lshl_add_u64 v[114:115], v[114:115], 0, v[164:165]
	v_mul_f32_e32 v119, 0x45800000, v118
	v_cndmask_b32_e32 v118, v118, v119, vcc
	v_mul_f32_e32 v118, 0x3d800000, v118
	v_pk_mul_f32 v[110:111], v[110:111], v[118:119] op_sel_hi:[1,0]
	v_pk_mul_f32 v[108:109], v[108:109], v[118:119] op_sel_hi:[1,0]
	v_pk_mul_f32 v[106:107], v[106:107], v[118:119] op_sel_hi:[1,0]
	v_pk_mul_f32 v[104:105], v[104:105], v[118:119] op_sel_hi:[1,0]
	v_pk_mul_f32 v[102:103], v[102:103], v[118:119] op_sel_hi:[1,0]
	v_pk_mul_f32 v[100:101], v[100:101], v[118:119] op_sel_hi:[1,0]
	v_pk_mul_f32 v[120:121], v[98:99], v[118:119] op_sel_hi:[1,0]
	v_pk_mul_f32 v[118:119], v[96:97], v[118:119] op_sel_hi:[1,0]
	v_cvt_pk_bf16_f32 v96, v108, v109
	v_cvt_pk_bf16_f32 v97, v110, v111
	v_cvt_pk_bf16_f32 v98, v104, v105
	v_cvt_pk_bf16_f32 v99, v106, v107
	v_lshl_add_u64 v[116:117], v[112:113], 2, s[14:15]
	global_store_dwordx4 v[114:115], v[96:99], off
	s_nop 1
	v_cvt_pk_bf16_f32 v96, v100, v101
	v_cvt_pk_bf16_f32 v97, v102, v103
	v_cvt_pk_bf16_f32 v98, v118, v119
	v_cvt_pk_bf16_f32 v99, v120, v121
	global_store_dwordx4 v[114:115], v[96:99], off offset:256
	s_nop 0
	s_nop 0
	v_fmamk_f32 v100, v201, 0x3a800000, v158
	v_mul_f32_e32 v101, 0x4b800000, v100
	v_cmp_gt_f32_e32 vcc, s75, v100
	v_lshlrev_b64 v[98:99], 11, v[112:113]
	v_or_b32_e32 v96, 48, v150
	v_cndmask_b32_e32 v100, v100, v101, vcc
	v_rsq_f32_e32 v102, v100
	v_lshl_add_u64 v[98:99], s[12:13], 0, v[98:99]
	v_ashrrev_i32_e32 v97, 31, v96
	v_lshl_add_u64 v[98:99], v[98:99], 0, v[164:165]
	v_mul_f32_e32 v103, 0x45800000, v102
	v_cndmask_b32_e32 v102, v102, v103, vcc
	v_mul_f32_e32 v102, 0x3d800000, v102
	v_pk_mul_f32 v[94:95], v[94:95], v[102:103] op_sel_hi:[1,0]
	v_pk_mul_f32 v[92:93], v[92:93], v[102:103] op_sel_hi:[1,0]
	v_pk_mul_f32 v[90:91], v[90:91], v[102:103] op_sel_hi:[1,0]
	v_pk_mul_f32 v[88:89], v[88:89], v[102:103] op_sel_hi:[1,0]
	v_pk_mul_f32 v[86:87], v[86:87], v[102:103] op_sel_hi:[1,0]
	v_pk_mul_f32 v[84:85], v[84:85], v[102:103] op_sel_hi:[1,0]
	v_pk_mul_f32 v[104:105], v[82:83], v[102:103] op_sel_hi:[1,0]
	v_pk_mul_f32 v[102:103], v[80:81], v[102:103] op_sel_hi:[1,0]
	v_cvt_pk_bf16_f32 v80, v92, v93
	v_cvt_pk_bf16_f32 v81, v94, v95
	v_cvt_pk_bf16_f32 v82, v88, v89
	v_cvt_pk_bf16_f32 v83, v90, v91
	v_lshl_add_u64 v[100:101], v[96:97], 2, s[14:15]
	global_store_dwordx4 v[98:99], v[80:83], off
	s_nop 1
	v_cvt_pk_bf16_f32 v80, v84, v85
	v_cvt_pk_bf16_f32 v81, v86, v87
	v_cvt_pk_bf16_f32 v82, v102, v103
	v_cvt_pk_bf16_f32 v83, v104, v105
	global_store_dwordx4 v[98:99], v[80:83], off offset:256
	s_nop 0
	s_nop 0
	v_fmamk_f32 v80, v202, 0x3a800000, v158
	v_mul_f32_e32 v81, 0x4b800000, v80
	v_cmp_gt_f32_e32 vcc, s75, v80
	s_nop 1
	v_cndmask_b32_e32 v80, v80, v81, vcc
	v_rsq_f32_e32 v82, v80
	v_lshlrev_b64 v[80:81], 11, v[96:97]
	v_lshl_add_u64 v[80:81], s[12:13], 0, v[80:81]
	v_lshl_add_u64 v[80:81], v[80:81], 0, v[164:165]
	v_mul_f32_e32 v83, 0x45800000, v82
	v_cndmask_b32_e32 v82, v82, v83, vcc
	v_mul_f32_e32 v82, 0x3d800000, v82
	v_pk_mul_f32 v[78:79], v[78:79], v[82:83] op_sel_hi:[1,0]
	v_pk_mul_f32 v[76:77], v[76:77], v[82:83] op_sel_hi:[1,0]
	v_pk_mul_f32 v[74:75], v[74:75], v[82:83] op_sel_hi:[1,0]
	v_pk_mul_f32 v[72:73], v[72:73], v[82:83] op_sel_hi:[1,0]
	v_pk_mul_f32 v[70:71], v[70:71], v[82:83] op_sel_hi:[1,0]
	v_pk_mul_f32 v[68:69], v[68:69], v[82:83] op_sel_hi:[1,0]
	v_pk_mul_f32 v[84:85], v[66:67], v[82:83] op_sel_hi:[1,0]
	v_pk_mul_f32 v[82:83], v[64:65], v[82:83] op_sel_hi:[1,0]
	v_cvt_pk_bf16_f32 v64, v76, v77
	v_cvt_pk_bf16_f32 v65, v78, v79
	v_cvt_pk_bf16_f32 v66, v72, v73
	v_cvt_pk_bf16_f32 v67, v74, v75
	global_store_dwordx4 v[80:81], v[64:67], off
	s_nop 1
	v_cvt_pk_bf16_f32 v64, v68, v69
	v_cvt_pk_bf16_f32 v65, v70, v71
	v_cvt_pk_bf16_f32 v66, v82, v83
	v_cvt_pk_bf16_f32 v67, v84, v85
	global_store_dwordx4 v[80:81], v[64:67], off offset:256
	s_nop 0
	s_nop 0
	v_lshl_add_u64 v[64:65], v[148:149], 0, s[8:9]
	s_nop 0
	v_fmamk_f32 v66, v203, 0x3a800000, v158
	v_mul_f32_e32 v67, 0x4b800000, v66
	v_cmp_gt_f32_e32 vcc, s75, v66
	s_nop 1
	v_cndmask_b32_e32 v66, v66, v67, vcc
	v_rsq_f32_e32 v68, v66
	v_add_co_u32_e64 v66, s[0:1], s76, v148
	v_mul_f32_e32 v69, 0x45800000, v68
	v_cndmask_b32_e32 v68, v68, v69, vcc
	v_mul_f32_e32 v68, 0x3d800000, v68
	v_addc_co_u32_e64 v67, s[0:1], 0, v149, s[0:1]
	v_pk_mul_f32 v[62:63], v[62:63], v[68:69] op_sel_hi:[1,0]
	v_pk_mul_f32 v[60:61], v[60:61], v[68:69] op_sel_hi:[1,0]
	v_pk_mul_f32 v[58:59], v[58:59], v[68:69] op_sel_hi:[1,0]
	v_pk_mul_f32 v[56:57], v[56:57], v[68:69] op_sel_hi:[1,0]
	v_pk_mul_f32 v[54:55], v[54:55], v[68:69] op_sel_hi:[1,0]
	v_pk_mul_f32 v[52:53], v[52:53], v[68:69] op_sel_hi:[1,0]
	v_pk_mul_f32 v[70:71], v[50:51], v[68:69] op_sel_hi:[1,0]
	v_pk_mul_f32 v[68:69], v[48:49], v[68:69] op_sel_hi:[1,0]
	v_cvt_pk_bf16_f32 v48, v60, v61
	v_cvt_pk_bf16_f32 v49, v62, v63
	v_cvt_pk_bf16_f32 v50, v56, v57
	v_cvt_pk_bf16_f32 v51, v58, v59
	global_store_dwordx4 v[66:67], v[48:51], off
	s_nop 1
	v_cvt_pk_bf16_f32 v48, v52, v53
	v_cvt_pk_bf16_f32 v49, v54, v55
	v_cvt_pk_bf16_f32 v50, v68, v69
	v_cvt_pk_bf16_f32 v51, v70, v71
	global_store_dwordx4 v[64:65], v[48:51], off offset:256
	s_nop 0
	s_nop 0
	v_lshl_add_u64 v[48:49], v[148:149], 0, s[36:37]
	s_nop 0
	v_fmamk_f32 v50, v204, 0x3a800000, v158
	v_mul_f32_e32 v51, 0x4b800000, v50
	v_cmp_gt_f32_e32 vcc, s75, v50
	s_nop 1
	v_cndmask_b32_e32 v50, v50, v51, vcc
	v_rsq_f32_e32 v52, v50
	v_add_co_u32_e64 v50, s[0:1], s77, v148
	v_mul_f32_e32 v53, 0x45800000, v52
	v_cndmask_b32_e32 v52, v52, v53, vcc
	v_mul_f32_e32 v52, 0x3d800000, v52
	v_addc_co_u32_e64 v51, s[0:1], 0, v149, s[0:1]
	v_pk_mul_f32 v[46:47], v[46:47], v[52:53] op_sel_hi:[1,0]
	v_pk_mul_f32 v[44:45], v[44:45], v[52:53] op_sel_hi:[1,0]
	v_pk_mul_f32 v[42:43], v[42:43], v[52:53] op_sel_hi:[1,0]
	v_pk_mul_f32 v[40:41], v[40:41], v[52:53] op_sel_hi:[1,0]
	v_pk_mul_f32 v[38:39], v[38:39], v[52:53] op_sel_hi:[1,0]
	v_pk_mul_f32 v[36:37], v[36:37], v[52:53] op_sel_hi:[1,0]
	v_pk_mul_f32 v[54:55], v[34:35], v[52:53] op_sel_hi:[1,0]
	v_pk_mul_f32 v[52:53], v[32:33], v[52:53] op_sel_hi:[1,0]
	v_cvt_pk_bf16_f32 v32, v44, v45
	v_cvt_pk_bf16_f32 v33, v46, v47
	v_cvt_pk_bf16_f32 v34, v40, v41
	v_cvt_pk_bf16_f32 v35, v42, v43
	global_store_dwordx4 v[50:51], v[32:35], off
	s_nop 1
	v_cvt_pk_bf16_f32 v32, v36, v37
	v_cvt_pk_bf16_f32 v33, v38, v39
	v_cvt_pk_bf16_f32 v34, v52, v53
	v_cvt_pk_bf16_f32 v35, v54, v55
	global_store_dwordx4 v[48:49], v[32:35], off offset:256
	s_nop 0
	s_nop 0
	v_lshl_add_u64 v[32:33], v[148:149], 0, s[38:39]
	s_nop 0
	v_fmamk_f32 v34, v205, 0x3a800000, v158
	v_mul_f32_e32 v35, 0x4b800000, v34
	v_cmp_gt_f32_e32 vcc, s75, v34
	s_nop 1
	v_cndmask_b32_e32 v34, v34, v35, vcc
	v_rsq_f32_e32 v36, v34
	v_add_co_u32_e64 v34, s[0:1], s78, v148
	v_mul_f32_e32 v37, 0x45800000, v36
	v_cndmask_b32_e32 v36, v36, v37, vcc
	v_mul_f32_e32 v36, 0x3d800000, v36
	v_addc_co_u32_e64 v35, s[0:1], 0, v149, s[0:1]
	v_pk_mul_f32 v[30:31], v[30:31], v[36:37] op_sel_hi:[1,0]
	v_pk_mul_f32 v[28:29], v[28:29], v[36:37] op_sel_hi:[1,0]
	v_pk_mul_f32 v[26:27], v[26:27], v[36:37] op_sel_hi:[1,0]
	v_pk_mul_f32 v[24:25], v[24:25], v[36:37] op_sel_hi:[1,0]
	v_pk_mul_f32 v[22:23], v[22:23], v[36:37] op_sel_hi:[1,0]
	v_pk_mul_f32 v[20:21], v[20:21], v[36:37] op_sel_hi:[1,0]
	v_pk_mul_f32 v[38:39], v[18:19], v[36:37] op_sel_hi:[1,0]
	v_pk_mul_f32 v[36:37], v[16:17], v[36:37] op_sel_hi:[1,0]
	v_cvt_pk_bf16_f32 v16, v28, v29
	v_cvt_pk_bf16_f32 v17, v30, v31
	v_cvt_pk_bf16_f32 v18, v24, v25
	v_cvt_pk_bf16_f32 v19, v26, v27
	global_store_dwordx4 v[34:35], v[16:19], off
	s_andn2_b64 vcc, exec, s[2:3]
	s_nop 0
	v_cvt_pk_bf16_f32 v16, v20, v21
	v_cvt_pk_bf16_f32 v17, v22, v23
	v_cvt_pk_bf16_f32 v18, v36, v37
	v_cvt_pk_bf16_f32 v19, v38, v39
	global_store_dwordx4 v[32:33], v[16:19], off offset:256
	s_nop 0
	s_nop 0
	v_lshl_add_u64 v[16:17], v[148:149], 0, s[44:45]
	s_nop 0
	v_fmamk_f32 v18, v206, 0x3a800000, v158
	v_mul_f32_e32 v19, 0x4b800000, v18
	v_cmp_gt_f32_e64 s[0:1], s75, v18
	s_nop 1
	v_cndmask_b32_e64 v18, v18, v19, s[0:1]
	v_rsq_f32_e32 v20, v18
	v_add_co_u32_e64 v18, s[2:3], s79, v148
	v_mul_f32_e32 v21, 0x45800000, v20
	v_cndmask_b32_e64 v20, v20, v21, s[0:1]
	v_mul_f32_e32 v20, 0x3d800000, v20
	v_addc_co_u32_e64 v19, s[2:3], 0, v149, s[2:3]
	v_pk_mul_f32 v[14:15], v[14:15], v[20:21] op_sel_hi:[1,0]
	v_pk_mul_f32 v[12:13], v[12:13], v[20:21] op_sel_hi:[1,0]
	v_pk_mul_f32 v[10:11], v[10:11], v[20:21] op_sel_hi:[1,0]
	v_pk_mul_f32 v[8:9], v[8:9], v[20:21] op_sel_hi:[1,0]
	v_pk_mul_f32 v[6:7], v[6:7], v[20:21] op_sel_hi:[1,0]
	v_pk_mul_f32 v[4:5], v[4:5], v[20:21] op_sel_hi:[1,0]
	v_pk_mul_f32 v[22:23], v[2:3], v[20:21] op_sel_hi:[1,0]
	v_pk_mul_f32 v[20:21], v[0:1], v[20:21] op_sel_hi:[1,0]
	v_cvt_pk_bf16_f32 v0, v12, v13
	v_cvt_pk_bf16_f32 v1, v14, v15
	v_cvt_pk_bf16_f32 v2, v8, v9
	v_cvt_pk_bf16_f32 v3, v10, v11
	s_mov_b64 s[0:1], -1
	global_store_dwordx4 v[18:19], v[0:3], off
	s_nop 1
	v_cvt_pk_bf16_f32 v0, v4, v5
	v_cvt_pk_bf16_f32 v1, v6, v7
	v_cvt_pk_bf16_f32 v2, v20, v21
	v_cvt_pk_bf16_f32 v3, v22, v23
	global_store_dwordx4 v[16:17], v[0:3], off offset:256
	s_cbranch_vccnz .LBB0_1078
	s_andn2_b64 vcc, exec, s[10:11]
	s_cbranch_vccnz .LBB0_1077
	s_barrier
	s_branch .LBB0_1077

.LBB0_1249:
	v_lshl_add_u32 v148, s44, 8, v152
	v_ashrrev_i32_e32 v149, 31, v148
	v_lshl_or_b32 v146, s42, 8, v154
	v_lshlrev_b64 v[160:161], 11, v[148:149]
	v_ashrrev_i32_e32 v147, 31, v146
	v_lshl_add_u64 v[160:161], s[10:11], 0, v[160:161]
	v_lshl_add_u64 v[164:165], v[146:147], 1, v[160:161]
	v_mov_b32_e32 v240, v164
	v_mov_b32_e32 v241, v165
	global_load_dwordx4 v[176:179], v[164:165], off
	global_load_dwordx4 v[180:183], v[164:165], off offset:256
	s_mov_b64 s[98:99], 0x8000
	v_lshl_add_u64 v[242:243], v[240:241], 0, s[98:99]
	global_load_dwordx4 v[184:187], v[242:243], off
	global_load_dwordx4 v[188:191], v[242:243], off offset:256
	s_mov_b64 s[98:99], 0x10000
	v_lshl_add_u64 v[242:243], v[240:241], 0, s[98:99]
	global_load_dwordx4 v[192:195], v[242:243], off
	global_load_dwordx4 v[196:199], v[242:243], off offset:256
	s_mov_b64 s[98:99], 0x18000
	v_lshl_add_u64 v[242:243], v[240:241], 0, s[98:99]
	global_load_dwordx4 v[200:203], v[242:243], off
	global_load_dwordx4 v[204:207], v[242:243], off offset:256
	s_mov_b64 s[98:99], 0x40000
	v_lshl_add_u64 v[242:243], v[240:241], 0, s[98:99]
	global_load_dwordx4 v[208:211], v[242:243], off
	global_load_dwordx4 v[212:215], v[242:243], off offset:256
	s_mov_b64 s[98:99], 0x48000
	v_lshl_add_u64 v[242:243], v[240:241], 0, s[98:99]
	global_load_dwordx4 v[216:219], v[242:243], off
	global_load_dwordx4 v[220:223], v[242:243], off offset:256
	s_mov_b64 s[98:99], 0x50000
	v_lshl_add_u64 v[242:243], v[240:241], 0, s[98:99]
	global_load_dwordx4 v[224:227], v[242:243], off
	global_load_dwordx4 v[228:231], v[242:243], off offset:256
	s_mov_b64 s[98:99], 0x58000
	v_lshl_add_u64 v[242:243], v[240:241], 0, s[98:99]
	global_load_dwordx4 v[232:235], v[242:243], off
	global_load_dwordx4 v[236:239], v[242:243], off offset:256
	s_nop 0
	v_and_b32_e32 v170, 64, v158
	v_add_u32_e32 v170, 64, v170
	v_xor_b32_e32 v171, 32, v158
	s_waitcnt vmcnt(14)
	v_lshlrev_b32_e32 v159, 16, v176
	v_and_b32_e32 v160, 0xffff0000, v176
	v_lshlrev_b32_e32 v166, 16, v177
	v_and_b32_e32 v161, 0xffff0000, v177
	v_lshlrev_b32_e32 v167, 16, v178
	v_and_b32_e32 v162, 0xffff0000, v178
	v_lshlrev_b32_e32 v168, 16, v179
	v_and_b32_e32 v163, 0xffff0000, v179
	v_add_f32_e32 v159, v124, v159
	v_add_f32_e32 v169, v125, v160
	v_add_f32_e32 v126, v126, v166
	v_add_f32_e32 v127, v127, v161
	v_add_f32_e32 v166, v120, v167
	v_add_f32_e32 v121, v121, v162
	v_add_f32_e32 v167, v122, v168
	v_add_f32_e32 v168, v123, v163
	v_cvt_pk_bf16_f32 v122, v159, v169
	v_cvt_pk_bf16_f32 v123, v126, v127
	v_cvt_pk_bf16_f32 v124, v166, v121
	v_cvt_pk_bf16_f32 v125, v167, v168
	s_nop 0
	v_mul_f32_e32 v169, v169, v169
	v_mul_f32_e32 v127, v127, v127
	v_mul_f32_e32 v121, v121, v121
	v_mul_f32_e32 v168, v168, v168
	v_fmac_f32_e32 v169, v159, v159
	v_fmac_f32_e32 v127, v126, v126
	v_fmac_f32_e32 v121, v166, v166
	v_fmac_f32_e32 v168, v167, v167
	v_add_f32_e32 v126, v169, v127
	v_add_f32_e32 v121, v121, v168
	v_add_f32_e32 v121, v126, v121
	v_xor_b32_e32 v120, 16, v158
	v_cmp_lt_i32_e32 vcc, v120, v170
	global_store_dwordx4 v[164:165], v[122:125], off
	s_nop 0
	v_lshlrev_b32_e32 v126, 16, v180
	v_and_b32_e32 v127, 0xffff0000, v180
	v_lshlrev_b32_e32 v159, 16, v181
	v_and_b32_e32 v160, 0xffff0000, v181
	v_lshlrev_b32_e32 v161, 16, v182
	v_and_b32_e32 v162, 0xffff0000, v182
	v_lshlrev_b32_e32 v166, 16, v183
	v_and_b32_e32 v163, 0xffff0000, v183
	v_add_f32_e32 v117, v117, v127
	v_add_f32_e32 v119, v119, v160
	v_add_f32_e32 v127, v113, v162
	v_add_f32_e32 v115, v115, v163
	v_add_f32_e32 v116, v116, v126
	v_add_f32_e32 v118, v118, v159
	v_add_f32_e32 v126, v112, v161
	v_add_f32_e32 v159, v114, v166
	v_mul_f32_e32 v112, v117, v117
	v_mul_f32_e32 v113, v119, v119
	v_mul_f32_e32 v114, v127, v127
	v_mul_f32_e32 v160, v115, v115
	v_fmac_f32_e32 v112, v116, v116
	v_fmac_f32_e32 v113, v118, v118
	v_fmac_f32_e32 v114, v126, v126
	v_fmac_f32_e32 v160, v159, v159
	v_add_f32_e32 v112, v112, v113
	v_add_f32_e32 v113, v114, v160
	v_cndmask_b32_e32 v120, v158, v120, vcc
	v_add_f32_e32 v112, v112, v113
	v_lshlrev_b32_e32 v120, 2, v120
	v_add_f32_e32 v112, v121, v112
	ds_bpermute_b32 v113, v120, v112
	v_cmp_lt_i32_e32 vcc, v171, v170
	v_cvt_pk_bf16_f32 v116, v116, v117
	v_cvt_pk_bf16_f32 v117, v118, v119
	v_cvt_pk_bf16_f32 v118, v126, v127
	s_waitcnt lgkmcnt(0)
	v_add_f32_e32 v112, v112, v113
	v_cvt_pk_bf16_f32 v119, v159, v115
	v_cndmask_b32_e32 v114, v158, v171, vcc
	v_lshlrev_b32_e32 v114, 2, v114
	ds_bpermute_b32 v113, v114, v112
	global_store_dwordx4 v[164:165], v[116:119], off offset:256
	s_and_saveexec_b64 s[20:21], s[2:3]
	s_cbranch_execz .LBB0_1251
	v_lshl_add_u64 v[116:117], v[148:149], 2, s[12:13]
	s_waitcnt lgkmcnt(0)
	v_add_f32_e32 v112, v112, v113
	global_atomic_add_f32 v[116:117], v112, off
.LBB0_1251:
	s_or_b64 exec, exec, s[20:21]
	v_or_b32_e32 v112, 16, v148
	s_waitcnt lgkmcnt(0)
	v_ashrrev_i32_e32 v113, 31, v112
	v_lshlrev_b64 v[116:117], 11, v[112:113]
	v_lshl_add_u64 v[116:117], s[10:11], 0, v[116:117]
	v_lshl_add_u64 v[122:123], v[146:147], 1, v[116:117]
	s_nop 0
	s_waitcnt vmcnt(14)
	v_lshlrev_b32_e32 v115, 16, v184
	v_and_b32_e32 v116, 0xffff0000, v184
	v_lshlrev_b32_e32 v121, 16, v185
	v_and_b32_e32 v117, 0xffff0000, v185
	v_lshlrev_b32_e32 v124, 16, v186
	v_and_b32_e32 v118, 0xffff0000, v186
	v_lshlrev_b32_e32 v125, 16, v187
	v_and_b32_e32 v119, 0xffff0000, v187
	v_add_f32_e32 v115, v108, v115
	v_add_f32_e32 v116, v109, v116
	v_add_f32_e32 v121, v110, v121
	v_add_f32_e32 v117, v111, v117
	v_add_f32_e32 v124, v104, v124
	v_add_f32_e32 v118, v105, v118
	v_add_f32_e32 v125, v106, v125
	v_add_f32_e32 v119, v107, v119
	v_cvt_pk_bf16_f32 v104, v115, v116
	v_cvt_pk_bf16_f32 v105, v121, v117
	v_cvt_pk_bf16_f32 v106, v124, v118
	v_cvt_pk_bf16_f32 v107, v125, v119
	s_nop 0
	v_mul_f32_e32 v116, v116, v116
	v_mul_f32_e32 v117, v117, v117
	v_mul_f32_e32 v118, v118, v118
	v_mul_f32_e32 v119, v119, v119
	v_fmac_f32_e32 v116, v115, v115
	v_fmac_f32_e32 v117, v121, v121
	v_fmac_f32_e32 v118, v124, v124
	v_fmac_f32_e32 v119, v125, v125
	v_add_f32_e32 v115, v116, v117
	v_add_f32_e32 v116, v118, v119
	v_add_f32_e32 v115, v115, v116
	global_store_dwordx4 v[122:123], v[104:107], off
	s_nop 0
	v_lshlrev_b32_e32 v116, 16, v188
	v_and_b32_e32 v108, 0xffff0000, v188
	v_lshlrev_b32_e32 v117, 16, v189
	v_and_b32_e32 v109, 0xffff0000, v189
	v_lshlrev_b32_e32 v118, 16, v190
	v_and_b32_e32 v110, 0xffff0000, v190
	v_lshlrev_b32_e32 v119, 16, v191
	v_and_b32_e32 v111, 0xffff0000, v191
	v_add_f32_e32 v101, v101, v108
	v_add_f32_e32 v103, v103, v109
	v_add_f32_e32 v109, v97, v110
	v_add_f32_e32 v111, v99, v111
	v_add_f32_e32 v100, v100, v116
	v_add_f32_e32 v102, v102, v117
	v_add_f32_e32 v108, v96, v118
	v_add_f32_e32 v110, v98, v119
	v_mul_f32_e32 v96, v101, v101
	v_mul_f32_e32 v97, v103, v103
	v_mul_f32_e32 v98, v109, v109
	v_mul_f32_e32 v99, v111, v111
	v_fmac_f32_e32 v96, v100, v100
	v_fmac_f32_e32 v97, v102, v102
	v_fmac_f32_e32 v98, v108, v108
	v_fmac_f32_e32 v99, v110, v110
	v_add_f32_e32 v96, v96, v97
	v_add_f32_e32 v97, v98, v99
	v_add_f32_e32 v96, v96, v97
	v_add_f32_e32 v96, v115, v96
	ds_bpermute_b32 v97, v120, v96
	v_cvt_pk_bf16_f32 v98, v100, v101
	v_cvt_pk_bf16_f32 v99, v102, v103
	v_cvt_pk_bf16_f32 v100, v108, v109
	v_cvt_pk_bf16_f32 v101, v110, v111
	s_waitcnt lgkmcnt(0)
	v_add_f32_e32 v96, v96, v97
	ds_bpermute_b32 v97, v114, v96
	global_store_dwordx4 v[122:123], v[98:101], off offset:256
	s_and_saveexec_b64 s[20:21], s[2:3]
	s_cbranch_execz .LBB0_1253
	v_lshl_add_u64 v[98:99], v[112:113], 2, s[12:13]
	s_waitcnt lgkmcnt(0)
	v_add_f32_e32 v96, v96, v97
	global_atomic_add_f32 v[98:99], v96, off
.LBB0_1253:
	s_or_b64 exec, exec, s[20:21]
	v_or_b32_e32 v96, 32, v148
	s_waitcnt lgkmcnt(0)
	v_ashrrev_i32_e32 v97, 31, v96
	v_lshlrev_b64 v[98:99], 11, v[96:97]
	v_lshl_add_u64 v[98:99], s[10:11], 0, v[98:99]
	v_lshl_add_u64 v[102:103], v[146:147], 1, v[98:99]
	s_nop 0
	s_waitcnt vmcnt(14)
	v_lshlrev_b32_e32 v104, 16, v192
	v_and_b32_e32 v98, 0xffff0000, v192
	v_lshlrev_b32_e32 v105, 16, v193
	v_and_b32_e32 v99, 0xffff0000, v193
	v_lshlrev_b32_e32 v106, 16, v194
	v_and_b32_e32 v100, 0xffff0000, v194
	v_lshlrev_b32_e32 v107, 16, v195
	v_and_b32_e32 v101, 0xffff0000, v195
	v_add_f32_e32 v104, v92, v104
	v_add_f32_e32 v98, v93, v98
	v_add_f32_e32 v105, v94, v105
	v_add_f32_e32 v99, v95, v99
	v_add_f32_e32 v106, v88, v106
	v_add_f32_e32 v100, v89, v100
	v_add_f32_e32 v107, v90, v107
	v_add_f32_e32 v101, v91, v101
	v_cvt_pk_bf16_f32 v88, v104, v98
	v_cvt_pk_bf16_f32 v89, v105, v99
	v_cvt_pk_bf16_f32 v90, v106, v100
	v_cvt_pk_bf16_f32 v91, v107, v101
	s_nop 0
	v_mul_f32_e32 v98, v98, v98
	v_mul_f32_e32 v99, v99, v99
	v_mul_f32_e32 v100, v100, v100
	v_mul_f32_e32 v101, v101, v101
	v_fmac_f32_e32 v98, v104, v104
	v_fmac_f32_e32 v99, v105, v105
	v_fmac_f32_e32 v100, v106, v106
	v_fmac_f32_e32 v101, v107, v107
	v_add_f32_e32 v98, v98, v99
	v_add_f32_e32 v99, v100, v101
	v_add_f32_e32 v98, v98, v99
	global_store_dwordx4 v[102:103], v[88:91], off
	s_nop 0
	v_lshlrev_b32_e32 v99, 16, v196
	v_and_b32_e32 v92, 0xffff0000, v196
	v_lshlrev_b32_e32 v100, 16, v197
	v_and_b32_e32 v93, 0xffff0000, v197
	v_lshlrev_b32_e32 v101, 16, v198
	v_and_b32_e32 v94, 0xffff0000, v198
	v_lshlrev_b32_e32 v104, 16, v199
	v_and_b32_e32 v95, 0xffff0000, v199
	v_add_f32_e32 v85, v85, v92
	v_add_f32_e32 v87, v87, v93
	v_add_f32_e32 v93, v81, v94
	v_add_f32_e32 v95, v83, v95
	v_add_f32_e32 v84, v84, v99
	v_add_f32_e32 v86, v86, v100
	v_add_f32_e32 v92, v80, v101
	v_add_f32_e32 v94, v82, v104
	v_mul_f32_e32 v80, v85, v85
	v_mul_f32_e32 v81, v87, v87
	v_mul_f32_e32 v82, v93, v93
	v_mul_f32_e32 v83, v95, v95
	v_fmac_f32_e32 v80, v84, v84
	v_fmac_f32_e32 v81, v86, v86
	v_fmac_f32_e32 v82, v92, v92
	v_fmac_f32_e32 v83, v94, v94
	v_add_f32_e32 v80, v80, v81
	v_add_f32_e32 v81, v82, v83
	v_add_f32_e32 v80, v80, v81
	v_add_f32_e32 v80, v98, v80
	ds_bpermute_b32 v81, v120, v80
	v_cvt_pk_bf16_f32 v82, v84, v85
	v_cvt_pk_bf16_f32 v83, v86, v87
	v_cvt_pk_bf16_f32 v84, v92, v93
	v_cvt_pk_bf16_f32 v85, v94, v95
	s_waitcnt lgkmcnt(0)
	v_add_f32_e32 v80, v80, v81
	ds_bpermute_b32 v81, v114, v80
	global_store_dwordx4 v[102:103], v[82:85], off offset:256
	s_and_saveexec_b64 s[20:21], s[2:3]
	s_cbranch_execz .LBB0_1255
	v_lshl_add_u64 v[82:83], v[96:97], 2, s[12:13]
	s_waitcnt lgkmcnt(0)
	v_add_f32_e32 v80, v80, v81
	global_atomic_add_f32 v[82:83], v80, off
.LBB0_1255:
	s_or_b64 exec, exec, s[20:21]
	v_or_b32_e32 v80, 48, v148
	s_waitcnt lgkmcnt(0)
	v_ashrrev_i32_e32 v81, 31, v80
	v_lshlrev_b64 v[82:83], 11, v[80:81]
	v_lshl_add_u64 v[82:83], s[10:11], 0, v[82:83]
	v_lshl_add_u64 v[86:87], v[146:147], 1, v[82:83]
	s_nop 0
	s_waitcnt vmcnt(14)
	v_lshlrev_b32_e32 v88, 16, v200
	v_and_b32_e32 v82, 0xffff0000, v200
	v_lshlrev_b32_e32 v89, 16, v201
	v_and_b32_e32 v83, 0xffff0000, v201
	v_lshlrev_b32_e32 v90, 16, v202
	v_and_b32_e32 v84, 0xffff0000, v202
	v_lshlrev_b32_e32 v91, 16, v203
	v_and_b32_e32 v85, 0xffff0000, v203
	v_add_f32_e32 v88, v76, v88
	v_add_f32_e32 v82, v77, v82
	v_add_f32_e32 v89, v78, v89
	v_add_f32_e32 v83, v79, v83
	v_add_f32_e32 v90, v72, v90
	v_add_f32_e32 v84, v73, v84
	v_add_f32_e32 v91, v74, v91
	v_add_f32_e32 v85, v75, v85
	v_cvt_pk_bf16_f32 v72, v88, v82
	v_cvt_pk_bf16_f32 v73, v89, v83
	v_cvt_pk_bf16_f32 v74, v90, v84
	v_cvt_pk_bf16_f32 v75, v91, v85
	s_nop 0
	v_mul_f32_e32 v82, v82, v82
	v_mul_f32_e32 v83, v83, v83
	v_mul_f32_e32 v84, v84, v84
	v_mul_f32_e32 v85, v85, v85
	v_fmac_f32_e32 v82, v88, v88
	v_fmac_f32_e32 v83, v89, v89
	v_fmac_f32_e32 v84, v90, v90
	v_fmac_f32_e32 v85, v91, v91
	v_add_f32_e32 v82, v82, v83
	v_add_f32_e32 v83, v84, v85
	v_add_f32_e32 v82, v82, v83
	global_store_dwordx4 v[86:87], v[72:75], off
	s_nop 0
	v_lshlrev_b32_e32 v83, 16, v204
	v_and_b32_e32 v76, 0xffff0000, v204
	v_lshlrev_b32_e32 v84, 16, v205
	v_and_b32_e32 v77, 0xffff0000, v205
	v_lshlrev_b32_e32 v85, 16, v206
	v_and_b32_e32 v78, 0xffff0000, v206
	v_lshlrev_b32_e32 v88, 16, v207
	v_and_b32_e32 v79, 0xffff0000, v207
	v_add_f32_e32 v69, v69, v76
	v_add_f32_e32 v71, v71, v77
	v_add_f32_e32 v77, v65, v78
	v_add_f32_e32 v79, v67, v79
	v_add_f32_e32 v68, v68, v83
	v_add_f32_e32 v70, v70, v84
	v_add_f32_e32 v76, v64, v85
	v_add_f32_e32 v78, v66, v88
	v_mul_f32_e32 v64, v69, v69
	v_mul_f32_e32 v65, v71, v71
	v_mul_f32_e32 v66, v77, v77
	v_mul_f32_e32 v67, v79, v79
	v_fmac_f32_e32 v64, v68, v68
	v_fmac_f32_e32 v65, v70, v70
	v_fmac_f32_e32 v66, v76, v76
	v_fmac_f32_e32 v67, v78, v78
	v_add_f32_e32 v64, v64, v65
	v_add_f32_e32 v65, v66, v67
	v_add_f32_e32 v64, v64, v65
	v_add_f32_e32 v64, v82, v64
	ds_bpermute_b32 v65, v120, v64
	v_cvt_pk_bf16_f32 v66, v68, v69
	v_cvt_pk_bf16_f32 v67, v70, v71
	v_cvt_pk_bf16_f32 v68, v76, v77
	v_cvt_pk_bf16_f32 v69, v78, v79
	s_waitcnt lgkmcnt(0)
	v_add_f32_e32 v64, v64, v65
	ds_bpermute_b32 v65, v114, v64
	global_store_dwordx4 v[86:87], v[66:69], off offset:256
	s_and_saveexec_b64 s[20:21], s[2:3]
	s_cbranch_execz .LBB0_1257
	v_lshl_add_u64 v[66:67], v[80:81], 2, s[12:13]
	s_waitcnt lgkmcnt(0)
	v_add_f32_e32 v64, v64, v65
	global_atomic_add_f32 v[66:67], v64, off
.LBB0_1257:
	s_or_b64 exec, exec, s[20:21]
	v_add_u32_e32 v64, 0x80, v148
	s_waitcnt lgkmcnt(0)
	v_ashrrev_i32_e32 v65, 31, v64
	v_lshlrev_b64 v[66:67], 11, v[64:65]
	v_lshl_add_u64 v[66:67], s[10:11], 0, v[66:67]
	v_lshl_add_u64 v[70:71], v[146:147], 1, v[66:67]
	s_nop 0
	s_waitcnt vmcnt(14)
	v_lshlrev_b32_e32 v72, 16, v208
	v_and_b32_e32 v66, 0xffff0000, v208
	v_lshlrev_b32_e32 v73, 16, v209
	v_and_b32_e32 v67, 0xffff0000, v209
	v_lshlrev_b32_e32 v74, 16, v210
	v_and_b32_e32 v68, 0xffff0000, v210
	v_lshlrev_b32_e32 v75, 16, v211
	v_and_b32_e32 v69, 0xffff0000, v211
	v_add_f32_e32 v72, v60, v72
	v_add_f32_e32 v66, v61, v66
	v_add_f32_e32 v73, v62, v73
	v_add_f32_e32 v67, v63, v67
	v_add_f32_e32 v74, v56, v74
	v_add_f32_e32 v68, v57, v68
	v_add_f32_e32 v75, v58, v75
	v_add_f32_e32 v69, v59, v69
	v_cvt_pk_bf16_f32 v56, v72, v66
	v_cvt_pk_bf16_f32 v57, v73, v67
	v_cvt_pk_bf16_f32 v58, v74, v68
	v_cvt_pk_bf16_f32 v59, v75, v69
	s_nop 0
	v_mul_f32_e32 v66, v66, v66
	v_mul_f32_e32 v67, v67, v67
	v_mul_f32_e32 v68, v68, v68
	v_mul_f32_e32 v69, v69, v69
	v_fmac_f32_e32 v66, v72, v72
	v_fmac_f32_e32 v67, v73, v73
	v_fmac_f32_e32 v68, v74, v74
	v_fmac_f32_e32 v69, v75, v75
	v_add_f32_e32 v66, v66, v67
	v_add_f32_e32 v67, v68, v69
	v_add_f32_e32 v66, v66, v67
	global_store_dwordx4 v[70:71], v[56:59], off
	s_nop 0
	v_lshlrev_b32_e32 v67, 16, v212
	v_and_b32_e32 v60, 0xffff0000, v212
	v_lshlrev_b32_e32 v68, 16, v213
	v_and_b32_e32 v61, 0xffff0000, v213
	v_lshlrev_b32_e32 v69, 16, v214
	v_and_b32_e32 v62, 0xffff0000, v214
	v_lshlrev_b32_e32 v72, 16, v215
	v_and_b32_e32 v63, 0xffff0000, v215
	v_add_f32_e32 v53, v53, v60
	v_add_f32_e32 v55, v55, v61
	v_add_f32_e32 v61, v49, v62
	v_add_f32_e32 v63, v51, v63
	v_add_f32_e32 v52, v52, v67
	v_add_f32_e32 v54, v54, v68
	v_add_f32_e32 v60, v48, v69
	v_add_f32_e32 v62, v50, v72
	v_mul_f32_e32 v48, v53, v53
	v_mul_f32_e32 v49, v55, v55
	v_mul_f32_e32 v50, v61, v61
	v_mul_f32_e32 v51, v63, v63
	v_fmac_f32_e32 v48, v52, v52
	v_fmac_f32_e32 v49, v54, v54
	v_fmac_f32_e32 v50, v60, v60
	v_fmac_f32_e32 v51, v62, v62
	v_add_f32_e32 v48, v48, v49
	v_add_f32_e32 v49, v50, v51
	v_add_f32_e32 v48, v48, v49
	v_add_f32_e32 v48, v66, v48
	ds_bpermute_b32 v49, v120, v48
	v_cvt_pk_bf16_f32 v50, v52, v53
	v_cvt_pk_bf16_f32 v51, v54, v55
	v_cvt_pk_bf16_f32 v52, v60, v61
	v_cvt_pk_bf16_f32 v53, v62, v63
	s_waitcnt lgkmcnt(0)
	v_add_f32_e32 v48, v48, v49
	ds_bpermute_b32 v49, v114, v48
	global_store_dwordx4 v[70:71], v[50:53], off offset:256
	s_and_saveexec_b64 s[20:21], s[2:3]
	s_cbranch_execz .LBB0_1259
	v_lshl_add_u64 v[50:51], v[64:65], 2, s[12:13]
	s_waitcnt lgkmcnt(0)
	v_add_f32_e32 v48, v48, v49
	global_atomic_add_f32 v[50:51], v48, off
.LBB0_1259:
	s_or_b64 exec, exec, s[20:21]
	v_add_u32_e32 v48, 0x90, v148
	s_waitcnt lgkmcnt(0)
	v_ashrrev_i32_e32 v49, 31, v48
	v_lshlrev_b64 v[50:51], 11, v[48:49]
	v_lshl_add_u64 v[50:51], s[10:11], 0, v[50:51]
	v_lshl_add_u64 v[54:55], v[146:147], 1, v[50:51]
	s_nop 0
	s_waitcnt vmcnt(14)
	v_lshlrev_b32_e32 v56, 16, v216
	v_and_b32_e32 v50, 0xffff0000, v216
	v_lshlrev_b32_e32 v57, 16, v217
	v_and_b32_e32 v51, 0xffff0000, v217
	v_lshlrev_b32_e32 v58, 16, v218
	v_and_b32_e32 v52, 0xffff0000, v218
	v_lshlrev_b32_e32 v59, 16, v219
	v_and_b32_e32 v53, 0xffff0000, v219
	v_add_f32_e32 v56, v44, v56
	v_add_f32_e32 v50, v45, v50
	v_add_f32_e32 v57, v46, v57
	v_add_f32_e32 v51, v47, v51
	v_add_f32_e32 v58, v40, v58
	v_add_f32_e32 v52, v41, v52
	v_add_f32_e32 v59, v42, v59
	v_add_f32_e32 v53, v43, v53
	v_cvt_pk_bf16_f32 v40, v56, v50
	v_cvt_pk_bf16_f32 v41, v57, v51
	v_cvt_pk_bf16_f32 v42, v58, v52
	v_cvt_pk_bf16_f32 v43, v59, v53
	s_nop 0
	v_mul_f32_e32 v50, v50, v50
	v_mul_f32_e32 v51, v51, v51
	v_mul_f32_e32 v52, v52, v52
	v_mul_f32_e32 v53, v53, v53
	v_fmac_f32_e32 v50, v56, v56
	v_fmac_f32_e32 v51, v57, v57
	v_fmac_f32_e32 v52, v58, v58
	v_fmac_f32_e32 v53, v59, v59
	v_add_f32_e32 v50, v50, v51
	v_add_f32_e32 v51, v52, v53
	v_add_f32_e32 v50, v50, v51
	global_store_dwordx4 v[54:55], v[40:43], off
	s_nop 0
	v_lshlrev_b32_e32 v51, 16, v220
	v_and_b32_e32 v44, 0xffff0000, v220
	v_lshlrev_b32_e32 v52, 16, v221
	v_and_b32_e32 v45, 0xffff0000, v221
	v_lshlrev_b32_e32 v53, 16, v222
	v_and_b32_e32 v46, 0xffff0000, v222
	v_lshlrev_b32_e32 v56, 16, v223
	v_and_b32_e32 v47, 0xffff0000, v223
	v_add_f32_e32 v37, v37, v44
	v_add_f32_e32 v39, v39, v45
	v_add_f32_e32 v45, v33, v46
	v_add_f32_e32 v47, v35, v47
	v_add_f32_e32 v36, v36, v51
	v_add_f32_e32 v38, v38, v52
	v_add_f32_e32 v44, v32, v53
	v_add_f32_e32 v46, v34, v56
	v_mul_f32_e32 v32, v37, v37
	v_mul_f32_e32 v33, v39, v39
	v_mul_f32_e32 v34, v45, v45
	v_mul_f32_e32 v35, v47, v47
	v_fmac_f32_e32 v32, v36, v36
	v_fmac_f32_e32 v33, v38, v38
	v_fmac_f32_e32 v34, v44, v44
	v_fmac_f32_e32 v35, v46, v46
	v_add_f32_e32 v32, v32, v33
	v_add_f32_e32 v33, v34, v35
	v_add_f32_e32 v32, v32, v33
	v_add_f32_e32 v32, v50, v32
	ds_bpermute_b32 v33, v120, v32
	v_cvt_pk_bf16_f32 v34, v36, v37
	v_cvt_pk_bf16_f32 v35, v38, v39
	v_cvt_pk_bf16_f32 v36, v44, v45
	v_cvt_pk_bf16_f32 v37, v46, v47
	s_waitcnt lgkmcnt(0)
	v_add_f32_e32 v32, v32, v33
	ds_bpermute_b32 v33, v114, v32
	global_store_dwordx4 v[54:55], v[34:37], off offset:256
	s_and_saveexec_b64 s[20:21], s[2:3]
	s_cbranch_execz .LBB0_1261
	v_lshl_add_u64 v[34:35], v[48:49], 2, s[12:13]
	s_waitcnt lgkmcnt(0)
	v_add_f32_e32 v32, v32, v33
	global_atomic_add_f32 v[34:35], v32, off
.LBB0_1261:
	s_or_b64 exec, exec, s[20:21]
	v_add_u32_e32 v32, 0xa0, v148
	s_waitcnt lgkmcnt(0)
	v_ashrrev_i32_e32 v33, 31, v32
	v_lshlrev_b64 v[34:35], 11, v[32:33]
	v_lshl_add_u64 v[34:35], s[10:11], 0, v[34:35]
	v_lshl_add_u64 v[38:39], v[146:147], 1, v[34:35]
	s_nop 0
	s_waitcnt vmcnt(14)
	v_lshlrev_b32_e32 v40, 16, v224
	v_and_b32_e32 v34, 0xffff0000, v224
	v_lshlrev_b32_e32 v41, 16, v225
	v_and_b32_e32 v35, 0xffff0000, v225
	v_lshlrev_b32_e32 v42, 16, v226
	v_and_b32_e32 v36, 0xffff0000, v226
	v_lshlrev_b32_e32 v43, 16, v227
	v_and_b32_e32 v37, 0xffff0000, v227
	v_add_f32_e32 v40, v28, v40
	v_add_f32_e32 v34, v29, v34
	v_add_f32_e32 v41, v30, v41
	v_add_f32_e32 v35, v31, v35
	v_add_f32_e32 v42, v24, v42
	v_add_f32_e32 v36, v25, v36
	v_add_f32_e32 v43, v26, v43
	v_add_f32_e32 v37, v27, v37
	v_cvt_pk_bf16_f32 v24, v40, v34
	v_cvt_pk_bf16_f32 v25, v41, v35
	v_cvt_pk_bf16_f32 v26, v42, v36
	v_cvt_pk_bf16_f32 v27, v43, v37
	s_nop 0
	v_mul_f32_e32 v34, v34, v34
	v_mul_f32_e32 v35, v35, v35
	v_mul_f32_e32 v36, v36, v36
	v_mul_f32_e32 v37, v37, v37
	v_fmac_f32_e32 v34, v40, v40
	v_fmac_f32_e32 v35, v41, v41
	v_fmac_f32_e32 v36, v42, v42
	v_fmac_f32_e32 v37, v43, v43
	v_add_f32_e32 v34, v34, v35
	v_add_f32_e32 v35, v36, v37
	v_add_f32_e32 v34, v34, v35
	global_store_dwordx4 v[38:39], v[24:27], off
	s_nop 0
	v_lshlrev_b32_e32 v35, 16, v228
	v_and_b32_e32 v28, 0xffff0000, v228
	v_lshlrev_b32_e32 v36, 16, v229
	v_and_b32_e32 v29, 0xffff0000, v229
	v_lshlrev_b32_e32 v37, 16, v230
	v_and_b32_e32 v30, 0xffff0000, v230
	v_lshlrev_b32_e32 v40, 16, v231
	v_and_b32_e32 v31, 0xffff0000, v231
	v_add_f32_e32 v21, v21, v28
	v_add_f32_e32 v23, v23, v29
	v_add_f32_e32 v29, v17, v30
	v_add_f32_e32 v31, v19, v31
	v_add_f32_e32 v20, v20, v35
	v_add_f32_e32 v22, v22, v36
	v_add_f32_e32 v28, v16, v37
	v_add_f32_e32 v30, v18, v40
	v_mul_f32_e32 v16, v21, v21
	v_mul_f32_e32 v17, v23, v23
	v_mul_f32_e32 v18, v29, v29
	v_mul_f32_e32 v19, v31, v31
	v_fmac_f32_e32 v16, v20, v20
	v_fmac_f32_e32 v17, v22, v22
	v_fmac_f32_e32 v18, v28, v28
	v_fmac_f32_e32 v19, v30, v30
	v_add_f32_e32 v16, v16, v17
	v_add_f32_e32 v17, v18, v19
	v_add_f32_e32 v16, v16, v17
	v_add_f32_e32 v16, v34, v16
	ds_bpermute_b32 v17, v120, v16
	v_cvt_pk_bf16_f32 v18, v20, v21
	v_cvt_pk_bf16_f32 v19, v22, v23
	v_cvt_pk_bf16_f32 v20, v28, v29
	v_cvt_pk_bf16_f32 v21, v30, v31
	s_waitcnt lgkmcnt(0)
	v_add_f32_e32 v16, v16, v17
	ds_bpermute_b32 v17, v114, v16
	global_store_dwordx4 v[38:39], v[18:21], off offset:256
	s_and_saveexec_b64 s[20:21], s[2:3]
	s_cbranch_execz .LBB0_1263
	v_lshl_add_u64 v[18:19], v[32:33], 2, s[12:13]
	s_waitcnt lgkmcnt(0)
	v_add_f32_e32 v16, v16, v17
	global_atomic_add_f32 v[18:19], v16, off
.LBB0_1263:
	s_or_b64 exec, exec, s[20:21]
	v_add_u32_e32 v16, 0xb0, v148
	s_waitcnt lgkmcnt(0)
	v_ashrrev_i32_e32 v17, 31, v16
	v_lshlrev_b64 v[18:19], 11, v[16:17]
	v_lshl_add_u64 v[18:19], s[10:11], 0, v[18:19]
	v_lshl_add_u64 v[22:23], v[146:147], 1, v[18:19]
	s_nop 0
	s_waitcnt vmcnt(14)
	v_lshlrev_b32_e32 v24, 16, v232
	v_and_b32_e32 v18, 0xffff0000, v232
	v_lshlrev_b32_e32 v25, 16, v233
	v_and_b32_e32 v19, 0xffff0000, v233
	v_lshlrev_b32_e32 v26, 16, v234
	v_and_b32_e32 v20, 0xffff0000, v234
	v_lshlrev_b32_e32 v27, 16, v235
	v_and_b32_e32 v21, 0xffff0000, v235
	v_add_f32_e32 v24, v12, v24
	v_add_f32_e32 v18, v13, v18
	v_add_f32_e32 v25, v14, v25
	v_add_f32_e32 v19, v15, v19
	v_add_f32_e32 v26, v8, v26
	v_add_f32_e32 v20, v9, v20
	v_add_f32_e32 v27, v10, v27
	v_add_f32_e32 v21, v11, v21
	v_cvt_pk_bf16_f32 v8, v24, v18
	v_cvt_pk_bf16_f32 v9, v25, v19
	v_cvt_pk_bf16_f32 v10, v26, v20
	v_cvt_pk_bf16_f32 v11, v27, v21
	s_nop 0
	v_mul_f32_e32 v18, v18, v18
	v_mul_f32_e32 v19, v19, v19
	v_mul_f32_e32 v20, v20, v20
	v_mul_f32_e32 v21, v21, v21
	v_fmac_f32_e32 v18, v24, v24
	v_fmac_f32_e32 v19, v25, v25
	v_fmac_f32_e32 v20, v26, v26
	v_fmac_f32_e32 v21, v27, v27
	v_add_f32_e32 v18, v18, v19
	v_add_f32_e32 v19, v20, v21
	v_add_f32_e32 v18, v18, v19
	global_store_dwordx4 v[22:23], v[8:11], off
	s_nop 0
	v_lshlrev_b32_e32 v19, 16, v236
	v_and_b32_e32 v12, 0xffff0000, v236
	v_lshlrev_b32_e32 v20, 16, v237
	v_and_b32_e32 v13, 0xffff0000, v237
	v_lshlrev_b32_e32 v21, 16, v238
	v_and_b32_e32 v14, 0xffff0000, v238
	v_lshlrev_b32_e32 v24, 16, v239
	v_and_b32_e32 v15, 0xffff0000, v239
	v_add_f32_e32 v5, v5, v12
	v_add_f32_e32 v7, v7, v13
	v_add_f32_e32 v13, v1, v14
	v_add_f32_e32 v15, v3, v15
	v_add_f32_e32 v4, v4, v19
	v_add_f32_e32 v6, v6, v20
	v_add_f32_e32 v12, v0, v21
	v_add_f32_e32 v14, v2, v24
	v_mul_f32_e32 v0, v5, v5
	v_mul_f32_e32 v1, v7, v7
	v_mul_f32_e32 v2, v13, v13
	v_mul_f32_e32 v3, v15, v15
	v_fmac_f32_e32 v0, v4, v4
	v_fmac_f32_e32 v1, v6, v6
	v_fmac_f32_e32 v2, v12, v12
	v_fmac_f32_e32 v3, v14, v14
	v_add_f32_e32 v0, v0, v1
	v_add_f32_e32 v1, v2, v3
	v_add_f32_e32 v0, v0, v1
	v_add_f32_e32 v0, v18, v0
	ds_bpermute_b32 v1, v120, v0
	v_cvt_pk_bf16_f32 v2, v4, v5
	v_cvt_pk_bf16_f32 v3, v6, v7
	v_cvt_pk_bf16_f32 v4, v12, v13
	v_cvt_pk_bf16_f32 v5, v14, v15
	s_waitcnt lgkmcnt(0)
	v_add_f32_e32 v0, v0, v1
	ds_bpermute_b32 v1, v114, v0
	global_store_dwordx4 v[22:23], v[2:5], off offset:256
	s_and_saveexec_b64 s[20:21], s[2:3]
	s_cbranch_execz .LBB0_1265
	v_lshl_add_u64 v[2:3], v[16:17], 2, s[12:13]
	s_waitcnt lgkmcnt(0)
	v_add_f32_e32 v0, v0, v1
	global_atomic_add_f32 v[2:3], v0, off

.LBB0_1345:
	v_lshl_add_u32 v146, s0, 8, v150
	v_ashrrev_i32_e32 v147, 31, v146
	v_lshl_add_u64 v[148:149], v[146:147], 2, s[10:11]
	global_load_dword v147, v[148:149], off
	global_load_dword v200, v[148:149], off offset:64
	global_load_dword v201, v[148:149], off offset:128
	global_load_dword v202, v[148:149], off offset:192
	global_load_dword v203, v[148:149], off offset:512
	global_load_dword v204, v[148:149], off offset:576
	global_load_dword v205, v[148:149], off offset:640
	global_load_dword v206, v[148:149], off offset:704
	v_lshl_or_b32 v158, s1, 7, v153
	v_ashrrev_i32_e32 v159, 31, v158
	v_mov_b32_e32 v162, v122
	v_mov_b32_e32 v163, v114
	v_mov_b32_e32 v114, v123
	v_lshlrev_b64 v[122:123], 1, v[158:159]
	v_mov_b32_e32 v160, v124
	v_mov_b32_e32 v161, v116
	v_mov_b32_e32 v116, v125
	v_mov_b32_e32 v124, v126
	v_mov_b32_e32 v125, v118
	v_mov_b32_e32 v118, v127
	v_mov_b32_e32 v126, v120
	v_mov_b32_e32 v127, v112
	v_mov_b32_e32 v112, v121
	v_mov_b64_e32 v[120:121], s[8:9]
	v_or_b32_e32 v166, 16, v146
	v_mad_i64_i32 v[164:165], s[0:1], v146, s64, v[120:121]
	v_ashrrev_i32_e32 v167, 31, v166
	s_waitcnt vmcnt(0)
	v_fmamk_f32 v147, v147, 0x3a800000, v157
	v_mul_f32_e32 v158, 0x4b800000, v147
	v_cmp_gt_f32_e32 vcc, s63, v147
	s_nop 1
	v_cndmask_b32_e32 v147, v147, v158, vcc
	v_rsq_f32_e32 v147, v147
	v_lshl_add_u64 v[158:159], v[164:165], 0, v[122:123]
	v_lshl_add_u64 v[164:165], v[166:167], 2, s[10:11]
	v_mul_f32_e32 v167, 0x45800000, v147
	v_cndmask_b32_e32 v168, v147, v167, vcc
	v_pk_mul_f32 v[114:115], v[114:115], v[168:169] op_sel_hi:[1,0]
	v_pk_mul_f32 v[160:161], v[160:161], v[168:169] op_sel_hi:[1,0]
	v_pk_mul_f32 v[116:117], v[116:117], v[168:169] op_sel_hi:[1,0]
	v_pk_mul_f32 v[124:125], v[124:125], v[168:169] op_sel_hi:[1,0]
	v_pk_mul_f32 v[118:119], v[118:119], v[168:169] op_sel_hi:[1,0]
	v_pk_mul_f32 v[126:127], v[126:127], v[168:169] op_sel_hi:[1,0]
	v_pk_mul_f32 v[112:113], v[112:113], v[168:169] op_sel_hi:[1,0]
	v_pk_mul_f32 v[162:163], v[162:163], v[168:169] op_sel_hi:[1,0]
	v_mul_f32_e32 v173, 0xbfb8aa3b, v115
	v_mul_f32_e32 v147, 0xbfb8aa3b, v161
	v_mul_f32_e32 v167, 0xbfb8aa3b, v117
	v_mul_f32_e32 v168, 0xbfb8aa3b, v125
	v_mul_f32_e32 v169, 0xbfb8aa3b, v119
	v_mul_f32_e32 v170, 0xbfb8aa3b, v127
	v_mul_f32_e32 v171, 0xbfb8aa3b, v113
	v_mul_f32_e32 v172, 0xbfb8aa3b, v163
	v_exp_f32_e32 v173, v173
	v_exp_f32_e32 v147, v147
	v_exp_f32_e32 v167, v167
	v_exp_f32_e32 v168, v168
	v_exp_f32_e32 v169, v169
	v_exp_f32_e32 v170, v170
	v_exp_f32_e32 v171, v171
	v_exp_f32_e32 v172, v172
	v_add_f32_e32 v173, 1.0, v173
	v_add_f32_e32 v147, 1.0, v147
	v_add_f32_e32 v167, 1.0, v167
	v_add_f32_e32 v168, 1.0, v168
	v_add_f32_e32 v169, 1.0, v169
	v_add_f32_e32 v170, 1.0, v170
	v_add_f32_e32 v171, 1.0, v171
	v_add_f32_e32 v172, 1.0, v172
	v_rcp_f32_e32 v173, v173
	v_rcp_f32_e32 v147, v147
	v_rcp_f32_e32 v167, v167
	v_rcp_f32_e32 v168, v168
	v_rcp_f32_e32 v169, v169
	v_rcp_f32_e32 v170, v170
	v_rcp_f32_e32 v171, v171
	v_rcp_f32_e32 v172, v172
	v_mul_f32_e32 v115, v115, v173
	v_mul_f32_e32 v147, v161, v147
	v_mul_f32_e32 v117, v117, v167
	v_mul_f32_e32 v125, v125, v168
	v_mul_f32_e32 v119, v119, v169
	v_mul_f32_e32 v127, v127, v170
	v_mul_f32_e32 v113, v113, v171
	v_mul_f32_e32 v161, v163, v172
	v_mul_f32_e32 v115, v114, v115
	v_mul_f32_e32 v147, v160, v147
	v_mul_f32_e32 v116, v116, v117
	v_mul_f32_e32 v117, v124, v125
	v_mul_f32_e32 v118, v118, v119
	v_mul_f32_e32 v119, v126, v127
	v_mul_f32_e32 v124, v112, v113
	v_mul_f32_e32 v125, v162, v161
	v_cvt_pk_bf16_f32 v112, v147, v116
	v_cvt_pk_bf16_f32 v113, v117, v118
	v_cvt_pk_bf16_f32 v114, v119, v124
	v_cvt_pk_bf16_f32 v115, v125, v115
	global_store_dwordx4 v[158:159], v[112:115], off
	s_nop 0
	s_nop 0
	v_mov_b32_e32 v113, v100
	v_mov_b32_e32 v100, v109
	v_mov_b32_e32 v109, v102
	v_mov_b32_e32 v102, v111
	v_mov_b32_e32 v111, v96
	v_mov_b32_e32 v96, v105
	v_mov_b32_e32 v105, v98
	v_mov_b32_e32 v98, v107
	v_mov_b32_e32 v112, v108
	v_mov_b32_e32 v108, v110
	v_mov_b32_e32 v110, v104
	v_mov_b32_e32 v104, v106
	v_or_b32_e32 v106, 32, v146
	v_mad_i64_i32 v[114:115], s[0:1], v166, s64, v[120:121]
	v_lshl_add_u64 v[114:115], v[114:115], 0, v[122:123]
	s_nop 0
	v_fmamk_f32 v107, v200, 0x3a800000, v157
	v_mul_f32_e32 v116, 0x4b800000, v107
	v_cmp_gt_f32_e32 vcc, s63, v107
	s_nop 1
	v_cndmask_b32_e32 v107, v107, v116, vcc
	v_rsq_f32_e32 v118, v107
	v_ashrrev_i32_e32 v107, 31, v106
	v_lshl_add_u64 v[116:117], v[106:107], 2, s[10:11]
	v_mul_f32_e32 v107, 0x45800000, v118
	v_cndmask_b32_e32 v118, v118, v107, vcc
	v_pk_mul_f32 v[98:99], v[98:99], v[118:119] op_sel_hi:[1,0]
	v_pk_mul_f32 v[112:113], v[112:113], v[118:119] op_sel_hi:[1,0]
	v_pk_mul_f32 v[100:101], v[100:101], v[118:119] op_sel_hi:[1,0]
	v_pk_mul_f32 v[108:109], v[108:109], v[118:119] op_sel_hi:[1,0]
	v_pk_mul_f32 v[102:103], v[102:103], v[118:119] op_sel_hi:[1,0]
	v_pk_mul_f32 v[110:111], v[110:111], v[118:119] op_sel_hi:[1,0]
	v_pk_mul_f32 v[96:97], v[96:97], v[118:119] op_sel_hi:[1,0]
	v_pk_mul_f32 v[104:105], v[104:105], v[118:119] op_sel_hi:[1,0]
	v_mul_f32_e32 v147, 0xbfb8aa3b, v99
	v_mul_f32_e32 v107, 0xbfb8aa3b, v113
	v_mul_f32_e32 v118, 0xbfb8aa3b, v101
	v_mul_f32_e32 v119, 0xbfb8aa3b, v109
	v_mul_f32_e32 v124, 0xbfb8aa3b, v103
	v_mul_f32_e32 v125, 0xbfb8aa3b, v111
	v_mul_f32_e32 v126, 0xbfb8aa3b, v97
	v_mul_f32_e32 v127, 0xbfb8aa3b, v105
	v_exp_f32_e32 v147, v147
	v_exp_f32_e32 v107, v107
	v_exp_f32_e32 v118, v118
	v_exp_f32_e32 v119, v119
	v_exp_f32_e32 v124, v124
	v_exp_f32_e32 v125, v125
	v_exp_f32_e32 v126, v126
	v_exp_f32_e32 v127, v127
	v_add_f32_e32 v147, 1.0, v147
	v_add_f32_e32 v107, 1.0, v107
	v_add_f32_e32 v118, 1.0, v118
	v_add_f32_e32 v119, 1.0, v119
	v_add_f32_e32 v124, 1.0, v124
	v_add_f32_e32 v125, 1.0, v125
	v_add_f32_e32 v126, 1.0, v126
	v_add_f32_e32 v127, 1.0, v127
	v_rcp_f32_e32 v147, v147
	v_rcp_f32_e32 v107, v107
	v_rcp_f32_e32 v118, v118
	v_rcp_f32_e32 v119, v119
	v_rcp_f32_e32 v124, v124
	v_rcp_f32_e32 v125, v125
	v_rcp_f32_e32 v126, v126
	v_rcp_f32_e32 v127, v127
	v_mul_f32_e32 v99, v99, v147
	v_mul_f32_e32 v107, v113, v107
	v_mul_f32_e32 v101, v101, v118
	v_mul_f32_e32 v109, v109, v119
	v_mul_f32_e32 v103, v103, v124
	v_mul_f32_e32 v111, v111, v125
	v_mul_f32_e32 v97, v97, v126
	v_mul_f32_e32 v105, v105, v127
	v_mul_f32_e32 v99, v98, v99
	v_mul_f32_e32 v107, v112, v107
	v_mul_f32_e32 v100, v100, v101
	v_mul_f32_e32 v101, v108, v109
	v_mul_f32_e32 v102, v102, v103
	v_mul_f32_e32 v103, v110, v111
	v_mul_f32_e32 v108, v96, v97
	v_mul_f32_e32 v104, v104, v105
	v_cvt_pk_bf16_f32 v96, v107, v100
	v_cvt_pk_bf16_f32 v97, v101, v102
	v_cvt_pk_bf16_f32 v98, v103, v108
	v_cvt_pk_bf16_f32 v99, v104, v99
	global_store_dwordx4 v[114:115], v[96:99], off
	s_nop 0
	s_nop 0
	v_mov_b32_e32 v97, v84
	v_mov_b32_e32 v84, v93
	v_mov_b32_e32 v93, v86
	v_mov_b32_e32 v86, v95
	v_mov_b32_e32 v95, v80
	v_mov_b32_e32 v80, v89
	v_mov_b32_e32 v89, v82
	v_mov_b32_e32 v82, v91
	v_mov_b32_e32 v96, v92
	v_mov_b32_e32 v92, v94
	v_mov_b32_e32 v94, v88
	v_mov_b32_e32 v88, v90
	v_or_b32_e32 v90, 48, v146
	v_mad_i64_i32 v[98:99], s[0:1], v106, s64, v[120:121]
	v_lshl_add_u64 v[98:99], v[98:99], 0, v[122:123]
	s_nop 0
	v_fmamk_f32 v91, v201, 0x3a800000, v157
	v_mul_f32_e32 v100, 0x4b800000, v91
	v_cmp_gt_f32_e32 vcc, s63, v91
	s_nop 1
	v_cndmask_b32_e32 v91, v91, v100, vcc
	v_rsq_f32_e32 v102, v91
	v_ashrrev_i32_e32 v91, 31, v90
	v_lshl_add_u64 v[100:101], v[90:91], 2, s[10:11]
	v_mul_f32_e32 v91, 0x45800000, v102
	v_cndmask_b32_e32 v102, v102, v91, vcc
	v_pk_mul_f32 v[82:83], v[82:83], v[102:103] op_sel_hi:[1,0]
	v_pk_mul_f32 v[96:97], v[96:97], v[102:103] op_sel_hi:[1,0]
	v_pk_mul_f32 v[84:85], v[84:85], v[102:103] op_sel_hi:[1,0]
	v_pk_mul_f32 v[92:93], v[92:93], v[102:103] op_sel_hi:[1,0]
	v_pk_mul_f32 v[86:87], v[86:87], v[102:103] op_sel_hi:[1,0]
	v_pk_mul_f32 v[94:95], v[94:95], v[102:103] op_sel_hi:[1,0]
	v_pk_mul_f32 v[80:81], v[80:81], v[102:103] op_sel_hi:[1,0]
	v_pk_mul_f32 v[88:89], v[88:89], v[102:103] op_sel_hi:[1,0]
	v_mul_f32_e32 v108, 0xbfb8aa3b, v83
	v_mul_f32_e32 v91, 0xbfb8aa3b, v97
	v_mul_f32_e32 v102, 0xbfb8aa3b, v85
	v_mul_f32_e32 v103, 0xbfb8aa3b, v93
	v_mul_f32_e32 v104, 0xbfb8aa3b, v87
	v_mul_f32_e32 v105, 0xbfb8aa3b, v95
	v_mul_f32_e32 v106, 0xbfb8aa3b, v81
	v_mul_f32_e32 v107, 0xbfb8aa3b, v89
	v_exp_f32_e32 v108, v108
	v_exp_f32_e32 v91, v91
	v_exp_f32_e32 v102, v102
	v_exp_f32_e32 v103, v103
	v_exp_f32_e32 v104, v104
	v_exp_f32_e32 v105, v105
	v_exp_f32_e32 v106, v106
	v_exp_f32_e32 v107, v107
	v_add_f32_e32 v108, 1.0, v108
	v_add_f32_e32 v91, 1.0, v91
	v_add_f32_e32 v102, 1.0, v102
	v_add_f32_e32 v103, 1.0, v103
	v_add_f32_e32 v104, 1.0, v104
	v_add_f32_e32 v105, 1.0, v105
	v_add_f32_e32 v106, 1.0, v106
	v_add_f32_e32 v107, 1.0, v107
	v_rcp_f32_e32 v108, v108
	v_rcp_f32_e32 v91, v91
	v_rcp_f32_e32 v102, v102
	v_rcp_f32_e32 v103, v103
	v_rcp_f32_e32 v104, v104
	v_rcp_f32_e32 v105, v105
	v_rcp_f32_e32 v106, v106
	v_rcp_f32_e32 v107, v107
	v_mul_f32_e32 v83, v83, v108
	v_mul_f32_e32 v91, v97, v91
	v_mul_f32_e32 v85, v85, v102
	v_mul_f32_e32 v93, v93, v103
	v_mul_f32_e32 v87, v87, v104
	v_mul_f32_e32 v95, v95, v105
	v_mul_f32_e32 v81, v81, v106
	v_mul_f32_e32 v89, v89, v107
	v_mul_f32_e32 v83, v82, v83
	v_mul_f32_e32 v91, v96, v91
	v_mul_f32_e32 v84, v84, v85
	v_mul_f32_e32 v85, v92, v93
	v_mul_f32_e32 v86, v86, v87
	v_mul_f32_e32 v87, v94, v95
	v_mul_f32_e32 v92, v80, v81
	v_mul_f32_e32 v88, v88, v89
	v_cvt_pk_bf16_f32 v80, v91, v84
	v_cvt_pk_bf16_f32 v81, v85, v86
	v_cvt_pk_bf16_f32 v82, v87, v92
	v_cvt_pk_bf16_f32 v83, v88, v83
	global_store_dwordx4 v[98:99], v[80:83], off
	s_nop 0
	s_nop 0
	v_mov_b32_e32 v80, v76
	v_mov_b32_e32 v76, v78
	v_mov_b32_e32 v78, v68
	v_mov_b32_e32 v68, v70
	v_mov_b32_e32 v81, v72
	v_mov_b32_e32 v72, v77
	v_mov_b32_e32 v77, v74
	v_mov_b32_e32 v74, v79
	v_mov_b32_e32 v79, v64
	v_mov_b32_e32 v64, v69
	v_mov_b32_e32 v69, v66
	v_mov_b32_e32 v66, v71
	s_nop 0
	v_fmamk_f32 v70, v202, 0x3a800000, v157
	v_mul_f32_e32 v71, 0x4b800000, v70
	v_cmp_gt_f32_e32 vcc, s63, v70
	s_nop 1
	v_cndmask_b32_e32 v70, v70, v71, vcc
	v_rsq_f32_e32 v82, v70
	v_mad_i64_i32 v[70:71], s[0:1], v90, s64, v[120:121]
	v_lshl_add_u64 v[70:71], v[70:71], 0, v[122:123]
	v_mul_f32_e32 v83, 0x45800000, v82
	v_cndmask_b32_e32 v82, v82, v83, vcc
	v_pk_mul_f32 v[66:67], v[66:67], v[82:83] op_sel_hi:[1,0]
	v_pk_mul_f32 v[80:81], v[80:81], v[82:83] op_sel_hi:[1,0]
	v_pk_mul_f32 v[72:73], v[72:73], v[82:83] op_sel_hi:[1,0]
	v_pk_mul_f32 v[76:77], v[76:77], v[82:83] op_sel_hi:[1,0]
	v_pk_mul_f32 v[74:75], v[74:75], v[82:83] op_sel_hi:[1,0]
	v_pk_mul_f32 v[78:79], v[78:79], v[82:83] op_sel_hi:[1,0]
	v_pk_mul_f32 v[64:65], v[64:65], v[82:83] op_sel_hi:[1,0]
	v_pk_mul_f32 v[68:69], v[68:69], v[82:83] op_sel_hi:[1,0]
	v_mul_f32_e32 v89, 0xbfb8aa3b, v67
	v_mul_f32_e32 v82, 0xbfb8aa3b, v81
	v_mul_f32_e32 v83, 0xbfb8aa3b, v73
	v_mul_f32_e32 v84, 0xbfb8aa3b, v77
	v_mul_f32_e32 v85, 0xbfb8aa3b, v75
	v_mul_f32_e32 v86, 0xbfb8aa3b, v79
	v_mul_f32_e32 v87, 0xbfb8aa3b, v65
	v_mul_f32_e32 v88, 0xbfb8aa3b, v69
	v_exp_f32_e32 v89, v89
	v_exp_f32_e32 v82, v82
	v_exp_f32_e32 v83, v83
	v_exp_f32_e32 v84, v84
	v_exp_f32_e32 v85, v85
	v_exp_f32_e32 v86, v86
	v_exp_f32_e32 v87, v87
	v_exp_f32_e32 v88, v88
	v_add_f32_e32 v89, 1.0, v89
	v_add_f32_e32 v82, 1.0, v82
	v_add_f32_e32 v83, 1.0, v83
	v_add_f32_e32 v84, 1.0, v84
	v_add_f32_e32 v85, 1.0, v85
	v_add_f32_e32 v86, 1.0, v86
	v_add_f32_e32 v87, 1.0, v87
	v_add_f32_e32 v88, 1.0, v88
	v_rcp_f32_e32 v89, v89
	v_rcp_f32_e32 v82, v82
	v_rcp_f32_e32 v83, v83
	v_rcp_f32_e32 v84, v84
	v_rcp_f32_e32 v85, v85
	v_rcp_f32_e32 v86, v86
	v_rcp_f32_e32 v87, v87
	v_rcp_f32_e32 v88, v88
	v_mul_f32_e32 v67, v67, v89
	v_mul_f32_e32 v81, v81, v82
	v_mul_f32_e32 v73, v73, v83
	v_mul_f32_e32 v77, v77, v84
	v_mul_f32_e32 v75, v75, v85
	v_mul_f32_e32 v79, v79, v86
	v_mul_f32_e32 v65, v65, v87
	v_mul_f32_e32 v69, v69, v88
	v_mul_f32_e32 v67, v66, v67
	v_mul_f32_e32 v80, v80, v81
	v_mul_f32_e32 v72, v72, v73
	v_mul_f32_e32 v73, v76, v77
	v_mul_f32_e32 v74, v74, v75
	v_mul_f32_e32 v75, v78, v79
	v_mul_f32_e32 v76, v64, v65
	v_mul_f32_e32 v68, v68, v69
	v_cvt_pk_bf16_f32 v64, v80, v72
	v_cvt_pk_bf16_f32 v65, v73, v74
	v_cvt_pk_bf16_f32 v66, v75, v76
	v_cvt_pk_bf16_f32 v67, v68, v67
	global_store_dwordx4 v[70:71], v[64:67], off
	s_nop 0
	s_nop 0
	v_mov_b32_e32 v65, v56
	v_mov_b32_e32 v56, v61
	v_mov_b32_e32 v61, v58
	v_mov_b32_e32 v58, v63
	v_mov_b32_e32 v63, v48
	v_mov_b32_e32 v48, v53
	v_mov_b32_e32 v53, v50
	v_mov_b32_e32 v50, v55
	v_mov_b32_e32 v64, v60
	v_mov_b32_e32 v60, v62
	v_mov_b32_e32 v62, v52
	v_mov_b32_e32 v52, v54
	v_add_u32_e32 v54, 0x80, v146
	s_nop 0
	v_fmamk_f32 v55, v203, 0x3a800000, v157
	v_mul_f32_e32 v66, 0x4b800000, v55
	v_cmp_gt_f32_e32 vcc, s63, v55
	s_nop 1
	v_cndmask_b32_e32 v55, v55, v66, vcc
	v_rsq_f32_e32 v66, v55
	v_mad_i64_i32 v[54:55], s[0:1], v54, s64, v[120:121]
	v_lshl_add_u64 v[54:55], v[54:55], 0, v[122:123]
	v_mul_f32_e32 v67, 0x45800000, v66
	v_cndmask_b32_e32 v66, v66, v67, vcc
	v_pk_mul_f32 v[50:51], v[50:51], v[66:67] op_sel_hi:[1,0]
	v_pk_mul_f32 v[64:65], v[64:65], v[66:67] op_sel_hi:[1,0]
	v_pk_mul_f32 v[56:57], v[56:57], v[66:67] op_sel_hi:[1,0]
	v_pk_mul_f32 v[60:61], v[60:61], v[66:67] op_sel_hi:[1,0]
	v_pk_mul_f32 v[58:59], v[58:59], v[66:67] op_sel_hi:[1,0]
	v_pk_mul_f32 v[62:63], v[62:63], v[66:67] op_sel_hi:[1,0]
	v_pk_mul_f32 v[48:49], v[48:49], v[66:67] op_sel_hi:[1,0]
	v_pk_mul_f32 v[52:53], v[52:53], v[66:67] op_sel_hi:[1,0]
	v_mul_f32_e32 v73, 0xbfb8aa3b, v51
	v_mul_f32_e32 v66, 0xbfb8aa3b, v65
	v_mul_f32_e32 v67, 0xbfb8aa3b, v57
	v_mul_f32_e32 v68, 0xbfb8aa3b, v61
	v_mul_f32_e32 v69, 0xbfb8aa3b, v59
	v_mul_f32_e32 v70, 0xbfb8aa3b, v63
	v_mul_f32_e32 v71, 0xbfb8aa3b, v49
	v_mul_f32_e32 v72, 0xbfb8aa3b, v53
	v_exp_f32_e32 v73, v73
	v_exp_f32_e32 v66, v66
	v_exp_f32_e32 v67, v67
	v_exp_f32_e32 v68, v68
	v_exp_f32_e32 v69, v69
	v_exp_f32_e32 v70, v70
	v_exp_f32_e32 v71, v71
	v_exp_f32_e32 v72, v72
	v_add_f32_e32 v73, 1.0, v73
	v_add_f32_e32 v66, 1.0, v66
	v_add_f32_e32 v67, 1.0, v67
	v_add_f32_e32 v68, 1.0, v68
	v_add_f32_e32 v69, 1.0, v69
	v_add_f32_e32 v70, 1.0, v70
	v_add_f32_e32 v71, 1.0, v71
	v_add_f32_e32 v72, 1.0, v72
	v_rcp_f32_e32 v73, v73
	v_rcp_f32_e32 v66, v66
	v_rcp_f32_e32 v67, v67
	v_rcp_f32_e32 v68, v68
	v_rcp_f32_e32 v69, v69
	v_rcp_f32_e32 v70, v70
	v_rcp_f32_e32 v71, v71
	v_rcp_f32_e32 v72, v72
	v_mul_f32_e32 v51, v51, v73
	v_mul_f32_e32 v65, v65, v66
	v_mul_f32_e32 v57, v57, v67
	v_mul_f32_e32 v61, v61, v68
	v_mul_f32_e32 v59, v59, v69
	v_mul_f32_e32 v63, v63, v70
	v_mul_f32_e32 v49, v49, v71
	v_mul_f32_e32 v53, v53, v72
	v_mul_f32_e32 v51, v50, v51
	v_mul_f32_e32 v64, v64, v65
	v_mul_f32_e32 v56, v56, v57
	v_mul_f32_e32 v57, v60, v61
	v_mul_f32_e32 v58, v58, v59
	v_mul_f32_e32 v59, v62, v63
	v_mul_f32_e32 v60, v48, v49
	v_mul_f32_e32 v52, v52, v53
	v_cvt_pk_bf16_f32 v48, v64, v56
	v_cvt_pk_bf16_f32 v49, v57, v58
	v_cvt_pk_bf16_f32 v50, v59, v60
	v_cvt_pk_bf16_f32 v51, v52, v51
	global_store_dwordx4 v[54:55], v[48:51], off
	s_nop 0
	s_nop 0
	v_mov_b32_e32 v49, v40
	v_mov_b32_e32 v40, v45
	v_mov_b32_e32 v45, v42
	v_mov_b32_e32 v42, v47
	v_mov_b32_e32 v47, v32
	v_mov_b32_e32 v32, v37
	v_mov_b32_e32 v37, v34
	v_mov_b32_e32 v34, v39
	v_mov_b32_e32 v48, v44
	v_mov_b32_e32 v44, v46
	v_mov_b32_e32 v46, v36
	v_mov_b32_e32 v36, v38
	v_add_u32_e32 v38, 0x90, v146
	s_nop 0
	v_fmamk_f32 v39, v204, 0x3a800000, v157
	v_mul_f32_e32 v50, 0x4b800000, v39
	v_cmp_gt_f32_e32 vcc, s63, v39
	s_nop 1
	v_cndmask_b32_e32 v39, v39, v50, vcc
	v_rsq_f32_e32 v50, v39
	v_mad_i64_i32 v[38:39], s[0:1], v38, s64, v[120:121]
	v_lshl_add_u64 v[38:39], v[38:39], 0, v[122:123]
	v_mul_f32_e32 v51, 0x45800000, v50
	v_cndmask_b32_e32 v50, v50, v51, vcc
	v_pk_mul_f32 v[34:35], v[34:35], v[50:51] op_sel_hi:[1,0]
	v_pk_mul_f32 v[48:49], v[48:49], v[50:51] op_sel_hi:[1,0]
	v_pk_mul_f32 v[40:41], v[40:41], v[50:51] op_sel_hi:[1,0]
	v_pk_mul_f32 v[44:45], v[44:45], v[50:51] op_sel_hi:[1,0]
	v_pk_mul_f32 v[42:43], v[42:43], v[50:51] op_sel_hi:[1,0]
	v_pk_mul_f32 v[46:47], v[46:47], v[50:51] op_sel_hi:[1,0]
	v_pk_mul_f32 v[32:33], v[32:33], v[50:51] op_sel_hi:[1,0]
	v_pk_mul_f32 v[36:37], v[36:37], v[50:51] op_sel_hi:[1,0]
	v_mul_f32_e32 v57, 0xbfb8aa3b, v35
	v_mul_f32_e32 v50, 0xbfb8aa3b, v49
	v_mul_f32_e32 v51, 0xbfb8aa3b, v41
	v_mul_f32_e32 v52, 0xbfb8aa3b, v45
	v_mul_f32_e32 v53, 0xbfb8aa3b, v43
	v_mul_f32_e32 v54, 0xbfb8aa3b, v47
	v_mul_f32_e32 v55, 0xbfb8aa3b, v33
	v_mul_f32_e32 v56, 0xbfb8aa3b, v37
	v_exp_f32_e32 v57, v57
	v_exp_f32_e32 v50, v50
	v_exp_f32_e32 v51, v51
	v_exp_f32_e32 v52, v52
	v_exp_f32_e32 v53, v53
	v_exp_f32_e32 v54, v54
	v_exp_f32_e32 v55, v55
	v_exp_f32_e32 v56, v56
	v_add_f32_e32 v57, 1.0, v57
	v_add_f32_e32 v50, 1.0, v50
	v_add_f32_e32 v51, 1.0, v51
	v_add_f32_e32 v52, 1.0, v52
	v_add_f32_e32 v53, 1.0, v53
	v_add_f32_e32 v54, 1.0, v54
	v_add_f32_e32 v55, 1.0, v55
	v_add_f32_e32 v56, 1.0, v56
	v_rcp_f32_e32 v57, v57
	v_rcp_f32_e32 v50, v50
	v_rcp_f32_e32 v51, v51
	v_rcp_f32_e32 v52, v52
	v_rcp_f32_e32 v53, v53
	v_rcp_f32_e32 v54, v54
	v_rcp_f32_e32 v55, v55
	v_rcp_f32_e32 v56, v56
	v_mul_f32_e32 v35, v35, v57
	v_mul_f32_e32 v49, v49, v50
	v_mul_f32_e32 v41, v41, v51
	v_mul_f32_e32 v45, v45, v52
	v_mul_f32_e32 v43, v43, v53
	v_mul_f32_e32 v47, v47, v54
	v_mul_f32_e32 v33, v33, v55
	v_mul_f32_e32 v37, v37, v56
	v_mul_f32_e32 v35, v34, v35
	v_mul_f32_e32 v48, v48, v49
	v_mul_f32_e32 v40, v40, v41
	v_mul_f32_e32 v41, v44, v45
	v_mul_f32_e32 v42, v42, v43
	v_mul_f32_e32 v43, v46, v47
	v_mul_f32_e32 v44, v32, v33
	v_mul_f32_e32 v36, v36, v37
	v_cvt_pk_bf16_f32 v32, v48, v40
	v_cvt_pk_bf16_f32 v33, v41, v42
	v_cvt_pk_bf16_f32 v34, v43, v44
	v_cvt_pk_bf16_f32 v35, v36, v35
	global_store_dwordx4 v[38:39], v[32:35], off
	s_nop 0
	s_nop 0
	v_mov_b32_e32 v33, v24
	v_mov_b32_e32 v24, v29
	v_mov_b32_e32 v29, v26
	v_mov_b32_e32 v26, v31
	v_mov_b32_e32 v31, v16
	v_mov_b32_e32 v16, v21
	v_mov_b32_e32 v21, v18
	v_mov_b32_e32 v18, v23
	v_mov_b32_e32 v32, v28
	v_mov_b32_e32 v28, v30
	v_mov_b32_e32 v30, v20
	v_mov_b32_e32 v20, v22
	v_add_u32_e32 v22, 0xa0, v146
	s_nop 0
	v_fmamk_f32 v23, v205, 0x3a800000, v157
	v_mul_f32_e32 v34, 0x4b800000, v23
	v_cmp_gt_f32_e32 vcc, s63, v23
	s_nop 1
	v_cndmask_b32_e32 v23, v23, v34, vcc
	v_rsq_f32_e32 v34, v23
	v_mad_i64_i32 v[22:23], s[0:1], v22, s64, v[120:121]
	v_lshl_add_u64 v[22:23], v[22:23], 0, v[122:123]
	v_mul_f32_e32 v35, 0x45800000, v34
	v_cndmask_b32_e32 v34, v34, v35, vcc
	v_pk_mul_f32 v[18:19], v[18:19], v[34:35] op_sel_hi:[1,0]
	v_pk_mul_f32 v[32:33], v[32:33], v[34:35] op_sel_hi:[1,0]
	v_pk_mul_f32 v[24:25], v[24:25], v[34:35] op_sel_hi:[1,0]
	v_pk_mul_f32 v[28:29], v[28:29], v[34:35] op_sel_hi:[1,0]
	v_pk_mul_f32 v[26:27], v[26:27], v[34:35] op_sel_hi:[1,0]
	v_pk_mul_f32 v[30:31], v[30:31], v[34:35] op_sel_hi:[1,0]
	v_pk_mul_f32 v[16:17], v[16:17], v[34:35] op_sel_hi:[1,0]
	v_pk_mul_f32 v[20:21], v[20:21], v[34:35] op_sel_hi:[1,0]
	v_mul_f32_e32 v41, 0xbfb8aa3b, v19
	v_mul_f32_e32 v34, 0xbfb8aa3b, v33
	v_mul_f32_e32 v35, 0xbfb8aa3b, v25
	v_mul_f32_e32 v36, 0xbfb8aa3b, v29
	v_mul_f32_e32 v37, 0xbfb8aa3b, v27
	v_mul_f32_e32 v38, 0xbfb8aa3b, v31
	v_mul_f32_e32 v39, 0xbfb8aa3b, v17
	v_mul_f32_e32 v40, 0xbfb8aa3b, v21
	v_exp_f32_e32 v41, v41
	v_exp_f32_e32 v34, v34
	v_exp_f32_e32 v35, v35
	v_exp_f32_e32 v36, v36
	v_exp_f32_e32 v37, v37
	v_exp_f32_e32 v38, v38
	v_exp_f32_e32 v39, v39
	v_exp_f32_e32 v40, v40
	v_add_f32_e32 v41, 1.0, v41
	v_add_f32_e32 v34, 1.0, v34
	v_add_f32_e32 v35, 1.0, v35
	v_add_f32_e32 v36, 1.0, v36
	v_add_f32_e32 v37, 1.0, v37
	v_add_f32_e32 v38, 1.0, v38
	v_add_f32_e32 v39, 1.0, v39
	v_add_f32_e32 v40, 1.0, v40
	v_rcp_f32_e32 v41, v41
	v_rcp_f32_e32 v34, v34
	v_rcp_f32_e32 v35, v35
	v_rcp_f32_e32 v36, v36
	v_rcp_f32_e32 v37, v37
	v_rcp_f32_e32 v38, v38
	v_rcp_f32_e32 v39, v39
	v_rcp_f32_e32 v40, v40
	v_mul_f32_e32 v19, v19, v41
	v_mul_f32_e32 v33, v33, v34
	v_mul_f32_e32 v25, v25, v35
	v_mul_f32_e32 v29, v29, v36
	v_mul_f32_e32 v27, v27, v37
	v_mul_f32_e32 v31, v31, v38
	v_mul_f32_e32 v17, v17, v39
	v_mul_f32_e32 v21, v21, v40
	v_mul_f32_e32 v19, v18, v19
	v_mul_f32_e32 v32, v32, v33
	v_mul_f32_e32 v24, v24, v25
	v_mul_f32_e32 v25, v28, v29
	v_mul_f32_e32 v26, v26, v27
	v_mul_f32_e32 v27, v30, v31
	v_mul_f32_e32 v28, v16, v17
	v_mul_f32_e32 v20, v20, v21
	v_cvt_pk_bf16_f32 v16, v32, v24
	v_cvt_pk_bf16_f32 v17, v25, v26
	v_cvt_pk_bf16_f32 v18, v27, v28
	v_cvt_pk_bf16_f32 v19, v20, v19
	global_store_dwordx4 v[22:23], v[16:19], off
	s_nop 0
	s_andn2_b64 vcc, exec, s[2:3]
	v_mov_b32_e32 v17, v8
	v_mov_b32_e32 v8, v13
	v_mov_b32_e32 v13, v10
	v_mov_b32_e32 v10, v15
	v_mov_b32_e32 v15, v0
	v_mov_b32_e32 v0, v5
	v_mov_b32_e32 v5, v2
	v_mov_b32_e32 v2, v7
	v_mov_b32_e32 v16, v12
	v_mov_b32_e32 v12, v14
	v_mov_b32_e32 v14, v4
	v_mov_b32_e32 v4, v6
	v_add_u32_e32 v6, 0xb0, v146
	s_nop 0
	v_fmamk_f32 v7, v206, 0x3a800000, v157
	v_mul_f32_e32 v18, 0x4b800000, v7
	v_cmp_gt_f32_e64 s[0:1], s63, v7
	s_nop 1
	v_cndmask_b32_e64 v7, v7, v18, s[0:1]
	v_rsq_f32_e32 v18, v7
	v_mad_i64_i32 v[6:7], s[20:21], v6, s64, v[120:121]
	v_lshl_add_u64 v[6:7], v[6:7], 0, v[122:123]
	v_mul_f32_e32 v19, 0x45800000, v18
	v_cndmask_b32_e64 v18, v18, v19, s[0:1]
	v_pk_mul_f32 v[2:3], v[2:3], v[18:19] op_sel_hi:[1,0]
	v_pk_mul_f32 v[16:17], v[16:17], v[18:19] op_sel_hi:[1,0]
	v_pk_mul_f32 v[8:9], v[8:9], v[18:19] op_sel_hi:[1,0]
	v_pk_mul_f32 v[12:13], v[12:13], v[18:19] op_sel_hi:[1,0]
	v_pk_mul_f32 v[10:11], v[10:11], v[18:19] op_sel_hi:[1,0]
	v_pk_mul_f32 v[14:15], v[14:15], v[18:19] op_sel_hi:[1,0]
	v_pk_mul_f32 v[0:1], v[0:1], v[18:19] op_sel_hi:[1,0]
	v_pk_mul_f32 v[4:5], v[4:5], v[18:19] op_sel_hi:[1,0]
	v_mul_f32_e32 v25, 0xbfb8aa3b, v3
	v_mul_f32_e32 v18, 0xbfb8aa3b, v17
	v_mul_f32_e32 v19, 0xbfb8aa3b, v9
	v_mul_f32_e32 v20, 0xbfb8aa3b, v13
	v_mul_f32_e32 v21, 0xbfb8aa3b, v11
	v_mul_f32_e32 v22, 0xbfb8aa3b, v15
	v_mul_f32_e32 v23, 0xbfb8aa3b, v1
	v_mul_f32_e32 v24, 0xbfb8aa3b, v5
	v_exp_f32_e32 v25, v25
	v_exp_f32_e32 v18, v18
	v_exp_f32_e32 v19, v19
	v_exp_f32_e32 v20, v20
	v_exp_f32_e32 v21, v21
	v_exp_f32_e32 v22, v22
	v_exp_f32_e32 v23, v23
	v_exp_f32_e32 v24, v24
	v_add_f32_e32 v25, 1.0, v25
	v_add_f32_e32 v18, 1.0, v18
	v_add_f32_e32 v19, 1.0, v19
	v_add_f32_e32 v20, 1.0, v20
	v_add_f32_e32 v21, 1.0, v21
	v_add_f32_e32 v22, 1.0, v22
	v_add_f32_e32 v23, 1.0, v23
	v_add_f32_e32 v24, 1.0, v24
	v_rcp_f32_e32 v25, v25
	v_rcp_f32_e32 v18, v18
	v_rcp_f32_e32 v19, v19
	v_rcp_f32_e32 v20, v20
	v_rcp_f32_e32 v21, v21
	v_rcp_f32_e32 v22, v22
	v_rcp_f32_e32 v23, v23
	v_rcp_f32_e32 v24, v24
	v_mul_f32_e32 v3, v3, v25
	v_mul_f32_e32 v17, v17, v18
	v_mul_f32_e32 v9, v9, v19
	v_mul_f32_e32 v13, v13, v20
	v_mul_f32_e32 v11, v11, v21
	v_mul_f32_e32 v15, v15, v22
	v_mul_f32_e32 v1, v1, v23
	v_mul_f32_e32 v5, v5, v24
	v_mul_f32_e32 v3, v2, v3
	s_mov_b64 s[0:1], -1
	v_mul_f32_e32 v16, v16, v17
	v_mul_f32_e32 v8, v8, v9
	v_mul_f32_e32 v9, v12, v13
	v_mul_f32_e32 v10, v10, v11
	v_mul_f32_e32 v11, v14, v15
	v_mul_f32_e32 v12, v0, v1
	v_mul_f32_e32 v4, v4, v5
	v_cvt_pk_bf16_f32 v0, v16, v8
	v_cvt_pk_bf16_f32 v1, v9, v10
	v_cvt_pk_bf16_f32 v2, v11, v12
	v_cvt_pk_bf16_f32 v3, v4, v3
	global_store_dwordx4 v[6:7], v[0:3], off
	s_cbranch_vccnz .LBB0_1334
	s_andn2_b64 vcc, exec, s[6:7]
	s_cbranch_vccnz .LBB0_1333
	s_barrier
	s_branch .LBB0_1333

.LBB0_1427:
	v_lshl_add_u32 v148, s21, 8, v153
	v_lshl_or_b32 v146, s20, 8, v155
	v_ashrrev_i32_e32 v149, 31, v148
	v_ashrrev_i32_e32 v147, 31, v146
	v_lshlrev_b64 v[160:161], 10, v[148:149]
	v_lshl_add_u64 v[160:161], v[160:161], 0, v[146:147]
	v_lshlrev_b64 v[164:165], 1, v[160:161]
	v_lshl_add_u64 v[160:161], s[10:11], 0, v[164:165]
	v_mov_b32_e32 v240, v160
	v_mov_b32_e32 v241, v161
	global_load_dwordx4 v[176:179], v[160:161], off
	global_load_dwordx4 v[180:183], v[160:161], off offset:256
	s_mov_b64 s[98:99], 0x8000
	v_lshl_add_u64 v[242:243], v[240:241], 0, s[98:99]
	global_load_dwordx4 v[184:187], v[242:243], off
	global_load_dwordx4 v[188:191], v[242:243], off offset:256
	s_mov_b64 s[98:99], 0x10000
	v_lshl_add_u64 v[242:243], v[240:241], 0, s[98:99]
	global_load_dwordx4 v[192:195], v[242:243], off
	global_load_dwordx4 v[196:199], v[242:243], off offset:256
	s_mov_b64 s[98:99], 0x18000
	v_lshl_add_u64 v[242:243], v[240:241], 0, s[98:99]
	global_load_dwordx4 v[200:203], v[242:243], off
	global_load_dwordx4 v[204:207], v[242:243], off offset:256
	s_mov_b64 s[98:99], 0x40000
	v_lshl_add_u64 v[242:243], v[240:241], 0, s[98:99]
	global_load_dwordx4 v[208:211], v[242:243], off
	global_load_dwordx4 v[212:215], v[242:243], off offset:256
	s_mov_b64 s[98:99], 0x48000
	v_lshl_add_u64 v[242:243], v[240:241], 0, s[98:99]
	global_load_dwordx4 v[216:219], v[242:243], off
	global_load_dwordx4 v[220:223], v[242:243], off offset:256
	s_mov_b64 s[98:99], 0x50000
	v_lshl_add_u64 v[242:243], v[240:241], 0, s[98:99]
	global_load_dwordx4 v[224:227], v[242:243], off
	global_load_dwordx4 v[228:231], v[242:243], off offset:256
	s_mov_b64 s[98:99], 0x58000
	v_lshl_add_u64 v[242:243], v[240:241], 0, s[98:99]
	global_load_dwordx4 v[232:235], v[242:243], off
	global_load_dwordx4 v[236:239], v[242:243], off offset:256
	s_nop 0
	v_lshl_add_u64 v[166:167], s[12:13], 0, v[164:165]
	v_or_b32_e32 v164, 0x100, v164
	v_lshl_add_u64 v[168:169], s[10:11], 0, v[164:165]
	s_waitcnt vmcnt(14)
	v_lshlrev_b32_e32 v170, 16, v176
	v_and_b32_e32 v160, 0xffff0000, v176
	v_lshlrev_b32_e32 v171, 16, v177
	v_and_b32_e32 v161, 0xffff0000, v177
	v_lshlrev_b32_e32 v172, 16, v178
	v_and_b32_e32 v162, 0xffff0000, v178
	v_lshlrev_b32_e32 v173, 16, v179
	v_and_b32_e32 v163, 0xffff0000, v179
	v_add_f32_e32 v170, v124, v170
	v_add_f32_e32 v174, v125, v160
	v_add_f32_e32 v126, v126, v171
	v_add_f32_e32 v127, v127, v161
	v_add_f32_e32 v171, v120, v172
	v_add_f32_e32 v121, v121, v162
	v_add_f32_e32 v172, v122, v173
	v_add_f32_e32 v173, v123, v163
	v_cvt_pk_bf16_f32 v122, v170, v174
	v_cvt_pk_bf16_f32 v123, v126, v127
	v_cvt_pk_bf16_f32 v124, v171, v121
	v_cvt_pk_bf16_f32 v125, v172, v173
	s_nop 0
	v_mul_f32_e32 v174, v174, v174
	v_mul_f32_e32 v127, v127, v127
	v_mul_f32_e32 v121, v121, v121
	v_mul_f32_e32 v173, v173, v173
	v_fmac_f32_e32 v174, v170, v170
	v_fmac_f32_e32 v127, v126, v126
	v_fmac_f32_e32 v121, v171, v171
	v_fmac_f32_e32 v173, v172, v172
	v_add_f32_e32 v126, v174, v127
	v_add_f32_e32 v121, v121, v173
	v_add_f32_e32 v121, v126, v121
	v_and_b32_e32 v168, 64, v159
	v_xor_b32_e32 v120, 16, v159
	v_add_u32_e32 v168, 64, v168
	v_cmp_lt_i32_e32 vcc, v120, v168
	v_xor_b32_e32 v169, 32, v159
	global_store_dwordx4 v[166:167], v[122:125], off
	v_cndmask_b32_e32 v120, v159, v120, vcc
	v_lshlrev_b32_e32 v120, 2, v120
	v_cmp_lt_i32_e32 vcc, v169, v168
	v_lshl_add_u64 v[122:123], s[12:13], 0, v[164:165]
	s_nop 0
	v_lshlrev_b32_e32 v126, 16, v180
	v_and_b32_e32 v127, 0xffff0000, v180
	v_lshlrev_b32_e32 v160, 16, v181
	v_and_b32_e32 v161, 0xffff0000, v181
	v_lshlrev_b32_e32 v170, 16, v182
	v_and_b32_e32 v162, 0xffff0000, v182
	v_lshlrev_b32_e32 v171, 16, v183
	v_and_b32_e32 v163, 0xffff0000, v183
	v_add_f32_e32 v117, v117, v127
	v_add_f32_e32 v119, v119, v161
	v_add_f32_e32 v127, v113, v162
	v_add_f32_e32 v115, v115, v163
	v_add_f32_e32 v116, v116, v126
	v_add_f32_e32 v118, v118, v160
	v_add_f32_e32 v126, v112, v170
	v_add_f32_e32 v160, v114, v171
	v_mul_f32_e32 v112, v117, v117
	v_mul_f32_e32 v113, v119, v119
	v_mul_f32_e32 v114, v127, v127
	v_mul_f32_e32 v161, v115, v115
	v_fmac_f32_e32 v112, v116, v116
	v_fmac_f32_e32 v113, v118, v118
	v_fmac_f32_e32 v114, v126, v126
	v_fmac_f32_e32 v161, v160, v160
	v_add_f32_e32 v112, v112, v113
	v_add_f32_e32 v113, v114, v161
	v_add_f32_e32 v112, v112, v113
	v_add_f32_e32 v112, v121, v112
	ds_bpermute_b32 v113, v120, v112
	v_cndmask_b32_e32 v114, v159, v169, vcc
	v_lshlrev_b32_e32 v114, 2, v114
	v_cvt_pk_bf16_f32 v116, v116, v117
	v_cvt_pk_bf16_f32 v117, v118, v119
	s_waitcnt lgkmcnt(0)
	v_add_f32_e32 v112, v112, v113
	ds_bpermute_b32 v113, v114, v112
	v_cvt_pk_bf16_f32 v118, v126, v127
	v_cvt_pk_bf16_f32 v119, v160, v115
	global_store_dwordx4 v[122:123], v[116:119], off
	s_and_saveexec_b64 s[20:21], s[2:3]
	s_cbranch_execz .LBB0_1429
	v_lshl_add_u64 v[116:117], v[148:149], 2, s[14:15]
	s_waitcnt lgkmcnt(0)
	v_add_f32_e32 v112, v112, v113
	global_atomic_add_f32 v[116:117], v112, off
.LBB0_1429:
	s_or_b64 exec, exec, s[20:21]
	v_or_b32_e32 v112, 16, v148
	s_waitcnt lgkmcnt(0)
	v_ashrrev_i32_e32 v113, 31, v112
	v_lshlrev_b64 v[116:117], 10, v[112:113]
	v_lshl_add_u64 v[116:117], v[116:117], 0, v[146:147]
	v_lshlrev_b64 v[122:123], 1, v[116:117]
	v_lshl_add_u64 v[116:117], s[10:11], 0, v[122:123]
	s_nop 0
	v_lshl_add_u64 v[124:125], s[12:13], 0, v[122:123]
	v_or_b32_e32 v122, 0x100, v122
	v_lshl_add_u64 v[126:127], s[10:11], 0, v[122:123]
	s_waitcnt vmcnt(14)
	v_lshlrev_b32_e32 v115, 16, v184
	v_and_b32_e32 v116, 0xffff0000, v184
	v_lshlrev_b32_e32 v121, 16, v185
	v_and_b32_e32 v117, 0xffff0000, v185
	v_lshlrev_b32_e32 v149, 16, v186
	v_and_b32_e32 v118, 0xffff0000, v186
	v_lshlrev_b32_e32 v160, 16, v187
	v_and_b32_e32 v119, 0xffff0000, v187
	v_add_f32_e32 v115, v108, v115
	v_add_f32_e32 v116, v109, v116
	v_add_f32_e32 v121, v110, v121
	v_add_f32_e32 v117, v111, v117
	v_add_f32_e32 v149, v104, v149
	v_add_f32_e32 v118, v105, v118
	v_add_f32_e32 v160, v106, v160
	v_add_f32_e32 v119, v107, v119
	v_cvt_pk_bf16_f32 v104, v115, v116
	v_cvt_pk_bf16_f32 v105, v121, v117
	v_cvt_pk_bf16_f32 v106, v149, v118
	v_cvt_pk_bf16_f32 v107, v160, v119
	s_nop 0
	v_mul_f32_e32 v116, v116, v116
	v_mul_f32_e32 v117, v117, v117
	v_mul_f32_e32 v118, v118, v118
	v_mul_f32_e32 v119, v119, v119
	v_fmac_f32_e32 v116, v115, v115
	v_fmac_f32_e32 v117, v121, v121
	v_fmac_f32_e32 v118, v149, v149
	v_fmac_f32_e32 v119, v160, v160
	v_add_f32_e32 v115, v116, v117
	v_add_f32_e32 v116, v118, v119
	v_add_f32_e32 v115, v115, v116
	global_store_dwordx4 v[124:125], v[104:107], off
	s_nop 0
	v_lshlrev_b32_e32 v116, 16, v188
	v_and_b32_e32 v108, 0xffff0000, v188
	v_lshlrev_b32_e32 v117, 16, v189
	v_and_b32_e32 v109, 0xffff0000, v189
	v_lshlrev_b32_e32 v118, 16, v190
	v_and_b32_e32 v110, 0xffff0000, v190
	v_lshlrev_b32_e32 v119, 16, v191
	v_and_b32_e32 v111, 0xffff0000, v191
	v_add_f32_e32 v101, v101, v108
	v_add_f32_e32 v103, v103, v109
	v_add_f32_e32 v109, v97, v110
	v_add_f32_e32 v111, v99, v111
	v_add_f32_e32 v100, v100, v116
	v_add_f32_e32 v102, v102, v117
	v_add_f32_e32 v108, v96, v118
	v_add_f32_e32 v110, v98, v119
	v_mul_f32_e32 v96, v101, v101
	v_mul_f32_e32 v97, v103, v103
	v_mul_f32_e32 v98, v109, v109
	v_mul_f32_e32 v99, v111, v111
	v_fmac_f32_e32 v96, v100, v100
	v_fmac_f32_e32 v97, v102, v102
	v_fmac_f32_e32 v98, v108, v108
	v_fmac_f32_e32 v99, v110, v110
	v_add_f32_e32 v96, v96, v97
	v_add_f32_e32 v97, v98, v99
	v_add_f32_e32 v96, v96, v97
	v_add_f32_e32 v96, v115, v96
	ds_bpermute_b32 v97, v120, v96
	v_cvt_pk_bf16_f32 v98, v100, v101
	v_cvt_pk_bf16_f32 v99, v102, v103
	v_lshl_add_u64 v[102:103], s[12:13], 0, v[122:123]
	v_cvt_pk_bf16_f32 v100, v108, v109
	s_waitcnt lgkmcnt(0)
	v_add_f32_e32 v96, v96, v97
	ds_bpermute_b32 v97, v114, v96
	v_cvt_pk_bf16_f32 v101, v110, v111
	global_store_dwordx4 v[102:103], v[98:101], off
	s_and_saveexec_b64 s[20:21], s[2:3]
	s_cbranch_execz .LBB0_1431
	v_lshl_add_u64 v[98:99], v[112:113], 2, s[14:15]
	s_waitcnt lgkmcnt(0)
	v_add_f32_e32 v96, v96, v97
	global_atomic_add_f32 v[98:99], v96, off
.LBB0_1431:
	s_or_b64 exec, exec, s[20:21]
	v_or_b32_e32 v96, 32, v148
	s_waitcnt lgkmcnt(0)
	v_ashrrev_i32_e32 v97, 31, v96
	v_lshlrev_b64 v[98:99], 10, v[96:97]
	v_lshl_add_u64 v[98:99], v[98:99], 0, v[146:147]
	v_lshlrev_b64 v[102:103], 1, v[98:99]
	v_lshl_add_u64 v[98:99], s[10:11], 0, v[102:103]
	s_nop 0
	v_lshl_add_u64 v[104:105], s[12:13], 0, v[102:103]
	v_or_b32_e32 v102, 0x100, v102
	v_lshl_add_u64 v[106:107], s[10:11], 0, v[102:103]
	s_waitcnt vmcnt(14)
	v_lshlrev_b32_e32 v108, 16, v192
	v_and_b32_e32 v98, 0xffff0000, v192
	v_lshlrev_b32_e32 v109, 16, v193
	v_and_b32_e32 v99, 0xffff0000, v193
	v_lshlrev_b32_e32 v110, 16, v194
	v_and_b32_e32 v100, 0xffff0000, v194
	v_lshlrev_b32_e32 v111, 16, v195
	v_and_b32_e32 v101, 0xffff0000, v195
	v_add_f32_e32 v108, v92, v108
	v_add_f32_e32 v98, v93, v98
	v_add_f32_e32 v109, v94, v109
	v_add_f32_e32 v99, v95, v99
	v_add_f32_e32 v110, v88, v110
	v_add_f32_e32 v100, v89, v100
	v_add_f32_e32 v111, v90, v111
	v_add_f32_e32 v101, v91, v101
	v_cvt_pk_bf16_f32 v88, v108, v98
	v_cvt_pk_bf16_f32 v89, v109, v99
	v_cvt_pk_bf16_f32 v90, v110, v100
	v_cvt_pk_bf16_f32 v91, v111, v101
	s_nop 0
	v_mul_f32_e32 v98, v98, v98
	v_mul_f32_e32 v99, v99, v99
	v_mul_f32_e32 v100, v100, v100
	v_mul_f32_e32 v101, v101, v101
	v_fmac_f32_e32 v98, v108, v108
	v_fmac_f32_e32 v99, v109, v109
	v_fmac_f32_e32 v100, v110, v110
	v_fmac_f32_e32 v101, v111, v111
	v_add_f32_e32 v98, v98, v99
	v_add_f32_e32 v99, v100, v101
	v_add_f32_e32 v98, v98, v99
	global_store_dwordx4 v[104:105], v[88:91], off
	s_nop 0
	v_lshlrev_b32_e32 v99, 16, v196
	v_and_b32_e32 v92, 0xffff0000, v196
	v_lshlrev_b32_e32 v100, 16, v197
	v_and_b32_e32 v93, 0xffff0000, v197
	v_lshlrev_b32_e32 v101, 16, v198
	v_and_b32_e32 v94, 0xffff0000, v198
	v_lshlrev_b32_e32 v106, 16, v199
	v_and_b32_e32 v95, 0xffff0000, v199
	v_add_f32_e32 v85, v85, v92
	v_add_f32_e32 v87, v87, v93
	v_add_f32_e32 v93, v81, v94
	v_add_f32_e32 v95, v83, v95
	v_add_f32_e32 v84, v84, v99
	v_add_f32_e32 v86, v86, v100
	v_add_f32_e32 v92, v80, v101
	v_add_f32_e32 v94, v82, v106
	v_mul_f32_e32 v80, v85, v85
	v_mul_f32_e32 v81, v87, v87
	v_mul_f32_e32 v82, v93, v93
	v_mul_f32_e32 v83, v95, v95
	v_fmac_f32_e32 v80, v84, v84
	v_fmac_f32_e32 v81, v86, v86
	v_fmac_f32_e32 v82, v92, v92
	v_fmac_f32_e32 v83, v94, v94
	v_add_f32_e32 v80, v80, v81
	v_add_f32_e32 v81, v82, v83
	v_add_f32_e32 v80, v80, v81
	v_add_f32_e32 v80, v98, v80
	ds_bpermute_b32 v81, v120, v80
	v_cvt_pk_bf16_f32 v82, v84, v85
	v_cvt_pk_bf16_f32 v83, v86, v87
	v_lshl_add_u64 v[86:87], s[12:13], 0, v[102:103]
	v_cvt_pk_bf16_f32 v84, v92, v93
	s_waitcnt lgkmcnt(0)
	v_add_f32_e32 v80, v80, v81
	ds_bpermute_b32 v81, v114, v80
	v_cvt_pk_bf16_f32 v85, v94, v95
	global_store_dwordx4 v[86:87], v[82:85], off
	s_and_saveexec_b64 s[20:21], s[2:3]
	s_cbranch_execz .LBB0_1433
	v_lshl_add_u64 v[82:83], v[96:97], 2, s[14:15]
	s_waitcnt lgkmcnt(0)
	v_add_f32_e32 v80, v80, v81
	global_atomic_add_f32 v[82:83], v80, off
.LBB0_1433:
	s_or_b64 exec, exec, s[20:21]
	v_or_b32_e32 v80, 48, v148
	s_waitcnt lgkmcnt(0)
	v_ashrrev_i32_e32 v81, 31, v80
	v_lshlrev_b64 v[82:83], 10, v[80:81]
	v_lshl_add_u64 v[82:83], v[82:83], 0, v[146:147]
	v_lshlrev_b64 v[86:87], 1, v[82:83]
	v_lshl_add_u64 v[82:83], s[10:11], 0, v[86:87]
	s_nop 0
	v_lshl_add_u64 v[88:89], s[12:13], 0, v[86:87]
	v_or_b32_e32 v86, 0x100, v86
	v_lshl_add_u64 v[90:91], s[10:11], 0, v[86:87]
	s_waitcnt vmcnt(14)
	v_lshlrev_b32_e32 v92, 16, v200
	v_and_b32_e32 v82, 0xffff0000, v200
	v_lshlrev_b32_e32 v93, 16, v201
	v_and_b32_e32 v83, 0xffff0000, v201
	v_lshlrev_b32_e32 v94, 16, v202
	v_and_b32_e32 v84, 0xffff0000, v202
	v_lshlrev_b32_e32 v95, 16, v203
	v_and_b32_e32 v85, 0xffff0000, v203
	v_add_f32_e32 v92, v76, v92
	v_add_f32_e32 v82, v77, v82
	v_add_f32_e32 v93, v78, v93
	v_add_f32_e32 v83, v79, v83
	v_add_f32_e32 v94, v72, v94
	v_add_f32_e32 v84, v73, v84
	v_add_f32_e32 v95, v74, v95
	v_add_f32_e32 v85, v75, v85
	v_cvt_pk_bf16_f32 v72, v92, v82
	v_cvt_pk_bf16_f32 v73, v93, v83
	v_cvt_pk_bf16_f32 v74, v94, v84
	v_cvt_pk_bf16_f32 v75, v95, v85
	s_nop 0
	v_mul_f32_e32 v82, v82, v82
	v_mul_f32_e32 v83, v83, v83
	v_mul_f32_e32 v84, v84, v84
	v_mul_f32_e32 v85, v85, v85
	v_fmac_f32_e32 v82, v92, v92
	v_fmac_f32_e32 v83, v93, v93
	v_fmac_f32_e32 v84, v94, v94
	v_fmac_f32_e32 v85, v95, v95
	v_add_f32_e32 v82, v82, v83
	v_add_f32_e32 v83, v84, v85
	v_add_f32_e32 v82, v82, v83
	global_store_dwordx4 v[88:89], v[72:75], off
	s_nop 0
	v_lshlrev_b32_e32 v83, 16, v204
	v_and_b32_e32 v76, 0xffff0000, v204
	v_lshlrev_b32_e32 v84, 16, v205
	v_and_b32_e32 v77, 0xffff0000, v205
	v_lshlrev_b32_e32 v85, 16, v206
	v_and_b32_e32 v78, 0xffff0000, v206
	v_lshlrev_b32_e32 v90, 16, v207
	v_and_b32_e32 v79, 0xffff0000, v207
	v_add_f32_e32 v69, v69, v76
	v_add_f32_e32 v71, v71, v77
	v_add_f32_e32 v77, v65, v78
	v_add_f32_e32 v79, v67, v79
	v_add_f32_e32 v68, v68, v83
	v_add_f32_e32 v70, v70, v84
	v_add_f32_e32 v76, v64, v85
	v_add_f32_e32 v78, v66, v90
	v_mul_f32_e32 v64, v69, v69
	v_mul_f32_e32 v65, v71, v71
	v_mul_f32_e32 v66, v77, v77
	v_mul_f32_e32 v67, v79, v79
	v_fmac_f32_e32 v64, v68, v68
	v_fmac_f32_e32 v65, v70, v70
	v_fmac_f32_e32 v66, v76, v76
	v_fmac_f32_e32 v67, v78, v78
	v_add_f32_e32 v64, v64, v65
	v_add_f32_e32 v65, v66, v67
	v_add_f32_e32 v64, v64, v65
	v_add_f32_e32 v64, v82, v64
	ds_bpermute_b32 v65, v120, v64
	v_cvt_pk_bf16_f32 v66, v68, v69
	v_cvt_pk_bf16_f32 v67, v70, v71
	v_lshl_add_u64 v[70:71], s[12:13], 0, v[86:87]
	v_cvt_pk_bf16_f32 v68, v76, v77
	s_waitcnt lgkmcnt(0)
	v_add_f32_e32 v64, v64, v65
	ds_bpermute_b32 v65, v114, v64
	v_cvt_pk_bf16_f32 v69, v78, v79
	global_store_dwordx4 v[70:71], v[66:69], off
	s_and_saveexec_b64 s[20:21], s[2:3]
	s_cbranch_execz .LBB0_1435
	v_lshl_add_u64 v[66:67], v[80:81], 2, s[14:15]
	s_waitcnt lgkmcnt(0)
	v_add_f32_e32 v64, v64, v65
	global_atomic_add_f32 v[66:67], v64, off
.LBB0_1435:
	s_or_b64 exec, exec, s[20:21]
	v_add_u32_e32 v64, 0x80, v148
	s_waitcnt lgkmcnt(0)
	v_ashrrev_i32_e32 v65, 31, v64
	v_lshlrev_b64 v[66:67], 10, v[64:65]
	v_lshl_add_u64 v[66:67], v[66:67], 0, v[146:147]
	v_lshlrev_b64 v[70:71], 1, v[66:67]
	v_lshl_add_u64 v[66:67], s[10:11], 0, v[70:71]
	s_nop 0
	v_lshl_add_u64 v[72:73], s[12:13], 0, v[70:71]
	v_or_b32_e32 v70, 0x100, v70
	v_lshl_add_u64 v[74:75], s[10:11], 0, v[70:71]
	s_waitcnt vmcnt(14)
	v_lshlrev_b32_e32 v76, 16, v208
	v_and_b32_e32 v66, 0xffff0000, v208
	v_lshlrev_b32_e32 v77, 16, v209
	v_and_b32_e32 v67, 0xffff0000, v209
	v_lshlrev_b32_e32 v78, 16, v210
	v_and_b32_e32 v68, 0xffff0000, v210
	v_lshlrev_b32_e32 v79, 16, v211
	v_and_b32_e32 v69, 0xffff0000, v211
	v_add_f32_e32 v76, v60, v76
	v_add_f32_e32 v66, v61, v66
	v_add_f32_e32 v77, v62, v77
	v_add_f32_e32 v67, v63, v67
	v_add_f32_e32 v78, v56, v78
	v_add_f32_e32 v68, v57, v68
	v_add_f32_e32 v79, v58, v79
	v_add_f32_e32 v69, v59, v69
	v_cvt_pk_bf16_f32 v56, v76, v66
	v_cvt_pk_bf16_f32 v57, v77, v67
	v_cvt_pk_bf16_f32 v58, v78, v68
	v_cvt_pk_bf16_f32 v59, v79, v69
	s_nop 0
	v_mul_f32_e32 v66, v66, v66
	v_mul_f32_e32 v67, v67, v67
	v_mul_f32_e32 v68, v68, v68
	v_mul_f32_e32 v69, v69, v69
	v_fmac_f32_e32 v66, v76, v76
	v_fmac_f32_e32 v67, v77, v77
	v_fmac_f32_e32 v68, v78, v78
	v_fmac_f32_e32 v69, v79, v79
	v_add_f32_e32 v66, v66, v67
	v_add_f32_e32 v67, v68, v69
	v_add_f32_e32 v66, v66, v67
	global_store_dwordx4 v[72:73], v[56:59], off
	s_nop 0
	v_lshlrev_b32_e32 v67, 16, v212
	v_and_b32_e32 v60, 0xffff0000, v212
	v_lshlrev_b32_e32 v68, 16, v213
	v_and_b32_e32 v61, 0xffff0000, v213
	v_lshlrev_b32_e32 v69, 16, v214
	v_and_b32_e32 v62, 0xffff0000, v214
	v_lshlrev_b32_e32 v74, 16, v215
	v_and_b32_e32 v63, 0xffff0000, v215
	v_add_f32_e32 v53, v53, v60
	v_add_f32_e32 v55, v55, v61
	v_add_f32_e32 v61, v49, v62
	v_add_f32_e32 v63, v51, v63
	v_add_f32_e32 v52, v52, v67
	v_add_f32_e32 v54, v54, v68
	v_add_f32_e32 v60, v48, v69
	v_add_f32_e32 v62, v50, v74
	v_mul_f32_e32 v48, v53, v53
	v_mul_f32_e32 v49, v55, v55
	v_mul_f32_e32 v50, v61, v61
	v_mul_f32_e32 v51, v63, v63
	v_fmac_f32_e32 v48, v52, v52
	v_fmac_f32_e32 v49, v54, v54
	v_fmac_f32_e32 v50, v60, v60
	v_fmac_f32_e32 v51, v62, v62
	v_add_f32_e32 v48, v48, v49
	v_add_f32_e32 v49, v50, v51
	v_add_f32_e32 v48, v48, v49
	v_add_f32_e32 v48, v66, v48
	ds_bpermute_b32 v49, v120, v48
	v_cvt_pk_bf16_f32 v50, v52, v53
	v_cvt_pk_bf16_f32 v51, v54, v55
	v_lshl_add_u64 v[54:55], s[12:13], 0, v[70:71]
	v_cvt_pk_bf16_f32 v52, v60, v61
	s_waitcnt lgkmcnt(0)
	v_add_f32_e32 v48, v48, v49
	ds_bpermute_b32 v49, v114, v48
	v_cvt_pk_bf16_f32 v53, v62, v63
	global_store_dwordx4 v[54:55], v[50:53], off
	s_and_saveexec_b64 s[20:21], s[2:3]
	s_cbranch_execz .LBB0_1437
	v_lshl_add_u64 v[50:51], v[64:65], 2, s[14:15]
	s_waitcnt lgkmcnt(0)
	v_add_f32_e32 v48, v48, v49
	global_atomic_add_f32 v[50:51], v48, off
.LBB0_1437:
	s_or_b64 exec, exec, s[20:21]
	v_add_u32_e32 v48, 0x90, v148
	s_waitcnt lgkmcnt(0)
	v_ashrrev_i32_e32 v49, 31, v48
	v_lshlrev_b64 v[50:51], 10, v[48:49]
	v_lshl_add_u64 v[50:51], v[50:51], 0, v[146:147]
	v_lshlrev_b64 v[54:55], 1, v[50:51]
	v_lshl_add_u64 v[50:51], s[10:11], 0, v[54:55]
	s_nop 0
	v_lshl_add_u64 v[56:57], s[12:13], 0, v[54:55]
	v_or_b32_e32 v54, 0x100, v54
	v_lshl_add_u64 v[58:59], s[10:11], 0, v[54:55]
	s_waitcnt vmcnt(14)
	v_lshlrev_b32_e32 v60, 16, v216
	v_and_b32_e32 v50, 0xffff0000, v216
	v_lshlrev_b32_e32 v61, 16, v217
	v_and_b32_e32 v51, 0xffff0000, v217
	v_lshlrev_b32_e32 v62, 16, v218
	v_and_b32_e32 v52, 0xffff0000, v218
	v_lshlrev_b32_e32 v63, 16, v219
	v_and_b32_e32 v53, 0xffff0000, v219
	v_add_f32_e32 v60, v44, v60
	v_add_f32_e32 v50, v45, v50
	v_add_f32_e32 v61, v46, v61
	v_add_f32_e32 v51, v47, v51
	v_add_f32_e32 v62, v40, v62
	v_add_f32_e32 v52, v41, v52
	v_add_f32_e32 v63, v42, v63
	v_add_f32_e32 v53, v43, v53
	v_cvt_pk_bf16_f32 v40, v60, v50
	v_cvt_pk_bf16_f32 v41, v61, v51
	v_cvt_pk_bf16_f32 v42, v62, v52
	v_cvt_pk_bf16_f32 v43, v63, v53
	s_nop 0
	v_mul_f32_e32 v50, v50, v50
	v_mul_f32_e32 v51, v51, v51
	v_mul_f32_e32 v52, v52, v52
	v_mul_f32_e32 v53, v53, v53
	v_fmac_f32_e32 v50, v60, v60
	v_fmac_f32_e32 v51, v61, v61
	v_fmac_f32_e32 v52, v62, v62
	v_fmac_f32_e32 v53, v63, v63
	v_add_f32_e32 v50, v50, v51
	v_add_f32_e32 v51, v52, v53
	v_add_f32_e32 v50, v50, v51
	global_store_dwordx4 v[56:57], v[40:43], off
	s_nop 0
	v_lshlrev_b32_e32 v51, 16, v220
	v_and_b32_e32 v44, 0xffff0000, v220
	v_lshlrev_b32_e32 v52, 16, v221
	v_and_b32_e32 v45, 0xffff0000, v221
	v_lshlrev_b32_e32 v53, 16, v222
	v_and_b32_e32 v46, 0xffff0000, v222
	v_lshlrev_b32_e32 v58, 16, v223
	v_and_b32_e32 v47, 0xffff0000, v223
	v_add_f32_e32 v37, v37, v44
	v_add_f32_e32 v39, v39, v45
	v_add_f32_e32 v45, v33, v46
	v_add_f32_e32 v47, v35, v47
	v_add_f32_e32 v36, v36, v51
	v_add_f32_e32 v38, v38, v52
	v_add_f32_e32 v44, v32, v53
	v_add_f32_e32 v46, v34, v58
	v_mul_f32_e32 v32, v37, v37
	v_mul_f32_e32 v33, v39, v39
	v_mul_f32_e32 v34, v45, v45
	v_mul_f32_e32 v35, v47, v47
	v_fmac_f32_e32 v32, v36, v36
	v_fmac_f32_e32 v33, v38, v38
	v_fmac_f32_e32 v34, v44, v44
	v_fmac_f32_e32 v35, v46, v46
	v_add_f32_e32 v32, v32, v33
	v_add_f32_e32 v33, v34, v35
	v_add_f32_e32 v32, v32, v33
	v_add_f32_e32 v32, v50, v32
	ds_bpermute_b32 v33, v120, v32
	v_cvt_pk_bf16_f32 v34, v36, v37
	v_cvt_pk_bf16_f32 v35, v38, v39
	v_lshl_add_u64 v[38:39], s[12:13], 0, v[54:55]
	v_cvt_pk_bf16_f32 v36, v44, v45
	s_waitcnt lgkmcnt(0)
	v_add_f32_e32 v32, v32, v33
	ds_bpermute_b32 v33, v114, v32
	v_cvt_pk_bf16_f32 v37, v46, v47
	global_store_dwordx4 v[38:39], v[34:37], off
	s_and_saveexec_b64 s[20:21], s[2:3]
	s_cbranch_execz .LBB0_1439
	v_lshl_add_u64 v[34:35], v[48:49], 2, s[14:15]
	s_waitcnt lgkmcnt(0)
	v_add_f32_e32 v32, v32, v33
	global_atomic_add_f32 v[34:35], v32, off
.LBB0_1439:
	s_or_b64 exec, exec, s[20:21]
	v_add_u32_e32 v32, 0xa0, v148
	s_waitcnt lgkmcnt(0)
	v_ashrrev_i32_e32 v33, 31, v32
	v_lshlrev_b64 v[34:35], 10, v[32:33]
	v_lshl_add_u64 v[34:35], v[34:35], 0, v[146:147]
	v_lshlrev_b64 v[38:39], 1, v[34:35]
	v_lshl_add_u64 v[34:35], s[10:11], 0, v[38:39]
	s_nop 0
	v_lshl_add_u64 v[40:41], s[12:13], 0, v[38:39]
	v_or_b32_e32 v38, 0x100, v38
	v_lshl_add_u64 v[42:43], s[10:11], 0, v[38:39]
	s_waitcnt vmcnt(14)
	v_lshlrev_b32_e32 v44, 16, v224
	v_and_b32_e32 v34, 0xffff0000, v224
	v_lshlrev_b32_e32 v45, 16, v225
	v_and_b32_e32 v35, 0xffff0000, v225
	v_lshlrev_b32_e32 v46, 16, v226
	v_and_b32_e32 v36, 0xffff0000, v226
	v_lshlrev_b32_e32 v47, 16, v227
	v_and_b32_e32 v37, 0xffff0000, v227
	v_add_f32_e32 v44, v28, v44
	v_add_f32_e32 v34, v29, v34
	v_add_f32_e32 v45, v30, v45
	v_add_f32_e32 v35, v31, v35
	v_add_f32_e32 v46, v24, v46
	v_add_f32_e32 v36, v25, v36
	v_add_f32_e32 v47, v26, v47
	v_add_f32_e32 v37, v27, v37
	v_cvt_pk_bf16_f32 v24, v44, v34
	v_cvt_pk_bf16_f32 v25, v45, v35
	v_cvt_pk_bf16_f32 v26, v46, v36
	v_cvt_pk_bf16_f32 v27, v47, v37
	s_nop 0
	v_mul_f32_e32 v34, v34, v34
	v_mul_f32_e32 v35, v35, v35
	v_mul_f32_e32 v36, v36, v36
	v_mul_f32_e32 v37, v37, v37
	v_fmac_f32_e32 v34, v44, v44
	v_fmac_f32_e32 v35, v45, v45
	v_fmac_f32_e32 v36, v46, v46
	v_fmac_f32_e32 v37, v47, v47
	v_add_f32_e32 v34, v34, v35
	v_add_f32_e32 v35, v36, v37
	v_add_f32_e32 v34, v34, v35
	global_store_dwordx4 v[40:41], v[24:27], off
	s_nop 0
	v_lshlrev_b32_e32 v35, 16, v228
	v_and_b32_e32 v28, 0xffff0000, v228
	v_lshlrev_b32_e32 v36, 16, v229
	v_and_b32_e32 v29, 0xffff0000, v229
	v_lshlrev_b32_e32 v37, 16, v230
	v_and_b32_e32 v30, 0xffff0000, v230
	v_lshlrev_b32_e32 v42, 16, v231
	v_and_b32_e32 v31, 0xffff0000, v231
	v_add_f32_e32 v21, v21, v28
	v_add_f32_e32 v23, v23, v29
	v_add_f32_e32 v29, v17, v30
	v_add_f32_e32 v31, v19, v31
	v_add_f32_e32 v20, v20, v35
	v_add_f32_e32 v22, v22, v36
	v_add_f32_e32 v28, v16, v37
	v_add_f32_e32 v30, v18, v42
	v_mul_f32_e32 v16, v21, v21
	v_mul_f32_e32 v17, v23, v23
	v_mul_f32_e32 v18, v29, v29
	v_mul_f32_e32 v19, v31, v31
	v_fmac_f32_e32 v16, v20, v20
	v_fmac_f32_e32 v17, v22, v22
	v_fmac_f32_e32 v18, v28, v28
	v_fmac_f32_e32 v19, v30, v30
	v_add_f32_e32 v16, v16, v17
	v_add_f32_e32 v17, v18, v19
	v_add_f32_e32 v16, v16, v17
	v_add_f32_e32 v16, v34, v16
	ds_bpermute_b32 v17, v120, v16
	v_cvt_pk_bf16_f32 v18, v20, v21
	v_cvt_pk_bf16_f32 v19, v22, v23
	v_lshl_add_u64 v[22:23], s[12:13], 0, v[38:39]
	v_cvt_pk_bf16_f32 v20, v28, v29
	s_waitcnt lgkmcnt(0)
	v_add_f32_e32 v16, v16, v17
	ds_bpermute_b32 v17, v114, v16
	v_cvt_pk_bf16_f32 v21, v30, v31
	global_store_dwordx4 v[22:23], v[18:21], off
	s_and_saveexec_b64 s[20:21], s[2:3]
	s_cbranch_execz .LBB0_1441
	v_lshl_add_u64 v[18:19], v[32:33], 2, s[14:15]
	s_waitcnt lgkmcnt(0)
	v_add_f32_e32 v16, v16, v17
	global_atomic_add_f32 v[18:19], v16, off
.LBB0_1441:
	s_or_b64 exec, exec, s[20:21]
	v_add_u32_e32 v16, 0xb0, v148
	s_waitcnt lgkmcnt(0)
	v_ashrrev_i32_e32 v17, 31, v16
	v_lshlrev_b64 v[18:19], 10, v[16:17]
	v_lshl_add_u64 v[18:19], v[18:19], 0, v[146:147]
	v_lshlrev_b64 v[22:23], 1, v[18:19]
	v_lshl_add_u64 v[18:19], s[10:11], 0, v[22:23]
	s_nop 0
	v_lshl_add_u64 v[24:25], s[12:13], 0, v[22:23]
	v_or_b32_e32 v22, 0x100, v22
	v_lshl_add_u64 v[26:27], s[10:11], 0, v[22:23]
	s_waitcnt vmcnt(14)
	v_lshlrev_b32_e32 v28, 16, v232
	v_and_b32_e32 v18, 0xffff0000, v232
	v_lshlrev_b32_e32 v29, 16, v233
	v_and_b32_e32 v19, 0xffff0000, v233
	v_lshlrev_b32_e32 v30, 16, v234
	v_and_b32_e32 v20, 0xffff0000, v234
	v_lshlrev_b32_e32 v31, 16, v235
	v_and_b32_e32 v21, 0xffff0000, v235
	v_add_f32_e32 v28, v12, v28
	v_add_f32_e32 v18, v13, v18
	v_add_f32_e32 v29, v14, v29
	v_add_f32_e32 v19, v15, v19
	v_add_f32_e32 v30, v8, v30
	v_add_f32_e32 v20, v9, v20
	v_add_f32_e32 v31, v10, v31
	v_add_f32_e32 v21, v11, v21
	v_cvt_pk_bf16_f32 v8, v28, v18
	v_cvt_pk_bf16_f32 v9, v29, v19
	v_cvt_pk_bf16_f32 v10, v30, v20
	v_cvt_pk_bf16_f32 v11, v31, v21
	s_nop 0
	v_mul_f32_e32 v18, v18, v18
	v_mul_f32_e32 v19, v19, v19
	v_mul_f32_e32 v20, v20, v20
	v_mul_f32_e32 v21, v21, v21
	v_fmac_f32_e32 v18, v28, v28
	v_fmac_f32_e32 v19, v29, v29
	v_fmac_f32_e32 v20, v30, v30
	v_fmac_f32_e32 v21, v31, v31
	v_add_f32_e32 v18, v18, v19
	v_add_f32_e32 v19, v20, v21
	v_add_f32_e32 v18, v18, v19
	global_store_dwordx4 v[24:25], v[8:11], off
	s_nop 0
	v_lshlrev_b32_e32 v19, 16, v236
	v_and_b32_e32 v12, 0xffff0000, v236
	v_lshlrev_b32_e32 v20, 16, v237
	v_and_b32_e32 v13, 0xffff0000, v237
	v_lshlrev_b32_e32 v21, 16, v238
	v_and_b32_e32 v14, 0xffff0000, v238
	v_lshlrev_b32_e32 v26, 16, v239
	v_and_b32_e32 v15, 0xffff0000, v239
	v_add_f32_e32 v5, v5, v12
	v_add_f32_e32 v7, v7, v13
	v_add_f32_e32 v13, v1, v14
	v_add_f32_e32 v15, v3, v15
	v_add_f32_e32 v4, v4, v19
	v_add_f32_e32 v6, v6, v20
	v_add_f32_e32 v12, v0, v21
	v_add_f32_e32 v14, v2, v26
	v_mul_f32_e32 v0, v5, v5
	v_mul_f32_e32 v1, v7, v7
	v_mul_f32_e32 v2, v13, v13
	v_mul_f32_e32 v3, v15, v15
	v_fmac_f32_e32 v0, v4, v4
	v_fmac_f32_e32 v1, v6, v6
	v_fmac_f32_e32 v2, v12, v12
	v_fmac_f32_e32 v3, v14, v14
	v_add_f32_e32 v0, v0, v1
	v_add_f32_e32 v1, v2, v3
	v_add_f32_e32 v0, v0, v1
	v_add_f32_e32 v0, v18, v0
	ds_bpermute_b32 v1, v120, v0
	v_cvt_pk_bf16_f32 v2, v4, v5
	v_cvt_pk_bf16_f32 v3, v6, v7
	v_lshl_add_u64 v[6:7], s[12:13], 0, v[22:23]
	v_cvt_pk_bf16_f32 v4, v12, v13
	s_waitcnt lgkmcnt(0)
	v_add_f32_e32 v0, v0, v1
	ds_bpermute_b32 v1, v114, v0
	v_cvt_pk_bf16_f32 v5, v14, v15
	global_store_dwordx4 v[6:7], v[2:5], off
	s_and_saveexec_b64 s[20:21], s[2:3]
	s_cbranch_execz .LBB0_1443
	v_lshl_add_u64 v[2:3], v[16:17], 2, s[14:15]
	s_waitcnt lgkmcnt(0)
	v_add_f32_e32 v0, v0, v1
	global_atomic_add_f32 v[2:3], v0, off

	.amdhsa_kernel _Z14fwd_megakernel6Params
		.amdhsa_group_segment_fixed_size 0
		.amdhsa_private_segment_fixed_size 0
		.amdhsa_kernarg_size 512
		.amdhsa_user_sgpr_count 2
		.amdhsa_user_sgpr_dispatch_ptr 0
		.amdhsa_user_sgpr_queue_ptr 0
		.amdhsa_user_sgpr_kernarg_segment_ptr 1
		.amdhsa_user_sgpr_dispatch_id 0
		.amdhsa_user_sgpr_kernarg_preload_length 0
		.amdhsa_user_sgpr_kernarg_preload_offset 0
		.amdhsa_user_sgpr_private_segment_size 0
		.amdhsa_uses_dynamic_stack 0
		.amdhsa_enable_private_segment 0
		.amdhsa_system_sgpr_workgroup_id_x 1
		.amdhsa_system_sgpr_workgroup_id_y 0
		.amdhsa_system_sgpr_workgroup_id_z 0
		.amdhsa_system_sgpr_workgroup_info 0
		.amdhsa_system_vgpr_workitem_id 2
		.amdhsa_next_free_vgpr 256
		.amdhsa_next_free_sgpr 100
		.amdhsa_accum_offset 256
		.amdhsa_reserve_vcc 1
		.amdhsa_float_round_mode_32 0
		.amdhsa_float_round_mode_16_64 0
		.amdhsa_float_denorm_mode_32 3
		.amdhsa_float_denorm_mode_16_64 3
		.amdhsa_dx10_clamp 1
		.amdhsa_ieee_mode 1
		.amdhsa_fp16_overflow 0
		.amdhsa_tg_split 0
		.amdhsa_exception_fp_ieee_invalid_op 0
		.amdhsa_exception_fp_denorm_src 0
		.amdhsa_exception_fp_ieee_div_zero 0
		.amdhsa_exception_fp_ieee_overflow 0
		.amdhsa_exception_fp_ieee_underflow 0
		.amdhsa_exception_fp_ieee_inexact 0
		.amdhsa_exception_int_div_zero 0
	.end_amdhsa_kernel

amdhsa.kernels:
  - .agpr_count:     0
    .args:
      - .offset:         0
        .size:           256
        .value_kind:     by_value
      - .offset:         256
        .size:           4
        .value_kind:     hidden_block_count_x
      - .offset:         260
        .size:           4
        .value_kind:     hidden_block_count_y
      - .offset:         264
        .size:           4
        .value_kind:     hidden_block_count_z
      - .offset:         268
        .size:           2
        .value_kind:     hidden_group_size_x
      - .offset:         270
        .size:           2
        .value_kind:     hidden_group_size_y
      - .offset:         272
        .size:           2
        .value_kind:     hidden_group_size_z
      - .offset:         274
        .size:           2
        .value_kind:     hidden_remainder_x
      - .offset:         276
        .size:           2
        .value_kind:     hidden_remainder_y
      - .offset:         278
        .size:           2
        .value_kind:     hidden_remainder_z
      - .offset:         296
        .size:           8
        .value_kind:     hidden_global_offset_x
      - .offset:         304
        .size:           8
        .value_kind:     hidden_global_offset_y
      - .offset:         312
        .size:           8
        .value_kind:     hidden_global_offset_z
      - .offset:         320
        .size:           2
        .value_kind:     hidden_grid_dims
      - .offset:         344
        .size:           8
        .value_kind:     hidden_multigrid_sync_arg
      - .offset:         376
        .size:           4
        .value_kind:     hidden_dynamic_lds_size
    .group_segment_fixed_size: 0
    .kernarg_segment_align: 8
    .kernarg_segment_size: 512
    .language:       OpenCL C
    .language_version:
      - 2
      - 0
    .max_flat_workgroup_size: 512
    .name:           _Z14fwd_megakernel6Params
    .private_segment_fixed_size: 0
    .sgpr_count:     106
    .sgpr_spill_count: 44
    .symbol:         _Z14fwd_megakernel6Params.kd
    .uniform_work_group_size: 1
    .uses_dynamic_stack: false
    .vgpr_count:     256
    .vgpr_spill_count: 0
    .wavefront_size: 64
